# code placement: every GEMM MFMA run start padded to an 8-byte boundary with s_nop 0; diff main loop and gate loop2 heads pinned to 64B (stacked on v17)
# baseline (speedup 1.0000x reference)
; #define PG8_STAGE(bufoff, gbase, voff) do { _Pragma("unroll") for (int _i = 0; _i < 2; ++_i) \
;         __builtin_amdgcn_global_load_lds((const unsigned*)((const char*)(gbase) + (voff)[_i]), (LAS unsigned*)(lds + (bufoff) + ldsw + _i * 8192), 16, 0, 0); } while (0)
; #define PG8_LDA(dst, b, h) do { _Pragma("unroll") for (int m = 0; m < 4; ++m) _Pragma("unroll") for (int k = 0; k < 2; ++k) dst[m][k] = *(const LAS bf16x8*)(lds + PG8_SA(b, h) + aoff + m * 2048 + k * 1024); } while (0)
; #define PG8_LDB(dst, b, h) do { _Pragma("unroll") for (int n = 0; n < 2; ++n) _Pragma("unroll") for (int k = 0; k < 2; ++k) dst[n][k] = *(const LAS bf16x8*)(lds + PG8_SB(b, h) + boff + n * 2048 + k * 1024); } while (0)
; #define PG8_MMA(ai, bj, At, Bt) do { __builtin_amdgcn_s_setprio(1); _Pragma("unroll") for (int m = 0; m < 4; ++m) _Pragma("unroll") for (int n = 0; n < 2; ++n) _Pragma("unroll") for (int k = 0; k < 2; ++k) \
;         acc[ai][bj][m][n] = __builtin_amdgcn_mfma_f32_16x16x32_bf16(Bt[n][k], At[m][k], acc[ai][bj][m][n], 0, 0, 0); __builtin_amdgcn_s_setprio(0); } while (0)
; #define PG8_WAIT_L(n) asm volatile("s_waitcnt lgkmcnt(" #n ")" ::: "memory")
; template <class Epi>
; DI void gemm_phase(int wv, LAS unsigned char* lds, const GemmD g, const Epi& E) {
;     ...
;         const bool has_next = S.next(ui + 1, nxt);
;         const char* nA = has_next ? (const char*)g.A + (size_t)nxt.pm * 256 * g.lda * 2 : cA; const char* nB = has_next ? (const char*)g.Bt + PG8_BROW(nxt.pn) * (size_t)g.ldb * 2 : cB;
;         for (int t = 0; t < nt; t += 2) {
;             const bool last = (t == nt - 2);
;             const char* a1 = cA + (size_t)(t + 1) * kstep;
;             const char* a2 = last ? nA : cA + (size_t)(t + 2) * kstep; const char* b2 = last ? nB : cB + (size_t)(t + 2) * kstep;
;             const char* a3 = a2 + kstep; const char* b3 = b2 + kstep;
;             PG8_LDB(B0, 0, 0); PG8_SCHED; PG8_LDA(At, 0, 0); PG8_STAGE(PG8_SA(1, 1), a1 + hstepA, voffA);
;             PG8_WAIT_L(8); PG8_BAR; PG8_WAIT_L(0); PG8_MMA(0, 0, At, B0); PG8_BAR; PG8_SCHED;
;             PG8_LDB(B1, 0, 1); PG8_STAGE(PG8_SB(0, 0), b2, voffB);
;             PG8_BAR; PG8_WAIT_L(0); PG8_MMA(0, 1, At, B1); PG8_BAR;
;             PG8_LDA(At, 0, 1); PG8_STAGE(PG8_SA(0, 0), a2, voffA);
;             PG8_BAR; PG8_WAIT_L(0); PG8_MMA(1, 0, At, B0); PG8_BAR; PG8_SCHED;
.LBB0_98:
	s_ashr_i32 s17, s16, 31
	s_lshl_b64 s[20:21], s[16:17], 19
	s_add_u32 s20, s6, s20
	s_addc_u32 s21, s7, s21
	s_and_b64 s[4:5], s[4:5], exec
	s_cselect_b32 s17, s21, s25
	s_cselect_b32 vcc_lo, s20, s24
	s_add_u32 s4, s24, 0x40080
	s_addc_u32 s5, s25, 0
	s_add_u32 vcc_hi, s22, 0x100
	s_addc_u32 s75, s23, 0
	s_mov_b32 s95, -2
	s_add_u32 s22, s4, 0xfffc0080
	s_addc_u32 s23, s5, -1
	s_add_i32 s3, 0, 0x10000
	v_add_u32_e32 v156, s3, v141
	ds_read_b128 v[144:147], v156
	ds_read_b128 v[148:151], v156 offset:1024
	ds_read_b128 v[152:155], v156 offset:2048
	ds_read_b128 v[156:159], v156 offset:3072
	s_cmp_eq_u32 s95, 12
	s_cselect_b32 s23, s17, s23
	s_cselect_b32 s22, vcc_lo, s22
	s_cselect_b32 s25, s19, s75
	s_cselect_b32 s24, s18, vcc_hi
	v_lshl_add_u64 v[164:165], s[4:5], 0, v[136:137]
	s_add_i32 m0, s15, 0xc000
	ds_read_b128 v[160:163], v143
	ds_read_b128 v[176:179], v143 offset:1024
	ds_read_b128 v[180:183], v143 offset:2048
	ds_read_b128 v[184:187], v143 offset:3072
	ds_read_b128 v[188:191], v143 offset:4096
	ds_read_b128 v[192:195], v143 offset:5120
	ds_read_b128 v[196:199], v143 offset:6144
	ds_read_b128 v[200:203], v143 offset:7168
	global_load_lds_dwordx4 v[164:165], off
	v_lshl_add_u64 v[164:165], s[4:5], 0, v[138:139]
	s_add_i32 m0, s15, 0xe000
	s_nop 0
	global_load_lds_dwordx4 v[164:165], off
	s_waitcnt lgkmcnt(8)
	s_barrier
	s_waitcnt lgkmcnt(0)
	s_waitcnt lgkmcnt(0)
	s_nop 0
	v_mfma_f32_16x16x32_bf16 v[126:129], v[144:147], v[160:163], 0
	v_mfma_f32_16x16x32_bf16 v[122:125], v[152:155], v[160:163], 0
	v_mfma_f32_16x16x32_bf16 v[118:121], v[144:147], v[180:183], 0
	v_mfma_f32_16x16x32_bf16 v[114:117], v[152:155], v[180:183], 0
	v_mfma_f32_16x16x32_bf16 v[102:105], v[144:147], v[188:191], 0
	v_mfma_f32_16x16x32_bf16 v[98:101], v[152:155], v[188:191], 0
	v_mfma_f32_16x16x32_bf16 v[86:89], v[144:147], v[196:199], 0
	v_mfma_f32_16x16x32_bf16 v[82:85], v[152:155], v[196:199], 0
	v_mfma_f32_16x16x32_bf16 v[126:129], v[148:151], v[176:179], v[126:129]
	v_mfma_f32_16x16x32_bf16 v[122:125], v[156:159], v[176:179], v[122:125]
	v_mfma_f32_16x16x32_bf16 v[118:121], v[148:151], v[184:187], v[118:121]
	v_mfma_f32_16x16x32_bf16 v[114:117], v[156:159], v[184:187], v[114:117]
	v_mfma_f32_16x16x32_bf16 v[102:105], v[148:151], v[192:195], v[102:105]
	v_mfma_f32_16x16x32_bf16 v[98:101], v[156:159], v[192:195], v[98:101]
	v_mfma_f32_16x16x32_bf16 v[86:89], v[148:151], v[200:203], v[86:89]
	v_mfma_f32_16x16x32_bf16 v[82:85], v[156:159], v[200:203], v[82:85]
	s_barrier
	s_add_i32 s2, 0, 0x14000
	v_add_u32_e32 v164, s2, v141
	s_add_i32 s3, s3, s37
	ds_read_b128 v[204:207], v164
	ds_read_b128 v[208:211], v164 offset:1024
	ds_read_b128 v[212:215], v164 offset:2048
	ds_read_b128 v[216:219], v164 offset:3072
	v_lshl_add_u64 v[164:165], s[24:25], 0, v[0:1]
	s_mov_b32 m0, s3
	v_lshl_add_u64 v[168:169], s[24:25], 0, v[130:131]
	global_load_lds_dwordx4 v[164:165], off
	s_add_i32 m0, s3, 0x2000
	s_nop 0
	global_load_lds_dwordx4 v[168:169], off
	s_barrier
	s_waitcnt lgkmcnt(0)
	s_waitcnt lgkmcnt(0)
	v_mfma_f32_16x16x32_bf16 v[110:113], v[204:207], v[160:163], 0
	v_mfma_f32_16x16x32_bf16 v[106:109], v[212:215], v[160:163], 0
	v_mfma_f32_16x16x32_bf16 v[94:97], v[204:207], v[180:183], 0
	v_mfma_f32_16x16x32_bf16 v[90:93], v[212:215], v[180:183], 0
	v_mfma_f32_16x16x32_bf16 v[78:81], v[204:207], v[188:191], 0
	v_mfma_f32_16x16x32_bf16 v[74:77], v[212:215], v[188:191], 0
	v_mfma_f32_16x16x32_bf16 v[70:73], v[204:207], v[196:199], 0
	v_mfma_f32_16x16x32_bf16 v[66:69], v[212:215], v[196:199], 0
	v_mfma_f32_16x16x32_bf16 v[110:113], v[208:211], v[176:179], v[110:113]
	v_mfma_f32_16x16x32_bf16 v[106:109], v[216:219], v[176:179], v[106:109]
	v_mfma_f32_16x16x32_bf16 v[94:97], v[208:211], v[184:187], v[94:97]
	v_mfma_f32_16x16x32_bf16 v[90:93], v[216:219], v[184:187], v[90:93]
	v_mfma_f32_16x16x32_bf16 v[78:81], v[208:211], v[192:195], v[78:81]
	v_mfma_f32_16x16x32_bf16 v[74:77], v[216:219], v[192:195], v[74:77]
	v_mfma_f32_16x16x32_bf16 v[70:73], v[208:211], v[200:203], v[70:73]
	v_mfma_f32_16x16x32_bf16 v[66:69], v[216:219], v[200:203], v[66:69]
	s_mov_b32 m0, s15
	v_lshl_add_u64 v[170:171], s[22:23], 0, v[134:135]
	s_barrier
	ds_read_b128 v[160:163], v143 offset:16384
	ds_read_b128 v[176:179], v143 offset:17408
	ds_read_b128 v[180:183], v143 offset:18432
	ds_read_b128 v[184:187], v143 offset:19456
	ds_read_b128 v[188:191], v143 offset:20480
	ds_read_b128 v[192:195], v143 offset:21504
	ds_read_b128 v[196:199], v143 offset:22528
	ds_read_b128 v[200:203], v143 offset:23552
	global_load_lds_dwordx4 v[170:171], off
	v_lshl_add_u64 v[220:221], s[22:23], 0, v[132:133]
	s_mov_b32 m0, s45
	s_nop 0
	global_load_lds_dwordx4 v[220:221], off
	s_barrier
	s_waitcnt lgkmcnt(0)
	s_waitcnt lgkmcnt(0)
	s_nop 0
	v_mfma_f32_16x16x32_bf16 v[62:65], v[144:147], v[160:163], 0
	v_mfma_f32_16x16x32_bf16 v[58:61], v[152:155], v[160:163], 0
	v_mfma_f32_16x16x32_bf16 v[54:57], v[144:147], v[180:183], 0
	v_mfma_f32_16x16x32_bf16 v[50:53], v[152:155], v[180:183], 0
	v_mfma_f32_16x16x32_bf16 v[38:41], v[144:147], v[188:191], 0
	v_mfma_f32_16x16x32_bf16 v[34:37], v[152:155], v[188:191], 0
	v_mfma_f32_16x16x32_bf16 v[22:25], v[144:147], v[196:199], 0
	v_mfma_f32_16x16x32_bf16 v[18:21], v[152:155], v[196:199], 0
	v_mfma_f32_16x16x32_bf16 v[62:65], v[148:151], v[176:179], v[62:65]
	v_mfma_f32_16x16x32_bf16 v[58:61], v[156:159], v[176:179], v[58:61]
	v_mfma_f32_16x16x32_bf16 v[54:57], v[148:151], v[184:187], v[54:57]
	v_mfma_f32_16x16x32_bf16 v[50:53], v[156:159], v[184:187], v[50:53]
	v_mfma_f32_16x16x32_bf16 v[38:41], v[148:151], v[192:195], v[38:41]
	v_mfma_f32_16x16x32_bf16 v[34:37], v[156:159], v[192:195], v[34:37]
	v_mfma_f32_16x16x32_bf16 v[22:25], v[148:151], v[200:203], v[22:25]
	v_mfma_f32_16x16x32_bf16 v[18:21], v[156:159], v[200:203], v[18:21]
	s_barrier
; #define PG8_STAGE(bufoff, gbase, voff) do { _Pragma("unroll") for (int _i = 0; _i < 2; ++_i) \
;         __builtin_amdgcn_global_load_lds((const unsigned*)((const char*)(gbase) + (voff)[_i]), (LAS unsigned*)(lds + (bufoff) + ldsw + _i * 8192), 16, 0, 0); } while (0)
; #define PG8_LDA(dst, b, h) do { _Pragma("unroll") for (int m = 0; m < 4; ++m) _Pragma("unroll") for (int k = 0; k < 2; ++k) dst[m][k] = *(const LAS bf16x8*)(lds + PG8_SA(b, h) + aoff + m * 2048 + k * 1024); } while (0)
; #define PG8_LDB(dst, b, h) do { _Pragma("unroll") for (int n = 0; n < 2; ++n) _Pragma("unroll") for (int k = 0; k < 2; ++k) dst[n][k] = *(const LAS bf16x8*)(lds + PG8_SB(b, h) + boff + n * 2048 + k * 1024); } while (0)
; #define PG8_MMA(ai, bj, At, Bt) do { __builtin_amdgcn_s_setprio(1); _Pragma("unroll") for (int m = 0; m < 4; ++m) _Pragma("unroll") for (int n = 0; n < 2; ++n) _Pragma("unroll") for (int k = 0; k < 2; ++k) \
;         acc[ai][bj][m][n] = __builtin_amdgcn_mfma_f32_16x16x32_bf16(Bt[n][k], At[m][k], acc[ai][bj][m][n], 0, 0, 0); __builtin_amdgcn_s_setprio(0); } while (0)
; #define PG8_WAIT_V(n) asm volatile("s_waitcnt vmcnt(" #n ")" ::: "memory")
; #define PG8_WAIT_L(n) asm volatile("s_waitcnt lgkmcnt(" #n ")" ::: "memory")
; #define PG8_BAR __builtin_amdgcn_s_barrier()
; #define PG8_SCHED __builtin_amdgcn_sched_barrier(0)
; template <class Epi>
; DI void gemm_phase(int wv, LAS unsigned char* lds, const GemmD g, const Epi& E) {
;     ...
;             PG8_STAGE(PG8_SB(0, 1), b2 + hstepB, voffB);
;             PG8_WAIT_V(6); PG8_BAR; PG8_MMA(1, 1, At, B1); PG8_BAR;
;             PG8_LDB(B0, 1, 0); PG8_SCHED; PG8_LDA(At, 1, 0); PG8_STAGE(PG8_SA(0, 1), a2 + hstepA, voffA);
;             PG8_WAIT_L(8); PG8_BAR; PG8_WAIT_L(0); PG8_MMA(0, 0, At, B0); PG8_BAR; PG8_SCHED;
;             PG8_LDB(B1, 1, 1); PG8_STAGE(PG8_SB(1, 0), b3, voffB);
	s_add_u32 s24, s24, s36
	s_addc_u32 s25, s25, 0
	s_add_i32 s2, s2, s37
	v_lshl_add_u64 v[222:223], s[24:25], 0, v[0:1]
	s_mov_b32 m0, s2
	v_lshl_add_u64 v[224:225], s[24:25], 0, v[130:131]
	global_load_lds_dwordx4 v[222:223], off
	s_add_i32 m0, s2, 0x2000
	s_nop 0
	global_load_lds_dwordx4 v[224:225], off
	s_waitcnt vmcnt(6)
	s_barrier
	v_mfma_f32_16x16x32_bf16 v[46:49], v[204:207], v[160:163], 0
	v_mfma_f32_16x16x32_bf16 v[42:45], v[212:215], v[160:163], 0
	v_mfma_f32_16x16x32_bf16 v[30:33], v[204:207], v[180:183], 0
	v_mfma_f32_16x16x32_bf16 v[26:29], v[212:215], v[180:183], 0
	v_mfma_f32_16x16x32_bf16 v[14:17], v[204:207], v[188:191], 0
	v_mfma_f32_16x16x32_bf16 v[10:13], v[212:215], v[188:191], 0
	v_mfma_f32_16x16x32_bf16 v[6:9], v[204:207], v[196:199], 0
	v_mfma_f32_16x16x32_bf16 v[2:5], v[212:215], v[196:199], 0
	v_mfma_f32_16x16x32_bf16 v[46:49], v[208:211], v[176:179], v[46:49]
	v_mfma_f32_16x16x32_bf16 v[42:45], v[216:219], v[176:179], v[42:45]
	v_mfma_f32_16x16x32_bf16 v[30:33], v[208:211], v[184:187], v[30:33]
	v_mfma_f32_16x16x32_bf16 v[26:29], v[216:219], v[184:187], v[26:29]
	v_mfma_f32_16x16x32_bf16 v[14:17], v[208:211], v[192:195], v[14:17]
	v_mfma_f32_16x16x32_bf16 v[10:13], v[216:219], v[192:195], v[10:13]
	v_mfma_f32_16x16x32_bf16 v[6:9], v[208:211], v[200:203], v[6:9]
	v_mfma_f32_16x16x32_bf16 v[2:5], v[216:219], v[200:203], v[2:5]
	s_add_i32 s2, 0, 0x18000
	v_add_u32_e32 v156, s2, v141
	s_barrier
	ds_read_b128 v[144:147], v156
	ds_read_b128 v[148:151], v156 offset:1024
	ds_read_b128 v[152:155], v156 offset:2048
	ds_read_b128 v[156:159], v156 offset:3072
	s_add_u32 s22, s22, 0x40000
	s_addc_u32 s23, s23, 0
	s_mov_b32 m0, s82
	v_lshl_add_u64 v[204:205], s[22:23], 0, v[134:135]
	ds_read_b128 v[160:163], v143 offset:32768
	ds_read_b128 v[176:179], v143 offset:33792
	ds_read_b128 v[180:183], v143 offset:34816
	ds_read_b128 v[184:187], v143 offset:35840
	ds_read_b128 v[188:191], v143 offset:36864
	ds_read_b128 v[192:195], v143 offset:37888
	ds_read_b128 v[196:199], v143 offset:38912
	ds_read_b128 v[200:203], v143 offset:39936
	global_load_lds_dwordx4 v[204:205], off
	v_lshl_add_u64 v[204:205], s[22:23], 0, v[132:133]
	s_mov_b32 m0, s83
	s_nop 0
	global_load_lds_dwordx4 v[204:205], off
	s_waitcnt lgkmcnt(8)
	s_barrier
	s_waitcnt lgkmcnt(0)
	s_waitcnt lgkmcnt(0)
	v_mfma_f32_16x16x32_bf16 v[126:129], v[144:147], v[160:163], v[126:129]
	v_mfma_f32_16x16x32_bf16 v[122:125], v[152:155], v[160:163], v[122:125]
	v_mfma_f32_16x16x32_bf16 v[118:121], v[144:147], v[180:183], v[118:121]
	v_mfma_f32_16x16x32_bf16 v[114:117], v[152:155], v[180:183], v[114:117]
	v_mfma_f32_16x16x32_bf16 v[102:105], v[144:147], v[188:191], v[102:105]
	v_mfma_f32_16x16x32_bf16 v[98:101], v[152:155], v[188:191], v[98:101]
	v_mfma_f32_16x16x32_bf16 v[86:89], v[144:147], v[196:199], v[86:89]
	v_mfma_f32_16x16x32_bf16 v[82:85], v[152:155], v[196:199], v[82:85]
	v_mfma_f32_16x16x32_bf16 v[126:129], v[148:151], v[176:179], v[126:129]
	v_mfma_f32_16x16x32_bf16 v[122:125], v[156:159], v[176:179], v[122:125]
	v_mfma_f32_16x16x32_bf16 v[118:121], v[148:151], v[184:187], v[118:121]
	v_mfma_f32_16x16x32_bf16 v[114:117], v[156:159], v[184:187], v[114:117]
	v_mfma_f32_16x16x32_bf16 v[102:105], v[148:151], v[192:195], v[102:105]
	v_mfma_f32_16x16x32_bf16 v[98:101], v[156:159], v[192:195], v[98:101]
	v_mfma_f32_16x16x32_bf16 v[86:89], v[148:151], v[200:203], v[86:89]
	v_mfma_f32_16x16x32_bf16 v[82:85], v[156:159], v[200:203], v[82:85]
	s_barrier
	s_add_i32 s3, 0, 0x1c000
	s_add_i32 s2, s2, s37
	v_add_u32_e32 v216, s3, v141
	v_lshl_add_u64 v[164:165], v[164:165], 0, s[58:59]
	s_mov_b32 m0, s2
	ds_read_b128 v[204:207], v216
	ds_read_b128 v[208:211], v216 offset:1024
	ds_read_b128 v[212:215], v216 offset:2048
	ds_read_b128 v[216:219], v216 offset:3072
	global_load_lds_dwordx4 v[164:165], off
	v_lshl_add_u64 v[164:165], v[168:169], 0, s[58:59]
	s_add_i32 m0, s2, 0x2000
	s_nop 0
	global_load_lds_dwordx4 v[164:165], off
	s_barrier
	s_waitcnt lgkmcnt(0)
	s_waitcnt lgkmcnt(0)
	v_mfma_f32_16x16x32_bf16 v[110:113], v[204:207], v[160:163], v[110:113]
	v_mfma_f32_16x16x32_bf16 v[106:109], v[212:215], v[160:163], v[106:109]
	v_mfma_f32_16x16x32_bf16 v[94:97], v[204:207], v[180:183], v[94:97]
	v_mfma_f32_16x16x32_bf16 v[90:93], v[212:215], v[180:183], v[90:93]
	v_mfma_f32_16x16x32_bf16 v[78:81], v[204:207], v[188:191], v[78:81]
	v_mfma_f32_16x16x32_bf16 v[74:77], v[212:215], v[188:191], v[74:77]
	v_mfma_f32_16x16x32_bf16 v[70:73], v[204:207], v[196:199], v[70:73]
	v_mfma_f32_16x16x32_bf16 v[66:69], v[212:215], v[196:199], v[66:69]
	v_mfma_f32_16x16x32_bf16 v[110:113], v[208:211], v[176:179], v[110:113]
	v_mfma_f32_16x16x32_bf16 v[106:109], v[216:219], v[176:179], v[106:109]
	v_mfma_f32_16x16x32_bf16 v[94:97], v[208:211], v[184:187], v[94:97]
	v_mfma_f32_16x16x32_bf16 v[90:93], v[216:219], v[184:187], v[90:93]
	v_mfma_f32_16x16x32_bf16 v[78:81], v[208:211], v[192:195], v[78:81]
	v_mfma_f32_16x16x32_bf16 v[74:77], v[216:219], v[192:195], v[74:77]
	v_mfma_f32_16x16x32_bf16 v[70:73], v[208:211], v[200:203], v[70:73]
	v_mfma_f32_16x16x32_bf16 v[66:69], v[216:219], v[200:203], v[66:69]
	s_mov_b32 m0, s84
	v_lshl_add_u64 v[164:165], v[170:171], 0, s[58:59]
	s_barrier
	ds_read_b128 v[160:163], v143 offset:49152
	ds_read_b128 v[176:179], v143 offset:50176
	ds_read_b128 v[180:183], v143 offset:51200
	ds_read_b128 v[184:187], v143 offset:52224
	ds_read_b128 v[188:191], v143 offset:53248
	ds_read_b128 v[192:195], v143 offset:54272
	ds_read_b128 v[196:199], v143 offset:55296
	ds_read_b128 v[200:203], v143 offset:56320
	global_load_lds_dwordx4 v[164:165], off
	v_lshl_add_u64 v[164:165], v[220:221], 0, s[58:59]
	s_mov_b32 m0, s85
	s_nop 0
	global_load_lds_dwordx4 v[164:165], off
	s_barrier
; #define PG8_STAGE(bufoff, gbase, voff) do { _Pragma("unroll") for (int _i = 0; _i < 2; ++_i) \
;         __builtin_amdgcn_global_load_lds((const unsigned*)((const char*)(gbase) + (voff)[_i]), (LAS unsigned*)(lds + (bufoff) + ldsw + _i * 8192), 16, 0, 0); } while (0)
; #define PG8_LDA(dst, b, h) do { _Pragma("unroll") for (int m = 0; m < 4; ++m) _Pragma("unroll") for (int k = 0; k < 2; ++k) dst[m][k] = *(const LAS bf16x8*)(lds + PG8_SA(b, h) + aoff + m * 2048 + k * 1024); } while (0)
; #define PG8_LDB(dst, b, h) do { _Pragma("unroll") for (int n = 0; n < 2; ++n) _Pragma("unroll") for (int k = 0; k < 2; ++k) dst[n][k] = *(const LAS bf16x8*)(lds + PG8_SB(b, h) + boff + n * 2048 + k * 1024); } while (0)
; #define PG8_MMA(ai, bj, At, Bt) do { __builtin_amdgcn_s_setprio(1); _Pragma("unroll") for (int m = 0; m < 4; ++m) _Pragma("unroll") for (int n = 0; n < 2; ++n) _Pragma("unroll") for (int k = 0; k < 2; ++k) \
;         acc[ai][bj][m][n] = __builtin_amdgcn_mfma_f32_16x16x32_bf16(Bt[n][k], At[m][k], acc[ai][bj][m][n], 0, 0, 0); __builtin_amdgcn_s_setprio(0); } while (0)
; #define PG8_WAIT_V(n) asm volatile("s_waitcnt vmcnt(" #n ")" ::: "memory")
; #define PG8_WAIT_L(n) asm volatile("s_waitcnt lgkmcnt(" #n ")" ::: "memory")
; #define PG8_BAR __builtin_amdgcn_s_barrier()
; template <class Epi>
; DI void gemm_phase(int wv, LAS unsigned char* lds, const GemmD g, const Epi& E) {
;     ...
;         for (int t = 0; t < nt; t += 2) {
;             const bool last = (t == nt - 2);
;             const char* a1 = cA + (size_t)(t + 1) * kstep;
;             const char* a2 = last ? nA : cA + (size_t)(t + 2) * kstep; const char* b2 = last ? nB : cB + (size_t)(t + 2) * kstep;
;             const char* a3 = a2 + kstep; const char* b3 = b2 + kstep;
;             PG8_LDB(B0, 0, 0); PG8_SCHED; PG8_LDA(At, 0, 0); PG8_STAGE(PG8_SA(1, 1), a1 + hstepA, voffA);
;             PG8_WAIT_L(8); PG8_BAR; PG8_WAIT_L(0); PG8_MMA(0, 0, At, B0); PG8_BAR; PG8_SCHED;
;             PG8_LDB(B1, 0, 1); PG8_STAGE(PG8_SB(0, 0), b2, voffB);
;             PG8_BAR; PG8_WAIT_L(0); PG8_MMA(0, 1, At, B1); PG8_BAR;
;     ...
;             PG8_LDA(At, 1, 1); PG8_STAGE(PG8_SA(1, 0), a3, voffA);
;             PG8_BAR; PG8_WAIT_L(0); PG8_MMA(1, 0, At, B0); PG8_BAR; PG8_SCHED;
;             PG8_STAGE(PG8_SB(1, 1), b3 + hstepB, voffB);
;             PG8_WAIT_V(6); PG8_BAR; PG8_MMA(1, 1, At, B1); PG8_BAR;
	s_waitcnt lgkmcnt(0)
	s_waitcnt lgkmcnt(0)
	s_nop 0
	v_mfma_f32_16x16x32_bf16 v[62:65], v[144:147], v[160:163], v[62:65]
	v_mfma_f32_16x16x32_bf16 v[58:61], v[152:155], v[160:163], v[58:61]
	v_mfma_f32_16x16x32_bf16 v[54:57], v[144:147], v[180:183], v[54:57]
	v_mfma_f32_16x16x32_bf16 v[50:53], v[152:155], v[180:183], v[50:53]
	v_mfma_f32_16x16x32_bf16 v[38:41], v[144:147], v[188:191], v[38:41]
	v_mfma_f32_16x16x32_bf16 v[34:37], v[152:155], v[188:191], v[34:37]
	v_mfma_f32_16x16x32_bf16 v[22:25], v[144:147], v[196:199], v[22:25]
	v_mfma_f32_16x16x32_bf16 v[18:21], v[152:155], v[196:199], v[18:21]
	v_mfma_f32_16x16x32_bf16 v[62:65], v[148:151], v[176:179], v[62:65]
	v_mfma_f32_16x16x32_bf16 v[58:61], v[156:159], v[176:179], v[58:61]
	v_mfma_f32_16x16x32_bf16 v[54:57], v[148:151], v[184:187], v[54:57]
	v_mfma_f32_16x16x32_bf16 v[50:53], v[156:159], v[184:187], v[50:53]
	v_mfma_f32_16x16x32_bf16 v[38:41], v[148:151], v[192:195], v[38:41]
	v_mfma_f32_16x16x32_bf16 v[34:37], v[156:159], v[192:195], v[34:37]
	v_mfma_f32_16x16x32_bf16 v[22:25], v[148:151], v[200:203], v[22:25]
	v_mfma_f32_16x16x32_bf16 v[18:21], v[156:159], v[200:203], v[18:21]
	s_barrier
	s_add_i32 s2, s3, s37
	v_lshl_add_u64 v[144:145], v[222:223], 0, s[58:59]
	s_mov_b32 m0, s2
	s_nop 0
	global_load_lds_dwordx4 v[144:145], off
	v_lshl_add_u64 v[144:145], v[224:225], 0, s[58:59]
	s_add_i32 m0, s2, 0x2000
	s_nop 0
	global_load_lds_dwordx4 v[144:145], off
	s_waitcnt vmcnt(6)
	s_barrier
	s_nop 0
	v_mfma_f32_16x16x32_bf16 v[46:49], v[204:207], v[160:163], v[46:49]
	v_mfma_f32_16x16x32_bf16 v[42:45], v[212:215], v[160:163], v[42:45]
	v_mfma_f32_16x16x32_bf16 v[30:33], v[204:207], v[180:183], v[30:33]
	v_mfma_f32_16x16x32_bf16 v[26:29], v[212:215], v[180:183], v[26:29]
	v_mfma_f32_16x16x32_bf16 v[14:17], v[204:207], v[188:191], v[14:17]
	v_mfma_f32_16x16x32_bf16 v[10:13], v[212:215], v[188:191], v[10:13]
	v_mfma_f32_16x16x32_bf16 v[6:9], v[204:207], v[196:199], v[6:9]
	v_mfma_f32_16x16x32_bf16 v[2:5], v[212:215], v[196:199], v[2:5]
	v_mfma_f32_16x16x32_bf16 v[46:49], v[208:211], v[176:179], v[46:49]
	v_mfma_f32_16x16x32_bf16 v[42:45], v[216:219], v[176:179], v[42:45]
	v_mfma_f32_16x16x32_bf16 v[30:33], v[208:211], v[184:187], v[30:33]
	v_mfma_f32_16x16x32_bf16 v[26:29], v[216:219], v[184:187], v[26:29]
	v_mfma_f32_16x16x32_bf16 v[14:17], v[208:211], v[192:195], v[14:17]
	v_mfma_f32_16x16x32_bf16 v[10:13], v[216:219], v[192:195], v[10:13]
	v_mfma_f32_16x16x32_bf16 v[6:9], v[208:211], v[200:203], v[6:9]
	v_mfma_f32_16x16x32_bf16 v[2:5], v[216:219], v[200:203], v[2:5]
	s_add_i32 s95, s95, 2
	s_add_u32 s4, s4, 0x100
	s_addc_u32 s5, s5, 0
	s_add_u32 vcc_hi, vcc_hi, 0x100
	s_addc_u32 s75, s75, 0
	s_cmp_gt_u32 s95, 13
	s_barrier
	s_cbranch_scc0 .LBB0_99
	s_branch .Lgemm_epi_a
	.p2align 6
.LBB0_99:
	s_add_u32 s22, s4, 0xfffc0080
	s_addc_u32 s23, s5, -1
	s_add_i32 s3, 0, 0x10000
	v_add_u32_e32 v156, s3, v141
	ds_read_b128 v[144:147], v156
	ds_read_b128 v[148:151], v156 offset:1024
	ds_read_b128 v[152:155], v156 offset:2048
	ds_read_b128 v[156:159], v156 offset:3072
	s_cmp_eq_u32 s95, 12
	s_cselect_b32 s23, s17, s23
	s_cselect_b32 s22, vcc_lo, s22
	s_cselect_b32 s25, s19, s75
	s_cselect_b32 s24, s18, vcc_hi
	v_lshl_add_u64 v[164:165], s[4:5], 0, v[136:137]
	s_add_i32 m0, s15, 0xc000
	ds_read_b128 v[160:163], v143
	ds_read_b128 v[176:179], v143 offset:1024
	ds_read_b128 v[180:183], v143 offset:2048
	ds_read_b128 v[184:187], v143 offset:3072
	ds_read_b128 v[188:191], v143 offset:4096
	ds_read_b128 v[192:195], v143 offset:5120
	ds_read_b128 v[196:199], v143 offset:6144
	ds_read_b128 v[200:203], v143 offset:7168
	global_load_lds_dwordx4 v[164:165], off
	v_lshl_add_u64 v[164:165], s[4:5], 0, v[138:139]
	s_add_i32 m0, s15, 0xe000
	s_nop 0
	global_load_lds_dwordx4 v[164:165], off
	s_waitcnt lgkmcnt(8)
	s_barrier
	s_waitcnt lgkmcnt(0)
	s_waitcnt lgkmcnt(0)
	v_mfma_f32_16x16x32_bf16 v[126:129], v[144:147], v[160:163], v[126:129]
	v_mfma_f32_16x16x32_bf16 v[122:125], v[152:155], v[160:163], v[122:125]
	v_mfma_f32_16x16x32_bf16 v[118:121], v[144:147], v[180:183], v[118:121]
	v_mfma_f32_16x16x32_bf16 v[114:117], v[152:155], v[180:183], v[114:117]
	v_mfma_f32_16x16x32_bf16 v[102:105], v[144:147], v[188:191], v[102:105]
	v_mfma_f32_16x16x32_bf16 v[98:101], v[152:155], v[188:191], v[98:101]
	v_mfma_f32_16x16x32_bf16 v[86:89], v[144:147], v[196:199], v[86:89]
	v_mfma_f32_16x16x32_bf16 v[82:85], v[152:155], v[196:199], v[82:85]
	v_mfma_f32_16x16x32_bf16 v[126:129], v[148:151], v[176:179], v[126:129]
	v_mfma_f32_16x16x32_bf16 v[122:125], v[156:159], v[176:179], v[122:125]
	v_mfma_f32_16x16x32_bf16 v[118:121], v[148:151], v[184:187], v[118:121]
	v_mfma_f32_16x16x32_bf16 v[114:117], v[156:159], v[184:187], v[114:117]
	v_mfma_f32_16x16x32_bf16 v[102:105], v[148:151], v[192:195], v[102:105]
	v_mfma_f32_16x16x32_bf16 v[98:101], v[156:159], v[192:195], v[98:101]
	v_mfma_f32_16x16x32_bf16 v[86:89], v[148:151], v[200:203], v[86:89]
	v_mfma_f32_16x16x32_bf16 v[82:85], v[156:159], v[200:203], v[82:85]
	s_barrier
	s_add_i32 s2, 0, 0x14000
	v_add_u32_e32 v164, s2, v141
	s_add_i32 s3, s3, s37
	ds_read_b128 v[204:207], v164
	ds_read_b128 v[208:211], v164 offset:1024
	ds_read_b128 v[212:215], v164 offset:2048
	ds_read_b128 v[216:219], v164 offset:3072
	v_lshl_add_u64 v[164:165], s[24:25], 0, v[0:1]
	s_mov_b32 m0, s3
	v_lshl_add_u64 v[168:169], s[24:25], 0, v[130:131]
	global_load_lds_dwordx4 v[164:165], off
	s_add_i32 m0, s3, 0x2000
	s_nop 0
	global_load_lds_dwordx4 v[168:169], off
	s_barrier
; #define PG8_STAGE(bufoff, gbase, voff) do { _Pragma("unroll") for (int _i = 0; _i < 2; ++_i) \
;         __builtin_amdgcn_global_load_lds((const unsigned*)((const char*)(gbase) + (voff)[_i]), (LAS unsigned*)(lds + (bufoff) + ldsw + _i * 8192), 16, 0, 0); } while (0)
; #define PG8_LDA(dst, b, h) do { _Pragma("unroll") for (int m = 0; m < 4; ++m) _Pragma("unroll") for (int k = 0; k < 2; ++k) dst[m][k] = *(const LAS bf16x8*)(lds + PG8_SA(b, h) + aoff + m * 2048 + k * 1024); } while (0)
; #define PG8_LDB(dst, b, h) do { _Pragma("unroll") for (int n = 0; n < 2; ++n) _Pragma("unroll") for (int k = 0; k < 2; ++k) dst[n][k] = *(const LAS bf16x8*)(lds + PG8_SB(b, h) + boff + n * 2048 + k * 1024); } while (0)
; #define PG8_MMA(ai, bj, At, Bt) do { __builtin_amdgcn_s_setprio(1); _Pragma("unroll") for (int m = 0; m < 4; ++m) _Pragma("unroll") for (int n = 0; n < 2; ++n) _Pragma("unroll") for (int k = 0; k < 2; ++k) \
;         acc[ai][bj][m][n] = __builtin_amdgcn_mfma_f32_16x16x32_bf16(Bt[n][k], At[m][k], acc[ai][bj][m][n], 0, 0, 0); __builtin_amdgcn_s_setprio(0); } while (0)
; #define PG8_WAIT_V(n) asm volatile("s_waitcnt vmcnt(" #n ")" ::: "memory")
; #define PG8_WAIT_L(n) asm volatile("s_waitcnt lgkmcnt(" #n ")" ::: "memory")
; #define PG8_BAR __builtin_amdgcn_s_barrier()
; #define PG8_SCHED __builtin_amdgcn_sched_barrier(0)
; template <class Epi>
; DI void gemm_phase(int wv, LAS unsigned char* lds, const GemmD g, const Epi& E) {
;     ...
;             PG8_BAR; PG8_WAIT_L(0); PG8_MMA(0, 1, At, B1); PG8_BAR;
;             PG8_LDA(At, 0, 1); PG8_STAGE(PG8_SA(0, 0), a2, voffA);
;             PG8_BAR; PG8_WAIT_L(0); PG8_MMA(1, 0, At, B0); PG8_BAR; PG8_SCHED;
;             PG8_STAGE(PG8_SB(0, 1), b2 + hstepB, voffB);
;             PG8_WAIT_V(6); PG8_BAR; PG8_MMA(1, 1, At, B1); PG8_BAR;
;             PG8_LDB(B0, 1, 0); PG8_SCHED; PG8_LDA(At, 1, 0); PG8_STAGE(PG8_SA(0, 1), a2 + hstepA, voffA);
;             PG8_WAIT_L(8); PG8_BAR; PG8_WAIT_L(0); PG8_MMA(0, 0, At, B0); PG8_BAR; PG8_SCHED;
;             PG8_LDB(B1, 1, 1); PG8_STAGE(PG8_SB(1, 0), b3, voffB);
	s_waitcnt lgkmcnt(0)
	s_waitcnt lgkmcnt(0)
	v_mfma_f32_16x16x32_bf16 v[110:113], v[204:207], v[160:163], v[110:113]
	v_mfma_f32_16x16x32_bf16 v[106:109], v[212:215], v[160:163], v[106:109]
	v_mfma_f32_16x16x32_bf16 v[94:97], v[204:207], v[180:183], v[94:97]
	v_mfma_f32_16x16x32_bf16 v[90:93], v[212:215], v[180:183], v[90:93]
	v_mfma_f32_16x16x32_bf16 v[78:81], v[204:207], v[188:191], v[78:81]
	v_mfma_f32_16x16x32_bf16 v[74:77], v[212:215], v[188:191], v[74:77]
	v_mfma_f32_16x16x32_bf16 v[70:73], v[204:207], v[196:199], v[70:73]
	v_mfma_f32_16x16x32_bf16 v[66:69], v[212:215], v[196:199], v[66:69]
	v_mfma_f32_16x16x32_bf16 v[110:113], v[208:211], v[176:179], v[110:113]
	v_mfma_f32_16x16x32_bf16 v[106:109], v[216:219], v[176:179], v[106:109]
	v_mfma_f32_16x16x32_bf16 v[94:97], v[208:211], v[184:187], v[94:97]
	v_mfma_f32_16x16x32_bf16 v[90:93], v[216:219], v[184:187], v[90:93]
	v_mfma_f32_16x16x32_bf16 v[78:81], v[208:211], v[192:195], v[78:81]
	v_mfma_f32_16x16x32_bf16 v[74:77], v[216:219], v[192:195], v[74:77]
	v_mfma_f32_16x16x32_bf16 v[70:73], v[208:211], v[200:203], v[70:73]
	v_mfma_f32_16x16x32_bf16 v[66:69], v[216:219], v[200:203], v[66:69]
	s_mov_b32 m0, s15
	v_lshl_add_u64 v[170:171], s[22:23], 0, v[134:135]
	s_barrier
	ds_read_b128 v[160:163], v143 offset:16384
	ds_read_b128 v[176:179], v143 offset:17408
	ds_read_b128 v[180:183], v143 offset:18432
	ds_read_b128 v[184:187], v143 offset:19456
	ds_read_b128 v[188:191], v143 offset:20480
	ds_read_b128 v[192:195], v143 offset:21504
	ds_read_b128 v[196:199], v143 offset:22528
	ds_read_b128 v[200:203], v143 offset:23552
	global_load_lds_dwordx4 v[170:171], off
	v_lshl_add_u64 v[220:221], s[22:23], 0, v[132:133]
	s_mov_b32 m0, s45
	s_nop 0
	global_load_lds_dwordx4 v[220:221], off
	s_barrier
	s_waitcnt lgkmcnt(0)
	s_waitcnt lgkmcnt(0)
	s_nop 0
	v_mfma_f32_16x16x32_bf16 v[62:65], v[144:147], v[160:163], v[62:65]
	v_mfma_f32_16x16x32_bf16 v[58:61], v[152:155], v[160:163], v[58:61]
	v_mfma_f32_16x16x32_bf16 v[54:57], v[144:147], v[180:183], v[54:57]
	v_mfma_f32_16x16x32_bf16 v[50:53], v[152:155], v[180:183], v[50:53]
	v_mfma_f32_16x16x32_bf16 v[38:41], v[144:147], v[188:191], v[38:41]
	v_mfma_f32_16x16x32_bf16 v[34:37], v[152:155], v[188:191], v[34:37]
	v_mfma_f32_16x16x32_bf16 v[22:25], v[144:147], v[196:199], v[22:25]
	v_mfma_f32_16x16x32_bf16 v[18:21], v[152:155], v[196:199], v[18:21]
	v_mfma_f32_16x16x32_bf16 v[62:65], v[148:151], v[176:179], v[62:65]
	v_mfma_f32_16x16x32_bf16 v[58:61], v[156:159], v[176:179], v[58:61]
	v_mfma_f32_16x16x32_bf16 v[54:57], v[148:151], v[184:187], v[54:57]
	v_mfma_f32_16x16x32_bf16 v[50:53], v[156:159], v[184:187], v[50:53]
	v_mfma_f32_16x16x32_bf16 v[38:41], v[148:151], v[192:195], v[38:41]
	v_mfma_f32_16x16x32_bf16 v[34:37], v[156:159], v[192:195], v[34:37]
	v_mfma_f32_16x16x32_bf16 v[22:25], v[148:151], v[200:203], v[22:25]
	v_mfma_f32_16x16x32_bf16 v[18:21], v[156:159], v[200:203], v[18:21]
	s_barrier
	s_add_u32 s24, s24, s36
	s_addc_u32 s25, s25, 0
	s_add_i32 s2, s2, s37
	v_lshl_add_u64 v[222:223], s[24:25], 0, v[0:1]
	s_mov_b32 m0, s2
	v_lshl_add_u64 v[224:225], s[24:25], 0, v[130:131]
	global_load_lds_dwordx4 v[222:223], off
	s_add_i32 m0, s2, 0x2000
	s_nop 0
	global_load_lds_dwordx4 v[224:225], off
	s_waitcnt vmcnt(6)
	s_barrier
	v_mfma_f32_16x16x32_bf16 v[46:49], v[204:207], v[160:163], v[46:49]
	v_mfma_f32_16x16x32_bf16 v[42:45], v[212:215], v[160:163], v[42:45]
	v_mfma_f32_16x16x32_bf16 v[30:33], v[204:207], v[180:183], v[30:33]
	v_mfma_f32_16x16x32_bf16 v[26:29], v[212:215], v[180:183], v[26:29]
	v_mfma_f32_16x16x32_bf16 v[14:17], v[204:207], v[188:191], v[14:17]
	v_mfma_f32_16x16x32_bf16 v[10:13], v[212:215], v[188:191], v[10:13]
	v_mfma_f32_16x16x32_bf16 v[6:9], v[204:207], v[196:199], v[6:9]
	v_mfma_f32_16x16x32_bf16 v[2:5], v[212:215], v[196:199], v[2:5]
	v_mfma_f32_16x16x32_bf16 v[46:49], v[208:211], v[176:179], v[46:49]
	v_mfma_f32_16x16x32_bf16 v[42:45], v[216:219], v[176:179], v[42:45]
	v_mfma_f32_16x16x32_bf16 v[30:33], v[208:211], v[184:187], v[30:33]
	v_mfma_f32_16x16x32_bf16 v[26:29], v[216:219], v[184:187], v[26:29]
	v_mfma_f32_16x16x32_bf16 v[14:17], v[208:211], v[192:195], v[14:17]
	v_mfma_f32_16x16x32_bf16 v[10:13], v[216:219], v[192:195], v[10:13]
	v_mfma_f32_16x16x32_bf16 v[6:9], v[208:211], v[200:203], v[6:9]
	v_mfma_f32_16x16x32_bf16 v[2:5], v[216:219], v[200:203], v[2:5]
	s_add_i32 s2, 0, 0x18000
	v_add_u32_e32 v156, s2, v141
	s_barrier
	ds_read_b128 v[144:147], v156
	ds_read_b128 v[148:151], v156 offset:1024
	ds_read_b128 v[152:155], v156 offset:2048
	ds_read_b128 v[156:159], v156 offset:3072
	s_add_u32 s22, s22, 0x40000
	s_addc_u32 s23, s23, 0
	s_mov_b32 m0, s82
	v_lshl_add_u64 v[204:205], s[22:23], 0, v[134:135]
	ds_read_b128 v[160:163], v143 offset:32768
	ds_read_b128 v[176:179], v143 offset:33792
	ds_read_b128 v[180:183], v143 offset:34816
	ds_read_b128 v[184:187], v143 offset:35840
	ds_read_b128 v[188:191], v143 offset:36864
	ds_read_b128 v[192:195], v143 offset:37888
	ds_read_b128 v[196:199], v143 offset:38912
	ds_read_b128 v[200:203], v143 offset:39936
	global_load_lds_dwordx4 v[204:205], off
	v_lshl_add_u64 v[204:205], s[22:23], 0, v[132:133]
	s_mov_b32 m0, s83
	s_nop 0
	global_load_lds_dwordx4 v[204:205], off
	s_waitcnt lgkmcnt(8)
	s_barrier
; #define PG8_STAGE(bufoff, gbase, voff) do { _Pragma("unroll") for (int _i = 0; _i < 2; ++_i) \
;         __builtin_amdgcn_global_load_lds((const unsigned*)((const char*)(gbase) + (voff)[_i]), (LAS unsigned*)(lds + (bufoff) + ldsw + _i * 8192), 16, 0, 0); } while (0)
; #define PG8_LDA(dst, b, h) do { _Pragma("unroll") for (int m = 0; m < 4; ++m) _Pragma("unroll") for (int k = 0; k < 2; ++k) dst[m][k] = *(const LAS bf16x8*)(lds + PG8_SA(b, h) + aoff + m * 2048 + k * 1024); } while (0)
; #define PG8_MMA(ai, bj, At, Bt) do { __builtin_amdgcn_s_setprio(1); _Pragma("unroll") for (int m = 0; m < 4; ++m) _Pragma("unroll") for (int n = 0; n < 2; ++n) _Pragma("unroll") for (int k = 0; k < 2; ++k) \
;         acc[ai][bj][m][n] = __builtin_amdgcn_mfma_f32_16x16x32_bf16(Bt[n][k], At[m][k], acc[ai][bj][m][n], 0, 0, 0); __builtin_amdgcn_s_setprio(0); } while (0)
; #define PG8_WAIT_V(n) asm volatile("s_waitcnt vmcnt(" #n ")" ::: "memory")
; #define PG8_WAIT_L(n) asm volatile("s_waitcnt lgkmcnt(" #n ")" ::: "memory")
; #define PG8_BAR __builtin_amdgcn_s_barrier()
; #define PG8_SCHED __builtin_amdgcn_sched_barrier(0)
; template <class Epi>
; DI void gemm_phase(int wv, LAS unsigned char* lds, const GemmD g, const Epi& E) {
;     ...
;             PG8_BAR; PG8_WAIT_L(0); PG8_MMA(0, 1, At, B1); PG8_BAR;
;             PG8_LDA(At, 1, 1); PG8_STAGE(PG8_SA(1, 0), a3, voffA);
;             PG8_BAR; PG8_WAIT_L(0); PG8_MMA(1, 0, At, B0); PG8_BAR; PG8_SCHED;
;             PG8_STAGE(PG8_SB(1, 1), b3 + hstepB, voffB);
;             PG8_WAIT_V(6); PG8_BAR; PG8_MMA(1, 1, At, B1); PG8_BAR;
	s_waitcnt lgkmcnt(0)
	s_waitcnt lgkmcnt(0)
	v_mfma_f32_16x16x32_bf16 v[126:129], v[144:147], v[160:163], v[126:129]
	v_mfma_f32_16x16x32_bf16 v[122:125], v[152:155], v[160:163], v[122:125]
	v_mfma_f32_16x16x32_bf16 v[118:121], v[144:147], v[180:183], v[118:121]
	v_mfma_f32_16x16x32_bf16 v[114:117], v[152:155], v[180:183], v[114:117]
	v_mfma_f32_16x16x32_bf16 v[102:105], v[144:147], v[188:191], v[102:105]
	v_mfma_f32_16x16x32_bf16 v[98:101], v[152:155], v[188:191], v[98:101]
	v_mfma_f32_16x16x32_bf16 v[86:89], v[144:147], v[196:199], v[86:89]
	v_mfma_f32_16x16x32_bf16 v[82:85], v[152:155], v[196:199], v[82:85]
	v_mfma_f32_16x16x32_bf16 v[126:129], v[148:151], v[176:179], v[126:129]
	v_mfma_f32_16x16x32_bf16 v[122:125], v[156:159], v[176:179], v[122:125]
	v_mfma_f32_16x16x32_bf16 v[118:121], v[148:151], v[184:187], v[118:121]
	v_mfma_f32_16x16x32_bf16 v[114:117], v[156:159], v[184:187], v[114:117]
	v_mfma_f32_16x16x32_bf16 v[102:105], v[148:151], v[192:195], v[102:105]
	v_mfma_f32_16x16x32_bf16 v[98:101], v[156:159], v[192:195], v[98:101]
	v_mfma_f32_16x16x32_bf16 v[86:89], v[148:151], v[200:203], v[86:89]
	v_mfma_f32_16x16x32_bf16 v[82:85], v[156:159], v[200:203], v[82:85]
	s_barrier
	s_add_i32 s3, 0, 0x1c000
	s_add_i32 s2, s2, s37
	v_add_u32_e32 v216, s3, v141
	v_lshl_add_u64 v[164:165], v[164:165], 0, s[58:59]
	s_mov_b32 m0, s2
	ds_read_b128 v[204:207], v216
	ds_read_b128 v[208:211], v216 offset:1024
	ds_read_b128 v[212:215], v216 offset:2048
	ds_read_b128 v[216:219], v216 offset:3072
	global_load_lds_dwordx4 v[164:165], off
	v_lshl_add_u64 v[164:165], v[168:169], 0, s[58:59]
	s_add_i32 m0, s2, 0x2000
	s_nop 0
	global_load_lds_dwordx4 v[164:165], off
	s_barrier
	s_waitcnt lgkmcnt(0)
	s_waitcnt lgkmcnt(0)
	v_mfma_f32_16x16x32_bf16 v[110:113], v[204:207], v[160:163], v[110:113]
	v_mfma_f32_16x16x32_bf16 v[106:109], v[212:215], v[160:163], v[106:109]
	v_mfma_f32_16x16x32_bf16 v[94:97], v[204:207], v[180:183], v[94:97]
	v_mfma_f32_16x16x32_bf16 v[90:93], v[212:215], v[180:183], v[90:93]
	v_mfma_f32_16x16x32_bf16 v[78:81], v[204:207], v[188:191], v[78:81]
	v_mfma_f32_16x16x32_bf16 v[74:77], v[212:215], v[188:191], v[74:77]
	v_mfma_f32_16x16x32_bf16 v[70:73], v[204:207], v[196:199], v[70:73]
	v_mfma_f32_16x16x32_bf16 v[66:69], v[212:215], v[196:199], v[66:69]
	v_mfma_f32_16x16x32_bf16 v[110:113], v[208:211], v[176:179], v[110:113]
	v_mfma_f32_16x16x32_bf16 v[106:109], v[216:219], v[176:179], v[106:109]
	v_mfma_f32_16x16x32_bf16 v[94:97], v[208:211], v[184:187], v[94:97]
	v_mfma_f32_16x16x32_bf16 v[90:93], v[216:219], v[184:187], v[90:93]
	v_mfma_f32_16x16x32_bf16 v[78:81], v[208:211], v[192:195], v[78:81]
	v_mfma_f32_16x16x32_bf16 v[74:77], v[216:219], v[192:195], v[74:77]
	v_mfma_f32_16x16x32_bf16 v[70:73], v[208:211], v[200:203], v[70:73]
	v_mfma_f32_16x16x32_bf16 v[66:69], v[216:219], v[200:203], v[66:69]
	s_mov_b32 m0, s84
	v_lshl_add_u64 v[164:165], v[170:171], 0, s[58:59]
	s_barrier
	ds_read_b128 v[160:163], v143 offset:49152
	ds_read_b128 v[176:179], v143 offset:50176
	ds_read_b128 v[180:183], v143 offset:51200
	ds_read_b128 v[184:187], v143 offset:52224
	ds_read_b128 v[188:191], v143 offset:53248
	ds_read_b128 v[192:195], v143 offset:54272
	ds_read_b128 v[196:199], v143 offset:55296
	ds_read_b128 v[200:203], v143 offset:56320
	global_load_lds_dwordx4 v[164:165], off
	v_lshl_add_u64 v[164:165], v[220:221], 0, s[58:59]
	s_mov_b32 m0, s85
	s_nop 0
	global_load_lds_dwordx4 v[164:165], off
	s_barrier
	s_waitcnt lgkmcnt(0)
	s_waitcnt lgkmcnt(0)
	s_nop 0
	v_mfma_f32_16x16x32_bf16 v[62:65], v[144:147], v[160:163], v[62:65]
	v_mfma_f32_16x16x32_bf16 v[58:61], v[152:155], v[160:163], v[58:61]
	v_mfma_f32_16x16x32_bf16 v[54:57], v[144:147], v[180:183], v[54:57]
	v_mfma_f32_16x16x32_bf16 v[50:53], v[152:155], v[180:183], v[50:53]
	v_mfma_f32_16x16x32_bf16 v[38:41], v[144:147], v[188:191], v[38:41]
	v_mfma_f32_16x16x32_bf16 v[34:37], v[152:155], v[188:191], v[34:37]
	v_mfma_f32_16x16x32_bf16 v[22:25], v[144:147], v[196:199], v[22:25]
	v_mfma_f32_16x16x32_bf16 v[18:21], v[152:155], v[196:199], v[18:21]
	v_mfma_f32_16x16x32_bf16 v[62:65], v[148:151], v[176:179], v[62:65]
	v_mfma_f32_16x16x32_bf16 v[58:61], v[156:159], v[176:179], v[58:61]
	v_mfma_f32_16x16x32_bf16 v[54:57], v[148:151], v[184:187], v[54:57]
	v_mfma_f32_16x16x32_bf16 v[50:53], v[156:159], v[184:187], v[50:53]
	v_mfma_f32_16x16x32_bf16 v[38:41], v[148:151], v[192:195], v[38:41]
	v_mfma_f32_16x16x32_bf16 v[34:37], v[156:159], v[192:195], v[34:37]
	v_mfma_f32_16x16x32_bf16 v[22:25], v[148:151], v[200:203], v[22:25]
	v_mfma_f32_16x16x32_bf16 v[18:21], v[156:159], v[200:203], v[18:21]
	s_barrier
	s_add_i32 s2, s3, s37
	v_lshl_add_u64 v[144:145], v[222:223], 0, s[58:59]
	s_mov_b32 m0, s2
	s_nop 0
	global_load_lds_dwordx4 v[144:145], off
	v_lshl_add_u64 v[144:145], v[224:225], 0, s[58:59]
	s_add_i32 m0, s2, 0x2000
	s_nop 0
	global_load_lds_dwordx4 v[144:145], off
	s_waitcnt vmcnt(6)
	s_barrier
	s_nop 0
	v_mfma_f32_16x16x32_bf16 v[46:49], v[204:207], v[160:163], v[46:49]
	v_mfma_f32_16x16x32_bf16 v[42:45], v[212:215], v[160:163], v[42:45]
	v_mfma_f32_16x16x32_bf16 v[30:33], v[204:207], v[180:183], v[30:33]
	v_mfma_f32_16x16x32_bf16 v[26:29], v[212:215], v[180:183], v[26:29]
	v_mfma_f32_16x16x32_bf16 v[14:17], v[204:207], v[188:191], v[14:17]
	v_mfma_f32_16x16x32_bf16 v[10:13], v[212:215], v[188:191], v[10:13]
	v_mfma_f32_16x16x32_bf16 v[6:9], v[204:207], v[196:199], v[6:9]
	v_mfma_f32_16x16x32_bf16 v[2:5], v[212:215], v[196:199], v[2:5]
	v_mfma_f32_16x16x32_bf16 v[46:49], v[208:211], v[176:179], v[46:49]
	v_mfma_f32_16x16x32_bf16 v[42:45], v[216:219], v[176:179], v[42:45]
	v_mfma_f32_16x16x32_bf16 v[30:33], v[208:211], v[184:187], v[30:33]
	v_mfma_f32_16x16x32_bf16 v[26:29], v[216:219], v[184:187], v[26:29]
	v_mfma_f32_16x16x32_bf16 v[14:17], v[208:211], v[192:195], v[14:17]
	v_mfma_f32_16x16x32_bf16 v[10:13], v[216:219], v[192:195], v[10:13]
	v_mfma_f32_16x16x32_bf16 v[6:9], v[208:211], v[200:203], v[6:9]
	v_mfma_f32_16x16x32_bf16 v[2:5], v[216:219], v[200:203], v[2:5]
	s_add_i32 s95, s95, 2
	s_add_u32 s4, s4, 0x100
	s_addc_u32 s5, s5, 0
	s_add_u32 vcc_hi, vcc_hi, 0x100
	s_addc_u32 s75, s75, 0
	s_cmp_gt_u32 s95, 13
	s_barrier
	s_cbranch_scc0 .LBB0_99

; #define LAS __attribute__((address_space(3)))
; DI float logsig(float z) { return fminf(z, 0.f) - __logf(1.f + __expf(-fabsf(z))); }
; DI void gla_gate_phase(int wv, LAS unsigned char* lds, const float* x, const float* w_in, const float* w2, const float* bg, const bf16_t* qk1,
;                        bf16_t* qd, bf16_t* ki, bf16_t* kst, float* decay, bf16_t* sbuf) {
;     ...
;         float cum = 0.f;
; #pragma unroll 4
;         for (int t = 0; t < 64; ++t) { float z = bc;
; #pragma unroll
;             for (int q = 0; q < 4; ++q) { const f32x4 gv = *(const LAS f32x4*)(gl + t * 16 + 4 * q); z += gv.x * w2c[4 * q] + gv.y * w2c[4 * q + 1] + gv.z * w2c[4 * q + 2] + gv.w * w2c[4 * q + 3]; }
;             cum += logsig(z) * 0.0625f; }
.LBB0_146:
	s_add_i32 s2, s1, 0
	s_add_i32 s3, s2, 0x10000
	v_mov_b32_e32 v2, s3
	s_add_i32 s3, s2, 0x10010
	v_mov_b32_e32 v6, s3
	ds_read_b128 v[2:5], v2
	ds_read_b128 v[6:9], v6
	s_add_i32 s3, s2, 0x10020
	s_addk_i32 s1, 0x100
	s_waitcnt lgkmcnt(1)
	v_mov_b32_e32 v10, v2
	s_waitcnt lgkmcnt(0)
	v_mov_b32_e32 v11, v6
	v_mov_b32_e32 v6, v3
	v_pk_mul_f32 v[2:3], v[22:23], v[6:7]
	v_mov_b32_e32 v6, v4
	v_pk_fma_f32 v[2:3], v[20:21], v[10:11], v[2:3]
	v_mov_b32_e32 v7, v8
	v_pk_fma_f32 v[2:3], v[24:25], v[6:7], v[2:3]
	v_mov_b32_e32 v8, v5
	v_pk_fma_f32 v[2:3], v[26:27], v[8:9], v[2:3]
	s_nop 0
	v_add_f32_e32 v2, v37, v2
	v_add_f32_e32 v12, v2, v3
	v_mov_b32_e32 v2, s3
	s_add_i32 s3, s2, 0x10030
	v_mov_b32_e32 v6, s3
	ds_read_b128 v[2:5], v2
	ds_read_b128 v[6:9], v6
	s_add_i32 s3, s2, 0x10040
	s_waitcnt lgkmcnt(1)
	v_mov_b32_e32 v10, v2
	s_waitcnt lgkmcnt(0)
	v_mov_b32_e32 v11, v6
	v_mov_b32_e32 v6, v3
	v_pk_mul_f32 v[2:3], v[30:31], v[6:7]
	v_mov_b32_e32 v6, v4
	v_pk_fma_f32 v[2:3], v[28:29], v[10:11], v[2:3]
	v_mov_b32_e32 v7, v8
	v_pk_fma_f32 v[2:3], v[32:33], v[6:7], v[2:3]
	v_mov_b32_e32 v8, v5
	v_pk_fma_f32 v[2:3], v[34:35], v[8:9], v[2:3]
	s_nop 0
	v_add_f32_e32 v2, v12, v2
	v_add_f32_e32 v2, v2, v3
	v_min_f32_e32 v3, 0, v2
	v_mul_f32_e64 v2, |v2|, s89
	v_exp_f32_e32 v2, v2
	s_nop 0
	v_add_f32_e32 v2, 1.0, v2
	v_cmp_gt_f32_e64 s[44:45], s90, v2
	s_nop 1
	v_cndmask_b32_e64 v4, 0, 32, s[44:45]
	v_ldexp_f32 v2, v2, v4
	v_log_f32_e32 v2, v2
	s_nop 0
	v_mul_f32_e32 v4, 0x3f317217, v2
	v_fma_f32 v4, v2, s91, -v4
	v_fmac_f32_e32 v4, 0x3377d1cf, v2
	v_fmac_f32_e32 v4, 0x3f317217, v2
	v_cmp_lt_f32_e64 vcc, |v2|, s92
	s_nop 1
	v_cndmask_b32_e32 v2, v2, v4, vcc
	v_cndmask_b32_e64 v4, 0, v245, s[44:45]
	v_sub_f32_e32 v2, v2, v4
	v_sub_f32_e32 v2, v3, v2
	v_fmac_f32_e32 v93, 0x3d800000, v2
	v_mov_b32_e32 v2, s3
	s_add_i32 s3, s2, 0x10050
	v_mov_b32_e32 v6, s3
	ds_read_b128 v[2:5], v2
	ds_read_b128 v[6:9], v6
	s_add_i32 s3, s2, 0x10060
	s_waitcnt lgkmcnt(1)
	v_mov_b32_e32 v10, v2
	s_waitcnt lgkmcnt(0)
	v_mov_b32_e32 v11, v6
	v_mov_b32_e32 v6, v3
	v_pk_mul_f32 v[2:3], v[22:23], v[6:7]
	v_mov_b32_e32 v6, v4
	v_pk_fma_f32 v[2:3], v[20:21], v[10:11], v[2:3]
	v_mov_b32_e32 v7, v8
	v_pk_fma_f32 v[2:3], v[24:25], v[6:7], v[2:3]
	v_mov_b32_e32 v8, v5
	v_pk_fma_f32 v[2:3], v[26:27], v[8:9], v[2:3]
	s_nop 0
	v_add_f32_e32 v2, v37, v2
	v_add_f32_e32 v12, v2, v3
	v_mov_b32_e32 v2, s3
	s_add_i32 s3, s2, 0x10070
	v_mov_b32_e32 v6, s3
	ds_read_b128 v[2:5], v2
	ds_read_b128 v[6:9], v6
	s_add_i32 s3, s2, 0x10080
	s_waitcnt lgkmcnt(1)
	v_mov_b32_e32 v10, v2
	s_waitcnt lgkmcnt(0)
	v_mov_b32_e32 v11, v6
	v_mov_b32_e32 v6, v3
	v_pk_mul_f32 v[2:3], v[30:31], v[6:7]
	v_mov_b32_e32 v6, v4
	v_pk_fma_f32 v[2:3], v[28:29], v[10:11], v[2:3]
	v_mov_b32_e32 v7, v8
	v_pk_fma_f32 v[2:3], v[32:33], v[6:7], v[2:3]
	v_mov_b32_e32 v8, v5
	v_pk_fma_f32 v[2:3], v[34:35], v[8:9], v[2:3]
	s_nop 0
	v_add_f32_e32 v2, v12, v2
	v_add_f32_e32 v2, v2, v3
	v_min_f32_e32 v3, 0, v2
	v_mul_f32_e64 v2, |v2|, s89
	v_exp_f32_e32 v2, v2
	s_nop 0
	v_add_f32_e32 v2, 1.0, v2
	v_cmp_gt_f32_e32 vcc, s90, v2
	s_nop 1
	v_cndmask_b32_e64 v4, 0, 32, vcc
	v_ldexp_f32 v2, v2, v4
	v_log_f32_e32 v2, v2
	s_nop 0
	v_mul_f32_e32 v4, 0x3f317217, v2
	v_fma_f32 v4, v2, s91, -v4
	v_fmac_f32_e32 v4, 0x3377d1cf, v2
	v_fmac_f32_e32 v4, 0x3f317217, v2
	v_cmp_lt_f32_e64 s[44:45], |v2|, s92
	s_nop 1
	v_cndmask_b32_e64 v2, v2, v4, s[44:45]
	v_cndmask_b32_e32 v4, 0, v245, vcc
	v_sub_f32_e32 v2, v2, v4
	v_sub_f32_e32 v2, v3, v2
	v_fmac_f32_e32 v93, 0x3d800000, v2
	v_mov_b32_e32 v2, s3
	s_add_i32 s3, s2, 0x10090
	v_mov_b32_e32 v6, s3
	ds_read_b128 v[2:5], v2
	ds_read_b128 v[6:9], v6
	s_add_i32 s3, s2, 0x100a0
	s_waitcnt lgkmcnt(1)
	v_mov_b32_e32 v10, v2
	s_waitcnt lgkmcnt(0)
	v_mov_b32_e32 v11, v6
	v_mov_b32_e32 v6, v3
	v_pk_mul_f32 v[2:3], v[22:23], v[6:7]
	v_mov_b32_e32 v6, v4
	v_pk_fma_f32 v[2:3], v[20:21], v[10:11], v[2:3]
	v_mov_b32_e32 v7, v8
	v_pk_fma_f32 v[2:3], v[24:25], v[6:7], v[2:3]
	v_mov_b32_e32 v8, v5
	v_pk_fma_f32 v[2:3], v[26:27], v[8:9], v[2:3]
	s_nop 0
	v_add_f32_e32 v2, v37, v2
	v_add_f32_e32 v12, v2, v3
	v_mov_b32_e32 v2, s3
	s_add_i32 s3, s2, 0x100b0
	v_mov_b32_e32 v6, s3
	ds_read_b128 v[2:5], v2
	ds_read_b128 v[6:9], v6
	s_add_i32 s3, s2, 0x100c0
	s_waitcnt lgkmcnt(1)
	v_mov_b32_e32 v10, v2
	s_waitcnt lgkmcnt(0)
	v_mov_b32_e32 v11, v6
	v_mov_b32_e32 v6, v3
	v_pk_mul_f32 v[2:3], v[30:31], v[6:7]
	v_mov_b32_e32 v6, v4
	v_pk_fma_f32 v[2:3], v[28:29], v[10:11], v[2:3]
	v_mov_b32_e32 v7, v8
	v_pk_fma_f32 v[2:3], v[32:33], v[6:7], v[2:3]
	v_mov_b32_e32 v8, v5
	v_pk_fma_f32 v[2:3], v[34:35], v[8:9], v[2:3]
	s_nop 0
	v_add_f32_e32 v2, v12, v2
	v_add_f32_e32 v2, v2, v3
	v_min_f32_e32 v3, 0, v2
	v_mul_f32_e64 v2, |v2|, s89
	v_exp_f32_e32 v2, v2
	s_nop 0
	v_add_f32_e32 v2, 1.0, v2
	v_cmp_gt_f32_e32 vcc, s90, v2
	s_nop 1
	v_cndmask_b32_e64 v4, 0, 32, vcc
	v_ldexp_f32 v2, v2, v4
	v_log_f32_e32 v2, v2
	s_nop 0
	v_mul_f32_e32 v4, 0x3f317217, v2
	v_fma_f32 v4, v2, s91, -v4
	v_fmac_f32_e32 v4, 0x3377d1cf, v2
	v_fmac_f32_e32 v4, 0x3f317217, v2
	v_cmp_lt_f32_e64 s[44:45], |v2|, s92
	s_nop 1
	v_cndmask_b32_e64 v2, v2, v4, s[44:45]
	v_cndmask_b32_e32 v4, 0, v245, vcc
	v_sub_f32_e32 v2, v2, v4
	v_sub_f32_e32 v2, v3, v2
	v_fmac_f32_e32 v93, 0x3d800000, v2
	v_mov_b32_e32 v2, s3
	s_add_i32 s3, s2, 0x100d0
	v_mov_b32_e32 v6, s3
	ds_read_b128 v[2:5], v2
	ds_read_b128 v[6:9], v6
	s_add_i32 s3, s2, 0x100e0
	s_add_i32 s2, s2, 0x100f0
	s_cmpk_lg_i32 s1, 0x1000
	s_waitcnt lgkmcnt(1)
	v_mov_b32_e32 v10, v2
	s_waitcnt lgkmcnt(0)
	v_mov_b32_e32 v11, v6
	v_mov_b32_e32 v6, v3
	v_pk_mul_f32 v[2:3], v[22:23], v[6:7]
	v_mov_b32_e32 v6, v4
	v_pk_fma_f32 v[2:3], v[20:21], v[10:11], v[2:3]
	v_mov_b32_e32 v7, v8
	v_pk_fma_f32 v[2:3], v[24:25], v[6:7], v[2:3]
	v_mov_b32_e32 v8, v5
	v_pk_fma_f32 v[2:3], v[26:27], v[8:9], v[2:3]
	v_mov_b32_e32 v6, s2
	v_add_f32_e32 v2, v37, v2
	v_add_f32_e32 v12, v2, v3
	v_mov_b32_e32 v2, s3
	ds_read_b128 v[2:5], v2
	ds_read_b128 v[6:9], v6
	s_waitcnt lgkmcnt(1)
	v_mov_b32_e32 v10, v2
	s_waitcnt lgkmcnt(0)
	v_mov_b32_e32 v11, v6
	v_mov_b32_e32 v6, v3
	v_pk_mul_f32 v[2:3], v[30:31], v[6:7]
	v_mov_b32_e32 v6, v4
	v_pk_fma_f32 v[2:3], v[28:29], v[10:11], v[2:3]
	v_mov_b32_e32 v7, v8
	v_pk_fma_f32 v[2:3], v[32:33], v[6:7], v[2:3]
	v_mov_b32_e32 v8, v5
	v_pk_fma_f32 v[2:3], v[34:35], v[8:9], v[2:3]
	s_nop 0
	v_add_f32_e32 v2, v12, v2
	v_add_f32_e32 v2, v2, v3
	v_min_f32_e32 v3, 0, v2
	v_mul_f32_e64 v2, |v2|, s89
	v_exp_f32_e32 v2, v2
	s_nop 0
	v_add_f32_e32 v2, 1.0, v2
	v_cmp_gt_f32_e32 vcc, s90, v2
	s_nop 1
	v_cndmask_b32_e64 v4, 0, 32, vcc
	v_ldexp_f32 v2, v2, v4
	v_log_f32_e32 v2, v2
	s_nop 0
	v_mul_f32_e32 v4, 0x3f317217, v2
	v_fma_f32 v4, v2, s91, -v4
	v_fmac_f32_e32 v4, 0x3377d1cf, v2
	v_fmac_f32_e32 v4, 0x3f317217, v2
	v_cmp_lt_f32_e64 s[44:45], |v2|, s92
	s_nop 1
	v_cndmask_b32_e64 v2, v2, v4, s[44:45]
	v_cndmask_b32_e32 v4, 0, v245, vcc
	v_sub_f32_e32 v2, v2, v4
	v_sub_f32_e32 v2, v3, v2
	v_fmac_f32_e32 v93, 0x3d800000, v2
	s_cbranch_scc1 .LBB0_146
; DI void gla_gate_phase(int wv, LAS unsigned char* lds, const float* x, const float* w_in, const float* w2, const float* bg, const bf16_t* qk1,
;                        bf16_t* qd, bf16_t* ki, bf16_t* kst, float* decay, bf16_t* sbuf) {
;     ...
;         const float blast = cum;
;         decay[((size_t)b * 64 + ch) * 512 + c] = __expf(blast);
;         cum = 0.f;
;         for (int t8 = 0; t8 < 64; t8 += 8) {
	s_lshl_b32 s1, s0, 17
	s_lshl_b32 s2, s0, 15
	s_lshl_b32 s3, s0, 16
	s_lshl_b32 s5, s0, 7
	s_and_b32 s0, s7, 63
	s_lshl_b64 s[44:45], s[84:85], 17
	v_readlane_b32 s6, v253, 52
	s_add_u32 s6, s6, s44
	v_readlane_b32 s44, v253, 53
	s_addc_u32 s45, s44, s45
	s_lshl_b32 s44, s0, 11
	v_mul_f32_e32 v2, 0x3fb8aa3b, v93
	s_add_u32 s44, s6, s44
	v_exp_f32_e32 v4, v2
	s_addc_u32 s45, s45, 0
	s_lshl_b64 s[82:83], s[84:85], 23
	s_or_b32 s82, s82, s1
	v_lshl_add_u64 v[6:7], s[82:83], 0, v[84:85]
	s_lshl_b64 s[82:83], s[84:85], 21
	v_lshl_add_u64 v[2:3], v[18:19], 2, s[44:45]
	s_or_b32 s82, s82, s2
	global_store_dword v[2:3], v4, off
	v_lshl_add_u64 v[2:3], s[82:83], 0, v[18:19]
	v_readlane_b32 s82, v253, 58
	s_lshl_b64 s[44:45], s[84:85], 22
	v_lshlrev_b64 v[2:3], 1, v[2:3]
	v_readlane_b32 s83, v253, 59
	v_mov_b32_e32 v95, 0
	s_mov_b32 s1, -8
	v_lshl_add_u64 v[8:9], s[82:83], 0, v[2:3]
	s_or_b32 s82, s44, s3
	v_readlane_b32 s2, v253, 62
	s_mov_b32 s83, s45
	v_readlane_b32 s3, v253, 63
	s_or_b32 s44, s44, s5
	v_lshl_add_u64 v[10:11], s[82:83], 0, v[86:87]
	v_lshl_add_u64 v[12:13], s[82:83], 0, v[88:89]
	v_lshl_add_u64 v[14:15], s[2:3], 0, v[2:3]
	v_lshl_add_u64 v[16:17], s[44:45], 0, v[90:91]
	s_mov_b32 s6, s4
	.p2align 6

; #define LAS __attribute__((address_space(3)))
; DI f32x16 zero16() { f32x16 z; for (int i = 0; i < 16; ++i) z[i] = 0.f; return z; }
; DI void diff_attn_phase(int wv, LAS unsigned char* lds, const bf16_t* qk, const bf16_t* vt, bf16_t* ob, const float* lq1, const float* lk1, const float* lq2, const float* lk2,
;                         const float* subg, int layer_idx) {
;     ...
;         const float slope2 = exp2f(-(float)(hd + 1)) * LOG2E;
;         const bf16_t* qkb = qk + (size_t)b * SEQ * 2048;
;         LAS unsigned char* qlds = lds + 2 * DA_BUF + wid * 4096 + lane * 16;
; #pragma unroll
;         for (int ks = 0; ks < 4; ++ks) *(LAS bf16x8*)(qlds + ks * 1024) = *(const bf16x8*)(qkb + (size_t)(q0 + rr) * 2048 + hd * 128 + map * 64 + ks * 16 + hh * 8);
;         const bf16_t* kg = qkb + 1024 + hd * 128 + kch * 8 + (size_t)krow0 * 2048;
;         const bf16_t* vg = vt + (size_t)(hd * 128 + vrow0) * M_TOK + (size_t)b * SEQ + vch * 8;
;         float cb[16];
; #pragma unroll
;         for (int i = 0; i < 16; ++i) cb[i] = slope2 * (float)((i & 7) + 16 * (i >> 3));
;         f32x16 O[4];
; #pragma unroll
;         for (int d = 0; d < 4; ++d) O[d] = zero16();
;         float m = -INFINITY, l = 0.f;
;         if (!have_pf) {
; #pragma unroll
;             for (int i = 0; i < 2; ++i) { gk[i] = *(const u32x4*)(kg + (size_t)i * 32 * 2048); gv[i] = *(const u32x4*)(vg + (size_t)i * 64 * M_TOK); } }
; #pragma unroll
;         for (int i = 0; i < 2; ++i) { *(LAS u32x4*)(lds + kst_off + i * 32 * DA_KP) = gk[i]; *(LAS u32x4*)(lds + vst_off + i * 64 * DA_VP) = gv[i]; }
;         __syncthreads();
;         const int tmain = 2 * qb;
.LBB0_422:
	s_add_i32 s16, s16, 1
	v_cvt_f32_ubyte0_e32 v0, s16
	s_mov_b32 s2, 0x42fc0000
	v_cmp_lt_f32_e32 vcc, s2, v0
	s_and_b64 s[16:17], vcc, exec
	s_cselect_b32 s2, 0xffffffc0, 0
	v_cndmask_b32_e32 v2, 0, v247, vcc
	v_sub_f32_e32 v0, v2, v0
	v_exp_f32_e32 v0, v0
	v_add_u32_e32 v163, 0, v167
	v_add_u32_e32 v165, 0, v208
	s_cmp_lg_u32 s15, 0
	v_ldexp_f32 v0, v0, s2
	s_mov_b32 s2, 2.0
	v_mul_f32_e32 v160, 0x3fb8aa3b, v0
	s_mov_b32 s3, 0x40400000
	v_pk_mul_f32 v[188:189], v[160:161], s[2:3] op_sel_hi:[0,1]
	s_mov_b32 s2, 4.0
	s_mov_b32 s3, 0x40a00000
	v_pk_mul_f32 v[186:187], v[160:161], s[2:3] op_sel_hi:[0,1]
	s_mov_b32 s2, 0x40c00000
	s_mov_b32 s3, 0x40e00000
	v_pk_mul_f32 v[184:185], v[160:161], s[2:3] op_sel_hi:[0,1]
	s_mov_b32 s2, 0x41800000
	s_mov_b32 s3, 0x41880000
	v_pk_mul_f32 v[182:183], v[160:161], s[2:3] op_sel_hi:[0,1]
	s_mov_b32 s2, 0x41900000
	s_mov_b32 s3, 0x41980000
	v_pk_mul_f32 v[180:181], v[160:161], s[2:3] op_sel_hi:[0,1]
	s_mov_b32 s2, 0x41a00000
	s_mov_b32 s3, 0x41a80000
	v_pk_mul_f32 v[178:179], v[160:161], s[2:3] op_sel_hi:[0,1]
	s_mov_b32 s2, 0x41b00000
	s_mov_b32 s3, 0x41b80000
	v_mul_f32_e32 v192, 0, v160
	v_pk_mul_f32 v[176:177], v[160:161], s[2:3] op_sel_hi:[0,1]
	v_mul_f32_e32 v119, 0x42000000, v160
	s_waitcnt vmcnt(3)
	ds_write_b128 v163, v[102:105]
	s_waitcnt vmcnt(2)
	ds_write_b128 v165, v[98:101] offset:17408
	s_waitcnt vmcnt(1)
	ds_write_b128 v163, v[106:109] offset:8704
	s_waitcnt vmcnt(0)
	ds_write_b128 v165, v[110:113] offset:26624
	s_waitcnt lgkmcnt(0)
	s_barrier
	s_cbranch_scc0 .LBB0_439
	s_lshr_b32 s3, s1, 2
	s_lshl_b32 s2, s14, 1
	s_lshl_b32 s1, s3, 3
	s_sub_i32 s1, s2, s1
	v_lshl_add_u32 v0, s3, 9, v216
	s_lshl_b32 s2, s14, 7
	v_mov_b32_e32 v159, 0
	v_mul_f32_e32 v157, 0x42000000, v160
	s_add_i32 s1, s1, 56
	v_subrev_u32_e32 v120, s2, v0
	v_mov_b32_e32 v218, 0xff800000
	s_mov_b32 s16, 0
	s_mov_b32 s25, 0
	v_mov_b32_e32 v50, 0
	v_mov_b32_e32 v51, v159
	v_mov_b32_e32 v52, v159
	v_mov_b32_e32 v53, v159
	v_mov_b32_e32 v54, v159
	v_mov_b32_e32 v55, v159
	v_mov_b32_e32 v56, v159
	v_mov_b32_e32 v57, v159
	v_mov_b32_e32 v58, v159
	v_mov_b32_e32 v59, v159
	v_mov_b32_e32 v60, v159
	v_mov_b32_e32 v61, v159
	v_mov_b32_e32 v62, v159
	v_mov_b32_e32 v63, v159
	v_mov_b32_e32 v64, v159
	v_mov_b32_e32 v65, v159
	v_mov_b32_e32 v34, 0
	v_mov_b32_e32 v35, v159
	v_mov_b32_e32 v36, v159
	v_mov_b32_e32 v37, v159
	v_mov_b32_e32 v38, v159
	v_mov_b32_e32 v39, v159
	v_mov_b32_e32 v40, v159
	v_mov_b32_e32 v41, v159
	v_mov_b32_e32 v42, v159
	v_mov_b32_e32 v43, v159
	v_mov_b32_e32 v44, v159
	v_mov_b32_e32 v45, v159
	v_mov_b32_e32 v46, v159
	v_mov_b32_e32 v47, v159
	v_mov_b32_e32 v48, v159
	v_mov_b32_e32 v49, v159
	v_mov_b32_e32 v18, 0
	v_mov_b32_e32 v19, v159
	v_mov_b32_e32 v20, v159
	v_mov_b32_e32 v21, v159
	v_mov_b32_e32 v22, v159
	v_mov_b32_e32 v23, v159
	v_mov_b32_e32 v24, v159
	v_mov_b32_e32 v25, v159
	v_mov_b32_e32 v26, v159
	v_mov_b32_e32 v27, v159
	v_mov_b32_e32 v28, v159
	v_mov_b32_e32 v29, v159
	v_mov_b32_e32 v30, v159
	v_mov_b32_e32 v31, v159
	v_mov_b32_e32 v32, v159
	v_mov_b32_e32 v33, v159
	v_mov_b32_e32 v2, 0
	v_mov_b32_e32 v3, v159
	v_mov_b32_e32 v4, v159
	v_mov_b32_e32 v5, v159
	v_mov_b32_e32 v6, v159
	v_mov_b32_e32 v7, v159
	v_mov_b32_e32 v8, v159
	v_mov_b32_e32 v9, v159
	v_mov_b32_e32 v10, v159
	v_mov_b32_e32 v11, v159
	v_mov_b32_e32 v12, v159
	v_mov_b32_e32 v13, v159
	v_mov_b32_e32 v14, v159
	v_mov_b32_e32 v15, v159
	v_mov_b32_e32 v16, v159
	v_mov_b32_e32 v17, v159
	.p2align 6

; #define PG8_STAGE(bufoff, gbase, voff) do { _Pragma("unroll") for (int _i = 0; _i < 2; ++_i) \
;         __builtin_amdgcn_global_load_lds((const unsigned*)((const char*)(gbase) + (voff)[_i]), (LAS unsigned*)(lds + (bufoff) + ldsw + _i * 8192), 16, 0, 0); } while (0)
; #define PG8_LDA(dst, b, h) do { _Pragma("unroll") for (int m = 0; m < 4; ++m) _Pragma("unroll") for (int k = 0; k < 2; ++k) dst[m][k] = *(const LAS bf16x8*)(lds + PG8_SA(b, h) + aoff + m * 2048 + k * 1024); } while (0)
; #define PG8_LDB(dst, b, h) do { _Pragma("unroll") for (int n = 0; n < 2; ++n) _Pragma("unroll") for (int k = 0; k < 2; ++k) dst[n][k] = *(const LAS bf16x8*)(lds + PG8_SB(b, h) + boff + n * 2048 + k * 1024); } while (0)
; #define PG8_MMA(ai, bj, At, Bt) do { __builtin_amdgcn_s_setprio(1); _Pragma("unroll") for (int m = 0; m < 4; ++m) _Pragma("unroll") for (int n = 0; n < 2; ++n) _Pragma("unroll") for (int k = 0; k < 2; ++k) \
;         acc[ai][bj][m][n] = __builtin_amdgcn_mfma_f32_16x16x32_bf16(Bt[n][k], At[m][k], acc[ai][bj][m][n], 0, 0, 0); __builtin_amdgcn_s_setprio(0); } while (0)
; #define PG8_WAIT_L(n) asm volatile("s_waitcnt lgkmcnt(" #n ")" ::: "memory")
; template <class Epi>
; DI void gemm_phase(int wv, LAS unsigned char* lds, const GemmD g, const Epi& E) {
;     ...
;         const bool has_next = S.next(ui + 1, nxt);
;         const char* nA = has_next ? (const char*)g.A + (size_t)nxt.pm * 256 * g.lda * 2 : cA; const char* nB = has_next ? (const char*)g.Bt + PG8_BROW(nxt.pn) * (size_t)g.ldb * 2 : cB;
;         for (int t = 0; t < nt; t += 2) {
;             const bool last = (t == nt - 2);
;             const char* a1 = cA + (size_t)(t + 1) * kstep;
;             const char* a2 = last ? nA : cA + (size_t)(t + 2) * kstep; const char* b2 = last ? nB : cB + (size_t)(t + 2) * kstep;
;             const char* a3 = a2 + kstep; const char* b3 = b2 + kstep;
;             PG8_LDB(B0, 0, 0); PG8_SCHED; PG8_LDA(At, 0, 0); PG8_STAGE(PG8_SA(1, 1), a1 + hstepA, voffA);
;             PG8_WAIT_L(8); PG8_BAR; PG8_WAIT_L(0); PG8_MMA(0, 0, At, B0); PG8_BAR; PG8_SCHED;
;             PG8_LDB(B1, 0, 1); PG8_STAGE(PG8_SB(0, 0), b2, voffB);
;             PG8_BAR; PG8_WAIT_L(0); PG8_MMA(0, 1, At, B1); PG8_BAR;
;             PG8_LDA(At, 0, 1); PG8_STAGE(PG8_SA(0, 0), a2, voffA);
;             PG8_BAR; PG8_WAIT_L(0); PG8_MMA(1, 0, At, B0); PG8_BAR; PG8_SCHED;
.LBB0_489:
	s_ashr_i32 s7, s6, 31
	v_cmp_lt_i64_e32 vcc, s[8:9], v[228:229]
	s_lshl_b64 s[8:9], s[6:7], 19
	s_add_u32 s8, s76, s8
	s_addc_u32 s9, s78, s9
	s_and_b64 s[16:17], vcc, exec
	s_cselect_b32 s7, s9, s27
	s_cselect_b32 s13, s8, s26
	s_lshl_b32 s16, s86, 8
	s_ashr_i32 s17, s16, 31
	s_lshl_b64 s[16:17], s[16:17], 11
	s_add_u32 s22, s39, s16
	s_addc_u32 s23, s40, s17
	s_and_b64 s[16:17], vcc, exec
	s_cselect_b32 s16, s23, s29
	s_cselect_b32 s17, s22, s28
	s_add_u32 s26, s26, 0x40080
	s_addc_u32 s27, s27, 0
	s_add_u32 s36, s28, 0x100
	s_addc_u32 s38, s29, 0
	s_mov_b32 s41, -2
	s_add_u32 s2, s26, 0xfffc0080
	s_addc_u32 s3, s27, -1
	s_add_i32 s18, 0, 0x10000
	v_add_u32_e32 v140, s18, v144
	ds_read_b128 v[148:151], v140
	ds_read_b128 v[152:155], v140 offset:1024
	ds_read_b128 v[156:159], v140 offset:2048
	ds_read_b128 v[160:163], v140 offset:3072
	s_cmp_eq_u32 s41, 12
	s_cselect_b32 s31, s7, s3
	s_cselect_b32 s30, s13, s2
	s_cselect_b32 s29, s16, s38
	s_cselect_b32 s28, s17, s36
	v_lshl_add_u64 v[140:141], s[26:27], 0, v[136:137]
	s_add_i32 m0, s25, 0xc000
	ds_read_b128 v[168:171], v146
	ds_read_b128 v[176:179], v146 offset:1024
	ds_read_b128 v[180:183], v146 offset:2048
	ds_read_b128 v[184:187], v146 offset:3072
	ds_read_b128 v[188:191], v146 offset:4096
	ds_read_b128 v[192:195], v146 offset:5120
	ds_read_b128 v[196:199], v146 offset:6144
	ds_read_b128 v[200:203], v146 offset:7168
	global_load_lds_dwordx4 v[140:141], off
	v_lshl_add_u64 v[140:141], s[26:27], 0, v[138:139]
	s_add_i32 m0, s25, 0xe000
	s_nop 0
	global_load_lds_dwordx4 v[140:141], off
	s_waitcnt lgkmcnt(8)
	s_barrier
	s_waitcnt lgkmcnt(0)
	s_waitcnt lgkmcnt(0)
	s_nop 0
	v_mfma_f32_16x16x32_bf16 v[126:129], v[148:151], v[168:171], 0
	v_mfma_f32_16x16x32_bf16 v[122:125], v[156:159], v[168:171], 0
	v_mfma_f32_16x16x32_bf16 v[110:113], v[148:151], v[180:183], 0
	v_mfma_f32_16x16x32_bf16 v[106:109], v[156:159], v[180:183], 0
	v_mfma_f32_16x16x32_bf16 v[94:97], v[148:151], v[188:191], 0
	v_mfma_f32_16x16x32_bf16 v[90:93], v[156:159], v[188:191], 0
	v_mfma_f32_16x16x32_bf16 v[78:81], v[148:151], v[196:199], 0
	v_mfma_f32_16x16x32_bf16 v[74:77], v[156:159], v[196:199], 0
	v_mfma_f32_16x16x32_bf16 v[126:129], v[152:155], v[176:179], v[126:129]
	v_mfma_f32_16x16x32_bf16 v[122:125], v[160:163], v[176:179], v[122:125]
	v_mfma_f32_16x16x32_bf16 v[110:113], v[152:155], v[184:187], v[110:113]
	v_mfma_f32_16x16x32_bf16 v[106:109], v[160:163], v[184:187], v[106:109]
	v_mfma_f32_16x16x32_bf16 v[94:97], v[152:155], v[192:195], v[94:97]
	v_mfma_f32_16x16x32_bf16 v[90:93], v[160:163], v[192:195], v[90:93]
	v_mfma_f32_16x16x32_bf16 v[78:81], v[152:155], v[200:203], v[78:81]
	v_mfma_f32_16x16x32_bf16 v[74:77], v[160:163], v[200:203], v[74:77]
	s_barrier
	s_add_i32 s2, 0, 0x14000
	v_add_u32_e32 v140, s2, v144
	s_add_i32 s3, s18, s79
	ds_read_b128 v[204:207], v140
	ds_read_b128 v[208:211], v140 offset:1024
	ds_read_b128 v[212:215], v140 offset:2048
	ds_read_b128 v[216:219], v140 offset:3072
	v_lshl_add_u64 v[140:141], s[28:29], 0, v[0:1]
	s_mov_b32 m0, s3
	v_lshl_add_u64 v[164:165], s[28:29], 0, v[134:135]
	global_load_lds_dwordx4 v[140:141], off
	s_add_i32 m0, s3, 0x2000
	s_nop 0
	global_load_lds_dwordx4 v[164:165], off
	s_barrier
	s_waitcnt lgkmcnt(0)
	s_waitcnt lgkmcnt(0)
	v_mfma_f32_16x16x32_bf16 v[118:121], v[204:207], v[168:171], 0
	v_mfma_f32_16x16x32_bf16 v[114:117], v[212:215], v[168:171], 0
	v_mfma_f32_16x16x32_bf16 v[102:105], v[204:207], v[180:183], 0
	v_mfma_f32_16x16x32_bf16 v[98:101], v[212:215], v[180:183], 0
	v_mfma_f32_16x16x32_bf16 v[86:89], v[204:207], v[188:191], 0
	v_mfma_f32_16x16x32_bf16 v[82:85], v[212:215], v[188:191], 0
	v_mfma_f32_16x16x32_bf16 v[70:73], v[204:207], v[196:199], 0
	v_mfma_f32_16x16x32_bf16 v[66:69], v[212:215], v[196:199], 0
	v_mfma_f32_16x16x32_bf16 v[118:121], v[208:211], v[176:179], v[118:121]
	v_mfma_f32_16x16x32_bf16 v[114:117], v[216:219], v[176:179], v[114:117]
	v_mfma_f32_16x16x32_bf16 v[102:105], v[208:211], v[184:187], v[102:105]
	v_mfma_f32_16x16x32_bf16 v[98:101], v[216:219], v[184:187], v[98:101]
	v_mfma_f32_16x16x32_bf16 v[86:89], v[208:211], v[192:195], v[86:89]
	v_mfma_f32_16x16x32_bf16 v[82:85], v[216:219], v[192:195], v[82:85]
	v_mfma_f32_16x16x32_bf16 v[70:73], v[208:211], v[200:203], v[70:73]
	v_mfma_f32_16x16x32_bf16 v[66:69], v[216:219], v[200:203], v[66:69]
	s_mov_b32 m0, s25
	v_lshl_add_u64 v[220:221], s[30:31], 0, v[130:131]
	s_barrier
	ds_read_b128 v[168:171], v146 offset:16384
	ds_read_b128 v[176:179], v146 offset:17408
	ds_read_b128 v[180:183], v146 offset:18432
	ds_read_b128 v[184:187], v146 offset:19456
	ds_read_b128 v[188:191], v146 offset:20480
	ds_read_b128 v[192:195], v146 offset:21504
	ds_read_b128 v[196:199], v146 offset:22528
	ds_read_b128 v[200:203], v146 offset:23552
	global_load_lds_dwordx4 v[220:221], off
	v_lshl_add_u64 v[222:223], s[30:31], 0, v[132:133]
	s_mov_b32 m0, s80
	s_nop 0
	global_load_lds_dwordx4 v[222:223], off
	s_barrier
	s_waitcnt lgkmcnt(0)
	s_waitcnt lgkmcnt(0)
	s_nop 0
	v_mfma_f32_16x16x32_bf16 v[62:65], v[148:151], v[168:171], 0
	v_mfma_f32_16x16x32_bf16 v[58:61], v[156:159], v[168:171], 0
	v_mfma_f32_16x16x32_bf16 v[46:49], v[148:151], v[180:183], 0
	v_mfma_f32_16x16x32_bf16 v[42:45], v[156:159], v[180:183], 0
	v_mfma_f32_16x16x32_bf16 v[30:33], v[148:151], v[188:191], 0
	v_mfma_f32_16x16x32_bf16 v[26:29], v[156:159], v[188:191], 0
	v_mfma_f32_16x16x32_bf16 v[14:17], v[148:151], v[196:199], 0
	v_mfma_f32_16x16x32_bf16 v[10:13], v[156:159], v[196:199], 0
	v_mfma_f32_16x16x32_bf16 v[62:65], v[152:155], v[176:179], v[62:65]
	v_mfma_f32_16x16x32_bf16 v[58:61], v[160:163], v[176:179], v[58:61]
	v_mfma_f32_16x16x32_bf16 v[46:49], v[152:155], v[184:187], v[46:49]
	v_mfma_f32_16x16x32_bf16 v[42:45], v[160:163], v[184:187], v[42:45]
	v_mfma_f32_16x16x32_bf16 v[30:33], v[152:155], v[192:195], v[30:33]
	v_mfma_f32_16x16x32_bf16 v[26:29], v[160:163], v[192:195], v[26:29]
	v_mfma_f32_16x16x32_bf16 v[14:17], v[152:155], v[200:203], v[14:17]
	v_mfma_f32_16x16x32_bf16 v[10:13], v[160:163], v[200:203], v[10:13]
	s_barrier
; #define PG8_STAGE(bufoff, gbase, voff) do { _Pragma("unroll") for (int _i = 0; _i < 2; ++_i) \
;         __builtin_amdgcn_global_load_lds((const unsigned*)((const char*)(gbase) + (voff)[_i]), (LAS unsigned*)(lds + (bufoff) + ldsw + _i * 8192), 16, 0, 0); } while (0)
; #define PG8_LDA(dst, b, h) do { _Pragma("unroll") for (int m = 0; m < 4; ++m) _Pragma("unroll") for (int k = 0; k < 2; ++k) dst[m][k] = *(const LAS bf16x8*)(lds + PG8_SA(b, h) + aoff + m * 2048 + k * 1024); } while (0)
; #define PG8_LDB(dst, b, h) do { _Pragma("unroll") for (int n = 0; n < 2; ++n) _Pragma("unroll") for (int k = 0; k < 2; ++k) dst[n][k] = *(const LAS bf16x8*)(lds + PG8_SB(b, h) + boff + n * 2048 + k * 1024); } while (0)
; #define PG8_MMA(ai, bj, At, Bt) do { __builtin_amdgcn_s_setprio(1); _Pragma("unroll") for (int m = 0; m < 4; ++m) _Pragma("unroll") for (int n = 0; n < 2; ++n) _Pragma("unroll") for (int k = 0; k < 2; ++k) \
;         acc[ai][bj][m][n] = __builtin_amdgcn_mfma_f32_16x16x32_bf16(Bt[n][k], At[m][k], acc[ai][bj][m][n], 0, 0, 0); __builtin_amdgcn_s_setprio(0); } while (0)
; #define PG8_WAIT_V(n) asm volatile("s_waitcnt vmcnt(" #n ")" ::: "memory")
; #define PG8_WAIT_L(n) asm volatile("s_waitcnt lgkmcnt(" #n ")" ::: "memory")
; #define PG8_BAR __builtin_amdgcn_s_barrier()
; #define PG8_SCHED __builtin_amdgcn_sched_barrier(0)
; template <class Epi>
; DI void gemm_phase(int wv, LAS unsigned char* lds, const GemmD g, const Epi& E) {
;     ...
;             PG8_STAGE(PG8_SB(0, 1), b2 + hstepB, voffB);
;             PG8_WAIT_V(6); PG8_BAR; PG8_MMA(1, 1, At, B1); PG8_BAR;
;             PG8_LDB(B0, 1, 0); PG8_SCHED; PG8_LDA(At, 1, 0); PG8_STAGE(PG8_SA(0, 1), a2 + hstepA, voffA);
;             PG8_WAIT_L(8); PG8_BAR; PG8_WAIT_L(0); PG8_MMA(0, 0, At, B0); PG8_BAR; PG8_SCHED;
;             PG8_LDB(B1, 1, 1); PG8_STAGE(PG8_SB(1, 0), b3, voffB);
;             PG8_BAR; PG8_WAIT_L(0); PG8_MMA(0, 1, At, B1); PG8_BAR;
;             PG8_LDA(At, 1, 1); PG8_STAGE(PG8_SA(1, 0), a3, voffA);
	s_add_u32 s18, s28, 0x40000
	s_addc_u32 s19, s29, 0
	s_add_i32 s2, s2, s79
	v_lshl_add_u64 v[148:149], s[18:19], 0, v[0:1]
	s_mov_b32 m0, s2
	s_nop 0
	global_load_lds_dwordx4 v[148:149], off
	v_lshl_add_u64 v[148:149], s[18:19], 0, v[134:135]
	s_add_i32 m0, s2, 0x2000
	s_nop 0
	global_load_lds_dwordx4 v[148:149], off
	s_waitcnt vmcnt(6)
	s_barrier
	v_mfma_f32_16x16x32_bf16 v[54:57], v[204:207], v[168:171], 0
	v_mfma_f32_16x16x32_bf16 v[50:53], v[212:215], v[168:171], 0
	v_mfma_f32_16x16x32_bf16 v[38:41], v[204:207], v[180:183], 0
	v_mfma_f32_16x16x32_bf16 v[34:37], v[212:215], v[180:183], 0
	v_mfma_f32_16x16x32_bf16 v[22:25], v[204:207], v[188:191], 0
	v_mfma_f32_16x16x32_bf16 v[18:21], v[212:215], v[188:191], 0
	v_mfma_f32_16x16x32_bf16 v[6:9], v[204:207], v[196:199], 0
	v_mfma_f32_16x16x32_bf16 v[2:5], v[212:215], v[196:199], 0
	v_mfma_f32_16x16x32_bf16 v[54:57], v[208:211], v[176:179], v[54:57]
	v_mfma_f32_16x16x32_bf16 v[50:53], v[216:219], v[176:179], v[50:53]
	v_mfma_f32_16x16x32_bf16 v[38:41], v[208:211], v[184:187], v[38:41]
	v_mfma_f32_16x16x32_bf16 v[34:37], v[216:219], v[184:187], v[34:37]
	v_mfma_f32_16x16x32_bf16 v[22:25], v[208:211], v[192:195], v[22:25]
	v_mfma_f32_16x16x32_bf16 v[18:21], v[216:219], v[192:195], v[18:21]
	v_mfma_f32_16x16x32_bf16 v[6:9], v[208:211], v[200:203], v[6:9]
	v_mfma_f32_16x16x32_bf16 v[2:5], v[216:219], v[200:203], v[2:5]
	s_add_i32 s2, 0, 0x18000
	v_add_u32_e32 v147, s2, v144
	s_barrier
	ds_read_b128 v[148:151], v147
	ds_read_b128 v[152:155], v147 offset:1024
	ds_read_b128 v[156:159], v147 offset:2048
	ds_read_b128 v[160:163], v147 offset:3072
	s_add_u32 s18, s30, 0x40000
	s_addc_u32 s19, s31, 0
	s_mov_b32 m0, s81
	v_lshl_add_u64 v[204:205], s[18:19], 0, v[130:131]
	ds_read_b128 v[168:171], v146 offset:32768
	ds_read_b128 v[176:179], v146 offset:33792
	ds_read_b128 v[180:183], v146 offset:34816
	ds_read_b128 v[184:187], v146 offset:35840
	ds_read_b128 v[188:191], v146 offset:36864
	ds_read_b128 v[192:195], v146 offset:37888
	ds_read_b128 v[196:199], v146 offset:38912
	ds_read_b128 v[200:203], v146 offset:39936
	global_load_lds_dwordx4 v[204:205], off
	v_lshl_add_u64 v[204:205], s[18:19], 0, v[132:133]
	s_mov_b32 m0, s82
	s_nop 0
	global_load_lds_dwordx4 v[204:205], off
	s_waitcnt lgkmcnt(8)
	s_barrier
	s_waitcnt lgkmcnt(0)
	s_waitcnt lgkmcnt(0)
	v_mfma_f32_16x16x32_bf16 v[126:129], v[148:151], v[168:171], v[126:129]
	v_mfma_f32_16x16x32_bf16 v[122:125], v[156:159], v[168:171], v[122:125]
	v_mfma_f32_16x16x32_bf16 v[110:113], v[148:151], v[180:183], v[110:113]
	v_mfma_f32_16x16x32_bf16 v[106:109], v[156:159], v[180:183], v[106:109]
	v_mfma_f32_16x16x32_bf16 v[94:97], v[148:151], v[188:191], v[94:97]
	v_mfma_f32_16x16x32_bf16 v[90:93], v[156:159], v[188:191], v[90:93]
	v_mfma_f32_16x16x32_bf16 v[78:81], v[148:151], v[196:199], v[78:81]
	v_mfma_f32_16x16x32_bf16 v[74:77], v[156:159], v[196:199], v[74:77]
	v_mfma_f32_16x16x32_bf16 v[126:129], v[152:155], v[176:179], v[126:129]
	v_mfma_f32_16x16x32_bf16 v[122:125], v[160:163], v[176:179], v[122:125]
	v_mfma_f32_16x16x32_bf16 v[110:113], v[152:155], v[184:187], v[110:113]
	v_mfma_f32_16x16x32_bf16 v[106:109], v[160:163], v[184:187], v[106:109]
	v_mfma_f32_16x16x32_bf16 v[94:97], v[152:155], v[192:195], v[94:97]
	v_mfma_f32_16x16x32_bf16 v[90:93], v[160:163], v[192:195], v[90:93]
	v_mfma_f32_16x16x32_bf16 v[78:81], v[152:155], v[200:203], v[78:81]
	v_mfma_f32_16x16x32_bf16 v[74:77], v[160:163], v[200:203], v[74:77]
	s_barrier
	s_add_i32 s3, 0, 0x1c000
	s_add_i32 s2, s2, s79
	v_add_u32_e32 v147, s3, v144
	v_lshl_add_u64 v[140:141], v[140:141], 0, s[58:59]
	s_mov_b32 m0, s2
	ds_read_b128 v[204:207], v147
	ds_read_b128 v[208:211], v147 offset:1024
	ds_read_b128 v[212:215], v147 offset:2048
	ds_read_b128 v[216:219], v147 offset:3072
	global_load_lds_dwordx4 v[140:141], off
	v_lshl_add_u64 v[140:141], v[164:165], 0, s[58:59]
	s_add_i32 m0, s2, 0x2000
	s_nop 0
	global_load_lds_dwordx4 v[140:141], off
	s_barrier
	s_waitcnt lgkmcnt(0)
	s_waitcnt lgkmcnt(0)
	v_mfma_f32_16x16x32_bf16 v[118:121], v[204:207], v[168:171], v[118:121]
	v_mfma_f32_16x16x32_bf16 v[114:117], v[212:215], v[168:171], v[114:117]
	v_mfma_f32_16x16x32_bf16 v[102:105], v[204:207], v[180:183], v[102:105]
	v_mfma_f32_16x16x32_bf16 v[98:101], v[212:215], v[180:183], v[98:101]
	v_mfma_f32_16x16x32_bf16 v[86:89], v[204:207], v[188:191], v[86:89]
	v_mfma_f32_16x16x32_bf16 v[82:85], v[212:215], v[188:191], v[82:85]
	v_mfma_f32_16x16x32_bf16 v[70:73], v[204:207], v[196:199], v[70:73]
	v_mfma_f32_16x16x32_bf16 v[66:69], v[212:215], v[196:199], v[66:69]
	v_mfma_f32_16x16x32_bf16 v[118:121], v[208:211], v[176:179], v[118:121]
	v_mfma_f32_16x16x32_bf16 v[114:117], v[216:219], v[176:179], v[114:117]
	v_mfma_f32_16x16x32_bf16 v[102:105], v[208:211], v[184:187], v[102:105]
	v_mfma_f32_16x16x32_bf16 v[98:101], v[216:219], v[184:187], v[98:101]
	v_mfma_f32_16x16x32_bf16 v[86:89], v[208:211], v[192:195], v[86:89]
	v_mfma_f32_16x16x32_bf16 v[82:85], v[216:219], v[192:195], v[82:85]
	v_mfma_f32_16x16x32_bf16 v[70:73], v[208:211], v[200:203], v[70:73]
	v_mfma_f32_16x16x32_bf16 v[66:69], v[216:219], v[200:203], v[66:69]
	s_mov_b32 m0, s83
	v_lshl_add_u64 v[140:141], v[220:221], 0, s[58:59]
	s_barrier
	ds_read_b128 v[168:171], v146 offset:49152
	ds_read_b128 v[176:179], v146 offset:50176
	ds_read_b128 v[180:183], v146 offset:51200
	ds_read_b128 v[184:187], v146 offset:52224
	ds_read_b128 v[188:191], v146 offset:53248
	ds_read_b128 v[192:195], v146 offset:54272
	ds_read_b128 v[196:199], v146 offset:55296
	ds_read_b128 v[200:203], v146 offset:56320
	global_load_lds_dwordx4 v[140:141], off
	v_lshl_add_u64 v[140:141], v[222:223], 0, s[58:59]
	s_mov_b32 m0, s84
	s_nop 0
	global_load_lds_dwordx4 v[140:141], off
	s_barrier
; #define PG8_STAGE(bufoff, gbase, voff) do { _Pragma("unroll") for (int _i = 0; _i < 2; ++_i) \
;         __builtin_amdgcn_global_load_lds((const unsigned*)((const char*)(gbase) + (voff)[_i]), (LAS unsigned*)(lds + (bufoff) + ldsw + _i * 8192), 16, 0, 0); } while (0)
; #define PG8_LDA(dst, b, h) do { _Pragma("unroll") for (int m = 0; m < 4; ++m) _Pragma("unroll") for (int k = 0; k < 2; ++k) dst[m][k] = *(const LAS bf16x8*)(lds + PG8_SA(b, h) + aoff + m * 2048 + k * 1024); } while (0)
; #define PG8_LDB(dst, b, h) do { _Pragma("unroll") for (int n = 0; n < 2; ++n) _Pragma("unroll") for (int k = 0; k < 2; ++k) dst[n][k] = *(const LAS bf16x8*)(lds + PG8_SB(b, h) + boff + n * 2048 + k * 1024); } while (0)
; #define PG8_MMA(ai, bj, At, Bt) do { __builtin_amdgcn_s_setprio(1); _Pragma("unroll") for (int m = 0; m < 4; ++m) _Pragma("unroll") for (int n = 0; n < 2; ++n) _Pragma("unroll") for (int k = 0; k < 2; ++k) \
;         acc[ai][bj][m][n] = __builtin_amdgcn_mfma_f32_16x16x32_bf16(Bt[n][k], At[m][k], acc[ai][bj][m][n], 0, 0, 0); __builtin_amdgcn_s_setprio(0); } while (0)
; #define PG8_WAIT_V(n) asm volatile("s_waitcnt vmcnt(" #n ")" ::: "memory")
; #define PG8_WAIT_L(n) asm volatile("s_waitcnt lgkmcnt(" #n ")" ::: "memory")
; #define PG8_BAR __builtin_amdgcn_s_barrier()
; #define PG8_SCHED __builtin_amdgcn_sched_barrier(0)
; template <class Epi>
; DI void gemm_phase(int wv, LAS unsigned char* lds, const GemmD g, const Epi& E) {
;     ...
;         for (int t = 0; t < nt; t += 2) {
;             const bool last = (t == nt - 2);
;             const char* a1 = cA + (size_t)(t + 1) * kstep;
;             const char* a2 = last ? nA : cA + (size_t)(t + 2) * kstep; const char* b2 = last ? nB : cB + (size_t)(t + 2) * kstep;
;             const char* a3 = a2 + kstep; const char* b3 = b2 + kstep;
;             PG8_LDB(B0, 0, 0); PG8_SCHED; PG8_LDA(At, 0, 0); PG8_STAGE(PG8_SA(1, 1), a1 + hstepA, voffA);
;             PG8_WAIT_L(8); PG8_BAR; PG8_WAIT_L(0); PG8_MMA(0, 0, At, B0); PG8_BAR; PG8_SCHED;
;             PG8_LDB(B1, 0, 1); PG8_STAGE(PG8_SB(0, 0), b2, voffB);
;     ...
;             PG8_BAR; PG8_WAIT_L(0); PG8_MMA(1, 0, At, B0); PG8_BAR; PG8_SCHED;
;             PG8_STAGE(PG8_SB(1, 1), b3 + hstepB, voffB);
;             PG8_WAIT_V(6); PG8_BAR; PG8_MMA(1, 1, At, B1); PG8_BAR;
	s_waitcnt lgkmcnt(0)
	s_waitcnt lgkmcnt(0)
	s_nop 0
	v_mfma_f32_16x16x32_bf16 v[62:65], v[148:151], v[168:171], v[62:65]
	v_mfma_f32_16x16x32_bf16 v[58:61], v[156:159], v[168:171], v[58:61]
	v_mfma_f32_16x16x32_bf16 v[46:49], v[148:151], v[180:183], v[46:49]
	v_mfma_f32_16x16x32_bf16 v[42:45], v[156:159], v[180:183], v[42:45]
	v_mfma_f32_16x16x32_bf16 v[30:33], v[148:151], v[188:191], v[30:33]
	v_mfma_f32_16x16x32_bf16 v[26:29], v[156:159], v[188:191], v[26:29]
	v_mfma_f32_16x16x32_bf16 v[14:17], v[148:151], v[196:199], v[14:17]
	v_mfma_f32_16x16x32_bf16 v[10:13], v[156:159], v[196:199], v[10:13]
	v_mfma_f32_16x16x32_bf16 v[62:65], v[152:155], v[176:179], v[62:65]
	v_mfma_f32_16x16x32_bf16 v[58:61], v[160:163], v[176:179], v[58:61]
	v_mfma_f32_16x16x32_bf16 v[46:49], v[152:155], v[184:187], v[46:49]
	v_mfma_f32_16x16x32_bf16 v[42:45], v[160:163], v[184:187], v[42:45]
	v_mfma_f32_16x16x32_bf16 v[30:33], v[152:155], v[192:195], v[30:33]
	v_mfma_f32_16x16x32_bf16 v[26:29], v[160:163], v[192:195], v[26:29]
	v_mfma_f32_16x16x32_bf16 v[14:17], v[152:155], v[200:203], v[14:17]
	v_mfma_f32_16x16x32_bf16 v[10:13], v[160:163], v[200:203], v[10:13]
	s_barrier
	s_add_u32 s18, s28, 0x40080
	s_addc_u32 s19, s29, 0
	s_add_i32 s2, s3, s79
	v_lshl_add_u64 v[140:141], s[18:19], 0, v[0:1]
	s_mov_b32 m0, s2
	s_nop 0
	global_load_lds_dwordx4 v[140:141], off
	v_lshl_add_u64 v[140:141], s[18:19], 0, v[134:135]
	s_add_i32 m0, s2, 0x2000
	s_nop 0
	global_load_lds_dwordx4 v[140:141], off
	s_waitcnt vmcnt(6)
	s_barrier
	v_mfma_f32_16x16x32_bf16 v[54:57], v[204:207], v[168:171], v[54:57]
	v_mfma_f32_16x16x32_bf16 v[50:53], v[212:215], v[168:171], v[50:53]
	v_mfma_f32_16x16x32_bf16 v[38:41], v[204:207], v[180:183], v[38:41]
	v_mfma_f32_16x16x32_bf16 v[34:37], v[212:215], v[180:183], v[34:37]
	v_mfma_f32_16x16x32_bf16 v[22:25], v[204:207], v[188:191], v[22:25]
	v_mfma_f32_16x16x32_bf16 v[18:21], v[212:215], v[188:191], v[18:21]
	v_mfma_f32_16x16x32_bf16 v[6:9], v[204:207], v[196:199], v[6:9]
	v_mfma_f32_16x16x32_bf16 v[2:5], v[212:215], v[196:199], v[2:5]
	v_mfma_f32_16x16x32_bf16 v[54:57], v[208:211], v[176:179], v[54:57]
	v_mfma_f32_16x16x32_bf16 v[50:53], v[216:219], v[176:179], v[50:53]
	v_mfma_f32_16x16x32_bf16 v[38:41], v[208:211], v[184:187], v[38:41]
	v_mfma_f32_16x16x32_bf16 v[34:37], v[216:219], v[184:187], v[34:37]
	v_mfma_f32_16x16x32_bf16 v[22:25], v[208:211], v[192:195], v[22:25]
	v_mfma_f32_16x16x32_bf16 v[18:21], v[216:219], v[192:195], v[18:21]
	v_mfma_f32_16x16x32_bf16 v[6:9], v[208:211], v[200:203], v[6:9]
	v_mfma_f32_16x16x32_bf16 v[2:5], v[216:219], v[200:203], v[2:5]
	s_add_i32 s41, s41, 2
	s_add_u32 s26, s26, 0x100
	s_addc_u32 s27, s27, 0
	s_add_u32 s36, s36, 0x100
	s_addc_u32 s38, s38, 0
	s_cmp_gt_u32 s41, 13
	s_barrier
	s_cbranch_scc0 .LBB0_490
	s_branch .Lgemm_epi_b
	.p2align 6
.LBB0_490:
	s_add_u32 s2, s26, 0xfffc0080
	s_addc_u32 s3, s27, -1
	s_add_i32 s18, 0, 0x10000
	v_add_u32_e32 v140, s18, v144
	ds_read_b128 v[148:151], v140
	ds_read_b128 v[152:155], v140 offset:1024
	ds_read_b128 v[156:159], v140 offset:2048
	ds_read_b128 v[160:163], v140 offset:3072
	s_cmp_eq_u32 s41, 12
	s_cselect_b32 s31, s7, s3
	s_cselect_b32 s30, s13, s2
	s_cselect_b32 s29, s16, s38
	s_cselect_b32 s28, s17, s36
	v_lshl_add_u64 v[140:141], s[26:27], 0, v[136:137]
	s_add_i32 m0, s25, 0xc000
	ds_read_b128 v[168:171], v146
	ds_read_b128 v[176:179], v146 offset:1024
	ds_read_b128 v[180:183], v146 offset:2048
	ds_read_b128 v[184:187], v146 offset:3072
	ds_read_b128 v[188:191], v146 offset:4096
	ds_read_b128 v[192:195], v146 offset:5120
	ds_read_b128 v[196:199], v146 offset:6144
	ds_read_b128 v[200:203], v146 offset:7168
	global_load_lds_dwordx4 v[140:141], off
	v_lshl_add_u64 v[140:141], s[26:27], 0, v[138:139]
	s_add_i32 m0, s25, 0xe000
	s_nop 0
	global_load_lds_dwordx4 v[140:141], off
	s_waitcnt lgkmcnt(8)
	s_barrier
	s_waitcnt lgkmcnt(0)
	s_waitcnt lgkmcnt(0)
	v_mfma_f32_16x16x32_bf16 v[126:129], v[148:151], v[168:171], v[126:129]
	v_mfma_f32_16x16x32_bf16 v[122:125], v[156:159], v[168:171], v[122:125]
	v_mfma_f32_16x16x32_bf16 v[110:113], v[148:151], v[180:183], v[110:113]
	v_mfma_f32_16x16x32_bf16 v[106:109], v[156:159], v[180:183], v[106:109]
	v_mfma_f32_16x16x32_bf16 v[94:97], v[148:151], v[188:191], v[94:97]
	v_mfma_f32_16x16x32_bf16 v[90:93], v[156:159], v[188:191], v[90:93]
	v_mfma_f32_16x16x32_bf16 v[78:81], v[148:151], v[196:199], v[78:81]
	v_mfma_f32_16x16x32_bf16 v[74:77], v[156:159], v[196:199], v[74:77]
	v_mfma_f32_16x16x32_bf16 v[126:129], v[152:155], v[176:179], v[126:129]
	v_mfma_f32_16x16x32_bf16 v[122:125], v[160:163], v[176:179], v[122:125]
	v_mfma_f32_16x16x32_bf16 v[110:113], v[152:155], v[184:187], v[110:113]
	v_mfma_f32_16x16x32_bf16 v[106:109], v[160:163], v[184:187], v[106:109]
	v_mfma_f32_16x16x32_bf16 v[94:97], v[152:155], v[192:195], v[94:97]
	v_mfma_f32_16x16x32_bf16 v[90:93], v[160:163], v[192:195], v[90:93]
	v_mfma_f32_16x16x32_bf16 v[78:81], v[152:155], v[200:203], v[78:81]
	v_mfma_f32_16x16x32_bf16 v[74:77], v[160:163], v[200:203], v[74:77]
	s_barrier
	s_add_i32 s2, 0, 0x14000
	v_add_u32_e32 v140, s2, v144
	s_add_i32 s3, s18, s79
	ds_read_b128 v[204:207], v140
	ds_read_b128 v[208:211], v140 offset:1024
	ds_read_b128 v[212:215], v140 offset:2048
	ds_read_b128 v[216:219], v140 offset:3072
	v_lshl_add_u64 v[140:141], s[28:29], 0, v[0:1]
	s_mov_b32 m0, s3
	v_lshl_add_u64 v[164:165], s[28:29], 0, v[134:135]
	global_load_lds_dwordx4 v[140:141], off
	s_add_i32 m0, s3, 0x2000
	s_nop 0
	global_load_lds_dwordx4 v[164:165], off
	s_barrier
; #define PG8_STAGE(bufoff, gbase, voff) do { _Pragma("unroll") for (int _i = 0; _i < 2; ++_i) \
;         __builtin_amdgcn_global_load_lds((const unsigned*)((const char*)(gbase) + (voff)[_i]), (LAS unsigned*)(lds + (bufoff) + ldsw + _i * 8192), 16, 0, 0); } while (0)
; #define PG8_LDA(dst, b, h) do { _Pragma("unroll") for (int m = 0; m < 4; ++m) _Pragma("unroll") for (int k = 0; k < 2; ++k) dst[m][k] = *(const LAS bf16x8*)(lds + PG8_SA(b, h) + aoff + m * 2048 + k * 1024); } while (0)
; #define PG8_LDB(dst, b, h) do { _Pragma("unroll") for (int n = 0; n < 2; ++n) _Pragma("unroll") for (int k = 0; k < 2; ++k) dst[n][k] = *(const LAS bf16x8*)(lds + PG8_SB(b, h) + boff + n * 2048 + k * 1024); } while (0)
; #define PG8_MMA(ai, bj, At, Bt) do { __builtin_amdgcn_s_setprio(1); _Pragma("unroll") for (int m = 0; m < 4; ++m) _Pragma("unroll") for (int n = 0; n < 2; ++n) _Pragma("unroll") for (int k = 0; k < 2; ++k) \
;         acc[ai][bj][m][n] = __builtin_amdgcn_mfma_f32_16x16x32_bf16(Bt[n][k], At[m][k], acc[ai][bj][m][n], 0, 0, 0); __builtin_amdgcn_s_setprio(0); } while (0)
; #define PG8_WAIT_V(n) asm volatile("s_waitcnt vmcnt(" #n ")" ::: "memory")
; #define PG8_WAIT_L(n) asm volatile("s_waitcnt lgkmcnt(" #n ")" ::: "memory")
; #define PG8_BAR __builtin_amdgcn_s_barrier()
; #define PG8_SCHED __builtin_amdgcn_sched_barrier(0)
; template <class Epi>
; DI void gemm_phase(int wv, LAS unsigned char* lds, const GemmD g, const Epi& E) {
;     ...
;             PG8_BAR; PG8_WAIT_L(0); PG8_MMA(0, 1, At, B1); PG8_BAR;
;             PG8_LDA(At, 0, 1); PG8_STAGE(PG8_SA(0, 0), a2, voffA);
;             PG8_BAR; PG8_WAIT_L(0); PG8_MMA(1, 0, At, B0); PG8_BAR; PG8_SCHED;
;             PG8_STAGE(PG8_SB(0, 1), b2 + hstepB, voffB);
;             PG8_WAIT_V(6); PG8_BAR; PG8_MMA(1, 1, At, B1); PG8_BAR;
;             PG8_LDB(B0, 1, 0); PG8_SCHED; PG8_LDA(At, 1, 0); PG8_STAGE(PG8_SA(0, 1), a2 + hstepA, voffA);
;             PG8_WAIT_L(8); PG8_BAR; PG8_WAIT_L(0); PG8_MMA(0, 0, At, B0); PG8_BAR; PG8_SCHED;
;             PG8_LDB(B1, 1, 1); PG8_STAGE(PG8_SB(1, 0), b3, voffB);
	s_waitcnt lgkmcnt(0)
	s_waitcnt lgkmcnt(0)
	v_mfma_f32_16x16x32_bf16 v[118:121], v[204:207], v[168:171], v[118:121]
	v_mfma_f32_16x16x32_bf16 v[114:117], v[212:215], v[168:171], v[114:117]
	v_mfma_f32_16x16x32_bf16 v[102:105], v[204:207], v[180:183], v[102:105]
	v_mfma_f32_16x16x32_bf16 v[98:101], v[212:215], v[180:183], v[98:101]
	v_mfma_f32_16x16x32_bf16 v[86:89], v[204:207], v[188:191], v[86:89]
	v_mfma_f32_16x16x32_bf16 v[82:85], v[212:215], v[188:191], v[82:85]
	v_mfma_f32_16x16x32_bf16 v[70:73], v[204:207], v[196:199], v[70:73]
	v_mfma_f32_16x16x32_bf16 v[66:69], v[212:215], v[196:199], v[66:69]
	v_mfma_f32_16x16x32_bf16 v[118:121], v[208:211], v[176:179], v[118:121]
	v_mfma_f32_16x16x32_bf16 v[114:117], v[216:219], v[176:179], v[114:117]
	v_mfma_f32_16x16x32_bf16 v[102:105], v[208:211], v[184:187], v[102:105]
	v_mfma_f32_16x16x32_bf16 v[98:101], v[216:219], v[184:187], v[98:101]
	v_mfma_f32_16x16x32_bf16 v[86:89], v[208:211], v[192:195], v[86:89]
	v_mfma_f32_16x16x32_bf16 v[82:85], v[216:219], v[192:195], v[82:85]
	v_mfma_f32_16x16x32_bf16 v[70:73], v[208:211], v[200:203], v[70:73]
	v_mfma_f32_16x16x32_bf16 v[66:69], v[216:219], v[200:203], v[66:69]
	s_mov_b32 m0, s25
	v_lshl_add_u64 v[220:221], s[30:31], 0, v[130:131]
	s_barrier
	ds_read_b128 v[168:171], v146 offset:16384
	ds_read_b128 v[176:179], v146 offset:17408
	ds_read_b128 v[180:183], v146 offset:18432
	ds_read_b128 v[184:187], v146 offset:19456
	ds_read_b128 v[188:191], v146 offset:20480
	ds_read_b128 v[192:195], v146 offset:21504
	ds_read_b128 v[196:199], v146 offset:22528
	ds_read_b128 v[200:203], v146 offset:23552
	global_load_lds_dwordx4 v[220:221], off
	v_lshl_add_u64 v[222:223], s[30:31], 0, v[132:133]
	s_mov_b32 m0, s80
	s_nop 0
	global_load_lds_dwordx4 v[222:223], off
	s_barrier
	s_waitcnt lgkmcnt(0)
	s_waitcnt lgkmcnt(0)
	s_nop 0
	v_mfma_f32_16x16x32_bf16 v[62:65], v[148:151], v[168:171], v[62:65]
	v_mfma_f32_16x16x32_bf16 v[58:61], v[156:159], v[168:171], v[58:61]
	v_mfma_f32_16x16x32_bf16 v[46:49], v[148:151], v[180:183], v[46:49]
	v_mfma_f32_16x16x32_bf16 v[42:45], v[156:159], v[180:183], v[42:45]
	v_mfma_f32_16x16x32_bf16 v[30:33], v[148:151], v[188:191], v[30:33]
	v_mfma_f32_16x16x32_bf16 v[26:29], v[156:159], v[188:191], v[26:29]
	v_mfma_f32_16x16x32_bf16 v[14:17], v[148:151], v[196:199], v[14:17]
	v_mfma_f32_16x16x32_bf16 v[10:13], v[156:159], v[196:199], v[10:13]
	v_mfma_f32_16x16x32_bf16 v[62:65], v[152:155], v[176:179], v[62:65]
	v_mfma_f32_16x16x32_bf16 v[58:61], v[160:163], v[176:179], v[58:61]
	v_mfma_f32_16x16x32_bf16 v[46:49], v[152:155], v[184:187], v[46:49]
	v_mfma_f32_16x16x32_bf16 v[42:45], v[160:163], v[184:187], v[42:45]
	v_mfma_f32_16x16x32_bf16 v[30:33], v[152:155], v[192:195], v[30:33]
	v_mfma_f32_16x16x32_bf16 v[26:29], v[160:163], v[192:195], v[26:29]
	v_mfma_f32_16x16x32_bf16 v[14:17], v[152:155], v[200:203], v[14:17]
	v_mfma_f32_16x16x32_bf16 v[10:13], v[160:163], v[200:203], v[10:13]
	s_barrier
	s_add_u32 s18, s28, 0x40000
	s_addc_u32 s19, s29, 0
	s_add_i32 s2, s2, s79
	v_lshl_add_u64 v[148:149], s[18:19], 0, v[0:1]
	s_mov_b32 m0, s2
	s_nop 0
	global_load_lds_dwordx4 v[148:149], off
	v_lshl_add_u64 v[148:149], s[18:19], 0, v[134:135]
	s_add_i32 m0, s2, 0x2000
	s_nop 0
	global_load_lds_dwordx4 v[148:149], off
	s_waitcnt vmcnt(6)
	s_barrier
	v_mfma_f32_16x16x32_bf16 v[54:57], v[204:207], v[168:171], v[54:57]
	v_mfma_f32_16x16x32_bf16 v[50:53], v[212:215], v[168:171], v[50:53]
	v_mfma_f32_16x16x32_bf16 v[38:41], v[204:207], v[180:183], v[38:41]
	v_mfma_f32_16x16x32_bf16 v[34:37], v[212:215], v[180:183], v[34:37]
	v_mfma_f32_16x16x32_bf16 v[22:25], v[204:207], v[188:191], v[22:25]
	v_mfma_f32_16x16x32_bf16 v[18:21], v[212:215], v[188:191], v[18:21]
	v_mfma_f32_16x16x32_bf16 v[6:9], v[204:207], v[196:199], v[6:9]
	v_mfma_f32_16x16x32_bf16 v[2:5], v[212:215], v[196:199], v[2:5]
	v_mfma_f32_16x16x32_bf16 v[54:57], v[208:211], v[176:179], v[54:57]
	v_mfma_f32_16x16x32_bf16 v[50:53], v[216:219], v[176:179], v[50:53]
	v_mfma_f32_16x16x32_bf16 v[38:41], v[208:211], v[184:187], v[38:41]
	v_mfma_f32_16x16x32_bf16 v[34:37], v[216:219], v[184:187], v[34:37]
	v_mfma_f32_16x16x32_bf16 v[22:25], v[208:211], v[192:195], v[22:25]
	v_mfma_f32_16x16x32_bf16 v[18:21], v[216:219], v[192:195], v[18:21]
	v_mfma_f32_16x16x32_bf16 v[6:9], v[208:211], v[200:203], v[6:9]
	v_mfma_f32_16x16x32_bf16 v[2:5], v[216:219], v[200:203], v[2:5]
	s_add_i32 s2, 0, 0x18000
	v_add_u32_e32 v147, s2, v144
	s_barrier
	ds_read_b128 v[148:151], v147
	ds_read_b128 v[152:155], v147 offset:1024
	ds_read_b128 v[156:159], v147 offset:2048
	ds_read_b128 v[160:163], v147 offset:3072
	s_add_u32 s18, s30, 0x40000
	s_addc_u32 s19, s31, 0
	s_mov_b32 m0, s81
	v_lshl_add_u64 v[204:205], s[18:19], 0, v[130:131]
	ds_read_b128 v[168:171], v146 offset:32768
	ds_read_b128 v[176:179], v146 offset:33792
	ds_read_b128 v[180:183], v146 offset:34816
	ds_read_b128 v[184:187], v146 offset:35840
	ds_read_b128 v[188:191], v146 offset:36864
	ds_read_b128 v[192:195], v146 offset:37888
	ds_read_b128 v[196:199], v146 offset:38912
	ds_read_b128 v[200:203], v146 offset:39936
	global_load_lds_dwordx4 v[204:205], off
	v_lshl_add_u64 v[204:205], s[18:19], 0, v[132:133]
	s_mov_b32 m0, s82
	s_nop 0
	global_load_lds_dwordx4 v[204:205], off
	s_waitcnt lgkmcnt(8)
	s_barrier
; #define PG8_STAGE(bufoff, gbase, voff) do { _Pragma("unroll") for (int _i = 0; _i < 2; ++_i) \
;         __builtin_amdgcn_global_load_lds((const unsigned*)((const char*)(gbase) + (voff)[_i]), (LAS unsigned*)(lds + (bufoff) + ldsw + _i * 8192), 16, 0, 0); } while (0)
; #define PG8_LDA(dst, b, h) do { _Pragma("unroll") for (int m = 0; m < 4; ++m) _Pragma("unroll") for (int k = 0; k < 2; ++k) dst[m][k] = *(const LAS bf16x8*)(lds + PG8_SA(b, h) + aoff + m * 2048 + k * 1024); } while (0)
; #define PG8_MMA(ai, bj, At, Bt) do { __builtin_amdgcn_s_setprio(1); _Pragma("unroll") for (int m = 0; m < 4; ++m) _Pragma("unroll") for (int n = 0; n < 2; ++n) _Pragma("unroll") for (int k = 0; k < 2; ++k) \
;         acc[ai][bj][m][n] = __builtin_amdgcn_mfma_f32_16x16x32_bf16(Bt[n][k], At[m][k], acc[ai][bj][m][n], 0, 0, 0); __builtin_amdgcn_s_setprio(0); } while (0)
; #define PG8_WAIT_V(n) asm volatile("s_waitcnt vmcnt(" #n ")" ::: "memory")
; #define PG8_WAIT_L(n) asm volatile("s_waitcnt lgkmcnt(" #n ")" ::: "memory")
; #define PG8_BAR __builtin_amdgcn_s_barrier()
; #define PG8_SCHED __builtin_amdgcn_sched_barrier(0)
; template <class Epi>
; DI void gemm_phase(int wv, LAS unsigned char* lds, const GemmD g, const Epi& E) {
;     ...
;             PG8_BAR; PG8_WAIT_L(0); PG8_MMA(0, 1, At, B1); PG8_BAR;
;             PG8_LDA(At, 1, 1); PG8_STAGE(PG8_SA(1, 0), a3, voffA);
;             PG8_BAR; PG8_WAIT_L(0); PG8_MMA(1, 0, At, B0); PG8_BAR; PG8_SCHED;
;             PG8_STAGE(PG8_SB(1, 1), b3 + hstepB, voffB);
;             PG8_WAIT_V(6); PG8_BAR; PG8_MMA(1, 1, At, B1); PG8_BAR;
	s_waitcnt lgkmcnt(0)
	s_waitcnt lgkmcnt(0)
	v_mfma_f32_16x16x32_bf16 v[126:129], v[148:151], v[168:171], v[126:129]
	v_mfma_f32_16x16x32_bf16 v[122:125], v[156:159], v[168:171], v[122:125]
	v_mfma_f32_16x16x32_bf16 v[110:113], v[148:151], v[180:183], v[110:113]
	v_mfma_f32_16x16x32_bf16 v[106:109], v[156:159], v[180:183], v[106:109]
	v_mfma_f32_16x16x32_bf16 v[94:97], v[148:151], v[188:191], v[94:97]
	v_mfma_f32_16x16x32_bf16 v[90:93], v[156:159], v[188:191], v[90:93]
	v_mfma_f32_16x16x32_bf16 v[78:81], v[148:151], v[196:199], v[78:81]
	v_mfma_f32_16x16x32_bf16 v[74:77], v[156:159], v[196:199], v[74:77]
	v_mfma_f32_16x16x32_bf16 v[126:129], v[152:155], v[176:179], v[126:129]
	v_mfma_f32_16x16x32_bf16 v[122:125], v[160:163], v[176:179], v[122:125]
	v_mfma_f32_16x16x32_bf16 v[110:113], v[152:155], v[184:187], v[110:113]
	v_mfma_f32_16x16x32_bf16 v[106:109], v[160:163], v[184:187], v[106:109]
	v_mfma_f32_16x16x32_bf16 v[94:97], v[152:155], v[192:195], v[94:97]
	v_mfma_f32_16x16x32_bf16 v[90:93], v[160:163], v[192:195], v[90:93]
	v_mfma_f32_16x16x32_bf16 v[78:81], v[152:155], v[200:203], v[78:81]
	v_mfma_f32_16x16x32_bf16 v[74:77], v[160:163], v[200:203], v[74:77]
	s_barrier
	s_add_i32 s3, 0, 0x1c000
	s_add_i32 s2, s2, s79
	v_add_u32_e32 v147, s3, v144
	v_lshl_add_u64 v[140:141], v[140:141], 0, s[58:59]
	s_mov_b32 m0, s2
	ds_read_b128 v[204:207], v147
	ds_read_b128 v[208:211], v147 offset:1024
	ds_read_b128 v[212:215], v147 offset:2048
	ds_read_b128 v[216:219], v147 offset:3072
	global_load_lds_dwordx4 v[140:141], off
	v_lshl_add_u64 v[140:141], v[164:165], 0, s[58:59]
	s_add_i32 m0, s2, 0x2000
	s_nop 0
	global_load_lds_dwordx4 v[140:141], off
	s_barrier
	s_waitcnt lgkmcnt(0)
	s_waitcnt lgkmcnt(0)
	v_mfma_f32_16x16x32_bf16 v[118:121], v[204:207], v[168:171], v[118:121]
	v_mfma_f32_16x16x32_bf16 v[114:117], v[212:215], v[168:171], v[114:117]
	v_mfma_f32_16x16x32_bf16 v[102:105], v[204:207], v[180:183], v[102:105]
	v_mfma_f32_16x16x32_bf16 v[98:101], v[212:215], v[180:183], v[98:101]
	v_mfma_f32_16x16x32_bf16 v[86:89], v[204:207], v[188:191], v[86:89]
	v_mfma_f32_16x16x32_bf16 v[82:85], v[212:215], v[188:191], v[82:85]
	v_mfma_f32_16x16x32_bf16 v[70:73], v[204:207], v[196:199], v[70:73]
	v_mfma_f32_16x16x32_bf16 v[66:69], v[212:215], v[196:199], v[66:69]
	v_mfma_f32_16x16x32_bf16 v[118:121], v[208:211], v[176:179], v[118:121]
	v_mfma_f32_16x16x32_bf16 v[114:117], v[216:219], v[176:179], v[114:117]
	v_mfma_f32_16x16x32_bf16 v[102:105], v[208:211], v[184:187], v[102:105]
	v_mfma_f32_16x16x32_bf16 v[98:101], v[216:219], v[184:187], v[98:101]
	v_mfma_f32_16x16x32_bf16 v[86:89], v[208:211], v[192:195], v[86:89]
	v_mfma_f32_16x16x32_bf16 v[82:85], v[216:219], v[192:195], v[82:85]
	v_mfma_f32_16x16x32_bf16 v[70:73], v[208:211], v[200:203], v[70:73]
	v_mfma_f32_16x16x32_bf16 v[66:69], v[216:219], v[200:203], v[66:69]
	s_mov_b32 m0, s83
	v_lshl_add_u64 v[140:141], v[220:221], 0, s[58:59]
	s_barrier
	ds_read_b128 v[168:171], v146 offset:49152
	ds_read_b128 v[176:179], v146 offset:50176
	ds_read_b128 v[180:183], v146 offset:51200
	ds_read_b128 v[184:187], v146 offset:52224
	ds_read_b128 v[188:191], v146 offset:53248
	ds_read_b128 v[192:195], v146 offset:54272
	ds_read_b128 v[196:199], v146 offset:55296
	ds_read_b128 v[200:203], v146 offset:56320
	global_load_lds_dwordx4 v[140:141], off
	v_lshl_add_u64 v[140:141], v[222:223], 0, s[58:59]
	s_mov_b32 m0, s84
	s_nop 0
	global_load_lds_dwordx4 v[140:141], off
	s_barrier
	s_waitcnt lgkmcnt(0)
	s_waitcnt lgkmcnt(0)
	s_nop 0
	v_mfma_f32_16x16x32_bf16 v[62:65], v[148:151], v[168:171], v[62:65]
	v_mfma_f32_16x16x32_bf16 v[58:61], v[156:159], v[168:171], v[58:61]
	v_mfma_f32_16x16x32_bf16 v[46:49], v[148:151], v[180:183], v[46:49]
	v_mfma_f32_16x16x32_bf16 v[42:45], v[156:159], v[180:183], v[42:45]
	v_mfma_f32_16x16x32_bf16 v[30:33], v[148:151], v[188:191], v[30:33]
	v_mfma_f32_16x16x32_bf16 v[26:29], v[156:159], v[188:191], v[26:29]
	v_mfma_f32_16x16x32_bf16 v[14:17], v[148:151], v[196:199], v[14:17]
	v_mfma_f32_16x16x32_bf16 v[10:13], v[156:159], v[196:199], v[10:13]
	v_mfma_f32_16x16x32_bf16 v[62:65], v[152:155], v[176:179], v[62:65]
	v_mfma_f32_16x16x32_bf16 v[58:61], v[160:163], v[176:179], v[58:61]
	v_mfma_f32_16x16x32_bf16 v[46:49], v[152:155], v[184:187], v[46:49]
	v_mfma_f32_16x16x32_bf16 v[42:45], v[160:163], v[184:187], v[42:45]
	v_mfma_f32_16x16x32_bf16 v[30:33], v[152:155], v[192:195], v[30:33]
	v_mfma_f32_16x16x32_bf16 v[26:29], v[160:163], v[192:195], v[26:29]
	v_mfma_f32_16x16x32_bf16 v[14:17], v[152:155], v[200:203], v[14:17]
	v_mfma_f32_16x16x32_bf16 v[10:13], v[160:163], v[200:203], v[10:13]
	s_barrier
	s_add_u32 s18, s28, 0x40080
	s_addc_u32 s19, s29, 0
	s_add_i32 s2, s3, s79
	v_lshl_add_u64 v[140:141], s[18:19], 0, v[0:1]
	s_mov_b32 m0, s2
	s_nop 0
	global_load_lds_dwordx4 v[140:141], off
	v_lshl_add_u64 v[140:141], s[18:19], 0, v[134:135]
	s_add_i32 m0, s2, 0x2000
	s_nop 0
	global_load_lds_dwordx4 v[140:141], off
	s_waitcnt vmcnt(6)
	s_barrier
	v_mfma_f32_16x16x32_bf16 v[54:57], v[204:207], v[168:171], v[54:57]
	v_mfma_f32_16x16x32_bf16 v[50:53], v[212:215], v[168:171], v[50:53]
	v_mfma_f32_16x16x32_bf16 v[38:41], v[204:207], v[180:183], v[38:41]
	v_mfma_f32_16x16x32_bf16 v[34:37], v[212:215], v[180:183], v[34:37]
	v_mfma_f32_16x16x32_bf16 v[22:25], v[204:207], v[188:191], v[22:25]
	v_mfma_f32_16x16x32_bf16 v[18:21], v[212:215], v[188:191], v[18:21]
	v_mfma_f32_16x16x32_bf16 v[6:9], v[204:207], v[196:199], v[6:9]
	v_mfma_f32_16x16x32_bf16 v[2:5], v[212:215], v[196:199], v[2:5]
	v_mfma_f32_16x16x32_bf16 v[54:57], v[208:211], v[176:179], v[54:57]
	v_mfma_f32_16x16x32_bf16 v[50:53], v[216:219], v[176:179], v[50:53]
	v_mfma_f32_16x16x32_bf16 v[38:41], v[208:211], v[184:187], v[38:41]
	v_mfma_f32_16x16x32_bf16 v[34:37], v[216:219], v[184:187], v[34:37]
	v_mfma_f32_16x16x32_bf16 v[22:25], v[208:211], v[192:195], v[22:25]
	v_mfma_f32_16x16x32_bf16 v[18:21], v[216:219], v[192:195], v[18:21]
	v_mfma_f32_16x16x32_bf16 v[6:9], v[208:211], v[200:203], v[6:9]
	v_mfma_f32_16x16x32_bf16 v[2:5], v[216:219], v[200:203], v[2:5]
	s_add_i32 s41, s41, 2
	s_add_u32 s26, s26, 0x100
	s_addc_u32 s27, s27, 0
	s_add_u32 s36, s36, 0x100
	s_addc_u32 s38, s38, 0
	s_cmp_gt_u32 s41, 13
	s_barrier
	s_cbranch_scc0 .LBB0_490

; #define PG8_STAGE(bufoff, gbase, voff) do { _Pragma("unroll") for (int _i = 0; _i < 2; ++_i) \
;         __builtin_amdgcn_global_load_lds((const unsigned*)((const char*)(gbase) + (voff)[_i]), (LAS unsigned*)(lds + (bufoff) + ldsw + _i * 8192), 16, 0, 0); } while (0)
; #define PG8_LDA(dst, b, h) do { _Pragma("unroll") for (int m = 0; m < 4; ++m) _Pragma("unroll") for (int k = 0; k < 2; ++k) dst[m][k] = *(const LAS bf16x8*)(lds + PG8_SA(b, h) + aoff + m * 2048 + k * 1024); } while (0)
; #define PG8_LDB(dst, b, h) do { _Pragma("unroll") for (int n = 0; n < 2; ++n) _Pragma("unroll") for (int k = 0; k < 2; ++k) dst[n][k] = *(const LAS bf16x8*)(lds + PG8_SB(b, h) + boff + n * 2048 + k * 1024); } while (0)
; #define PG8_MMA(ai, bj, At, Bt) do { __builtin_amdgcn_s_setprio(1); _Pragma("unroll") for (int m = 0; m < 4; ++m) _Pragma("unroll") for (int n = 0; n < 2; ++n) _Pragma("unroll") for (int k = 0; k < 2; ++k) \
;         acc[ai][bj][m][n] = __builtin_amdgcn_mfma_f32_16x16x32_bf16(Bt[n][k], At[m][k], acc[ai][bj][m][n], 0, 0, 0); __builtin_amdgcn_s_setprio(0); } while (0)
; #define PG8_WAIT_L(n) asm volatile("s_waitcnt lgkmcnt(" #n ")" ::: "memory")
; template <class Epi>
; DI void gemm_phase(int wv, LAS unsigned char* lds, const GemmD g, const Epi& E) {
;     ...
;         const bool has_next = S.next(ui + 1, nxt);
;         const char* nA = has_next ? (const char*)g.A + (size_t)nxt.pm * 256 * g.lda * 2 : cA; const char* nB = has_next ? (const char*)g.Bt + PG8_BROW(nxt.pn) * (size_t)g.ldb * 2 : cB;
;         for (int t = 0; t < nt; t += 2) {
;             const bool last = (t == nt - 2);
;             const char* a1 = cA + (size_t)(t + 1) * kstep;
;             const char* a2 = last ? nA : cA + (size_t)(t + 2) * kstep; const char* b2 = last ? nB : cB + (size_t)(t + 2) * kstep;
;             const char* a3 = a2 + kstep; const char* b3 = b2 + kstep;
;             PG8_LDB(B0, 0, 0); PG8_SCHED; PG8_LDA(At, 0, 0); PG8_STAGE(PG8_SA(1, 1), a1 + hstepA, voffA);
;             PG8_WAIT_L(8); PG8_BAR; PG8_WAIT_L(0); PG8_MMA(0, 0, At, B0); PG8_BAR; PG8_SCHED;
;             PG8_LDB(B1, 0, 1); PG8_STAGE(PG8_SB(0, 0), b2, voffB);
;             PG8_BAR; PG8_WAIT_L(0); PG8_MMA(0, 1, At, B1); PG8_BAR;
;             PG8_LDA(At, 0, 1); PG8_STAGE(PG8_SA(0, 0), a2, voffA);
;             PG8_BAR; PG8_WAIT_L(0); PG8_MMA(1, 0, At, B0); PG8_BAR; PG8_SCHED;
.LBB0_543:
	s_ashr_i32 s23, s22, 31
	s_lshl_b64 s[18:19], s[22:23], s85
	v_cmp_lt_i64_e32 vcc, s[24:25], v[174:175]
	s_add_u32 s24, s81, s18
	s_addc_u32 s25, s80, s19
	s_and_b64 s[18:19], vcc, exec
	s_cselect_b32 s23, s25, s29
	s_cselect_b32 s68, s24, s28
	s_lshl_b32 s18, s55, 8
	s_ashr_i32 s19, s18, 31
	s_lshl_b64 s[18:19], s[18:19], s9
	s_add_u32 s26, s82, s18
	s_addc_u32 s27, s83, s19
	s_and_b64 s[18:19], vcc, exec
	s_cselect_b32 vcc_lo, s27, s31
	s_cselect_b32 vcc_hi, s26, s30
	s_add_u32 s28, s28, 0x80
	s_addc_u32 s29, s29, 0
	s_add_u32 s37, s30, 0x100
	s_addc_u32 s18, s31, 0
	s_mov_b32 s19, 0
	s_add_i32 s95, s19, 2
	s_add_u32 s2, s28, 0x80
	s_addc_u32 s3, s29, 0
	s_add_i32 s94, 0, 0x10000
	v_add_u32_e32 v145, s94, v141
	ds_read_b128 v[146:149], v145
	ds_read_b128 v[150:153], v145 offset:1024
	ds_read_b128 v[154:157], v145 offset:2048
	ds_read_b128 v[158:161], v145 offset:3072
	s_cmp_eq_u32 s17, s19
	s_cselect_b32 s31, s23, s3
	s_cselect_b32 s30, s68, s2
	s_cselect_b32 s35, vcc_lo, s18
	s_cselect_b32 s34, vcc_hi, s37
	v_lshl_add_u64 v[200:201], s[28:29], 0, v[136:137]
	s_add_i32 m0, s86, 0xc000
	ds_read_b128 v[162:165], v144
	ds_read_b128 v[168:171], v144 offset:1024
	ds_read_b128 v[176:179], v144 offset:2048
	ds_read_b128 v[180:183], v144 offset:3072
	ds_read_b128 v[184:187], v144 offset:4096
	ds_read_b128 v[188:191], v144 offset:5120
	ds_read_b128 v[192:195], v144 offset:6144
	ds_read_b128 v[196:199], v144 offset:7168
	global_load_lds_dwordx4 v[200:201], off
	v_lshl_add_u64 v[200:201], s[28:29], 0, v[138:139]
	s_add_i32 m0, s86, 0xe000
	s_nop 0
	global_load_lds_dwordx4 v[200:201], off
	s_waitcnt lgkmcnt(8)
	s_barrier
	s_waitcnt lgkmcnt(0)
	s_waitcnt lgkmcnt(0)
	v_mfma_f32_16x16x32_bf16 v[126:129], v[146:149], v[162:165], 0
	v_mfma_f32_16x16x32_bf16 v[122:125], v[154:157], v[162:165], 0
	v_mfma_f32_16x16x32_bf16 v[118:121], v[146:149], v[176:179], 0
	v_mfma_f32_16x16x32_bf16 v[114:117], v[154:157], v[176:179], 0
	v_mfma_f32_16x16x32_bf16 v[102:105], v[146:149], v[184:187], 0
	v_mfma_f32_16x16x32_bf16 v[98:101], v[154:157], v[184:187], 0
	v_mfma_f32_16x16x32_bf16 v[86:89], v[146:149], v[192:195], 0
	v_mfma_f32_16x16x32_bf16 v[82:85], v[154:157], v[192:195], 0
	v_mfma_f32_16x16x32_bf16 v[126:129], v[150:153], v[168:171], v[126:129]
	v_mfma_f32_16x16x32_bf16 v[122:125], v[158:161], v[168:171], v[122:125]
	v_mfma_f32_16x16x32_bf16 v[118:121], v[150:153], v[180:183], v[118:121]
	v_mfma_f32_16x16x32_bf16 v[114:117], v[158:161], v[180:183], v[114:117]
	v_mfma_f32_16x16x32_bf16 v[102:105], v[150:153], v[188:191], v[102:105]
	v_mfma_f32_16x16x32_bf16 v[98:101], v[158:161], v[188:191], v[98:101]
	v_mfma_f32_16x16x32_bf16 v[86:89], v[150:153], v[196:199], v[86:89]
	v_mfma_f32_16x16x32_bf16 v[82:85], v[158:161], v[196:199], v[82:85]
	s_barrier
	s_add_i32 s2, 0, 0x14000
	s_add_i32 s3, s94, s84
	v_add_u32_e32 v145, s2, v141
	v_lshl_add_u64 v[216:217], s[34:35], 0, v[0:1]
	s_mov_b32 m0, s3
	ds_read_b128 v[200:203], v145
	ds_read_b128 v[204:207], v145 offset:1024
	ds_read_b128 v[208:211], v145 offset:2048
	ds_read_b128 v[212:215], v145 offset:3072
	global_load_lds_dwordx4 v[216:217], off
	v_lshl_add_u64 v[218:219], s[34:35], 0, v[134:135]
	s_add_i32 m0, s3, 0x2000
	s_nop 0
	global_load_lds_dwordx4 v[218:219], off
	s_barrier
	s_waitcnt lgkmcnt(0)
	s_waitcnt lgkmcnt(0)
	v_mfma_f32_16x16x32_bf16 v[110:113], v[200:203], v[162:165], 0
	v_mfma_f32_16x16x32_bf16 v[106:109], v[208:211], v[162:165], 0
	v_mfma_f32_16x16x32_bf16 v[94:97], v[200:203], v[176:179], 0
	v_mfma_f32_16x16x32_bf16 v[90:93], v[208:211], v[176:179], 0
	v_mfma_f32_16x16x32_bf16 v[78:81], v[200:203], v[184:187], 0
	v_mfma_f32_16x16x32_bf16 v[74:77], v[208:211], v[184:187], 0
	v_mfma_f32_16x16x32_bf16 v[70:73], v[200:203], v[192:195], 0
	v_mfma_f32_16x16x32_bf16 v[66:69], v[208:211], v[192:195], 0
	v_mfma_f32_16x16x32_bf16 v[110:113], v[204:207], v[168:171], v[110:113]
	v_mfma_f32_16x16x32_bf16 v[106:109], v[212:215], v[168:171], v[106:109]
	v_mfma_f32_16x16x32_bf16 v[94:97], v[204:207], v[180:183], v[94:97]
	v_mfma_f32_16x16x32_bf16 v[90:93], v[212:215], v[180:183], v[90:93]
	v_mfma_f32_16x16x32_bf16 v[78:81], v[204:207], v[188:191], v[78:81]
	v_mfma_f32_16x16x32_bf16 v[74:77], v[212:215], v[188:191], v[74:77]
	v_mfma_f32_16x16x32_bf16 v[70:73], v[204:207], v[196:199], v[70:73]
	v_mfma_f32_16x16x32_bf16 v[66:69], v[212:215], v[196:199], v[66:69]
	s_mov_b32 m0, s86
	v_lshl_add_u64 v[220:221], s[30:31], 0, v[130:131]
	s_barrier
	ds_read_b128 v[162:165], v144 offset:16384
	ds_read_b128 v[168:171], v144 offset:17408
	ds_read_b128 v[176:179], v144 offset:18432
	ds_read_b128 v[180:183], v144 offset:19456
	ds_read_b128 v[184:187], v144 offset:20480
	ds_read_b128 v[188:191], v144 offset:21504
	ds_read_b128 v[192:195], v144 offset:22528
	ds_read_b128 v[196:199], v144 offset:23552
	global_load_lds_dwordx4 v[220:221], off
	v_lshl_add_u64 v[222:223], s[30:31], 0, v[132:133]
	s_mov_b32 m0, s87
	s_nop 0
	global_load_lds_dwordx4 v[222:223], off
	s_barrier
	s_waitcnt lgkmcnt(0)
	s_waitcnt lgkmcnt(0)
	s_nop 0
	v_mfma_f32_16x16x32_bf16 v[62:65], v[146:149], v[162:165], 0
	v_mfma_f32_16x16x32_bf16 v[58:61], v[154:157], v[162:165], 0
	v_mfma_f32_16x16x32_bf16 v[54:57], v[146:149], v[176:179], 0
	v_mfma_f32_16x16x32_bf16 v[50:53], v[154:157], v[176:179], 0
	v_mfma_f32_16x16x32_bf16 v[38:41], v[146:149], v[184:187], 0
	v_mfma_f32_16x16x32_bf16 v[34:37], v[154:157], v[184:187], 0
	v_mfma_f32_16x16x32_bf16 v[22:25], v[146:149], v[192:195], 0
	v_mfma_f32_16x16x32_bf16 v[18:21], v[154:157], v[192:195], 0
	v_mfma_f32_16x16x32_bf16 v[62:65], v[150:153], v[168:171], v[62:65]
	v_mfma_f32_16x16x32_bf16 v[58:61], v[158:161], v[168:171], v[58:61]
	v_mfma_f32_16x16x32_bf16 v[54:57], v[150:153], v[180:183], v[54:57]
	v_mfma_f32_16x16x32_bf16 v[50:53], v[158:161], v[180:183], v[50:53]
	v_mfma_f32_16x16x32_bf16 v[38:41], v[150:153], v[188:191], v[38:41]
	v_mfma_f32_16x16x32_bf16 v[34:37], v[158:161], v[188:191], v[34:37]
	v_mfma_f32_16x16x32_bf16 v[22:25], v[150:153], v[196:199], v[22:25]
	v_mfma_f32_16x16x32_bf16 v[18:21], v[158:161], v[196:199], v[18:21]
	s_barrier
; #define PG8_STAGE(bufoff, gbase, voff) do { _Pragma("unroll") for (int _i = 0; _i < 2; ++_i) \
;         __builtin_amdgcn_global_load_lds((const unsigned*)((const char*)(gbase) + (voff)[_i]), (LAS unsigned*)(lds + (bufoff) + ldsw + _i * 8192), 16, 0, 0); } while (0)
; #define PG8_LDA(dst, b, h) do { _Pragma("unroll") for (int m = 0; m < 4; ++m) _Pragma("unroll") for (int k = 0; k < 2; ++k) dst[m][k] = *(const LAS bf16x8*)(lds + PG8_SA(b, h) + aoff + m * 2048 + k * 1024); } while (0)
; #define PG8_LDB(dst, b, h) do { _Pragma("unroll") for (int n = 0; n < 2; ++n) _Pragma("unroll") for (int k = 0; k < 2; ++k) dst[n][k] = *(const LAS bf16x8*)(lds + PG8_SB(b, h) + boff + n * 2048 + k * 1024); } while (0)
; #define PG8_MMA(ai, bj, At, Bt) do { __builtin_amdgcn_s_setprio(1); _Pragma("unroll") for (int m = 0; m < 4; ++m) _Pragma("unroll") for (int n = 0; n < 2; ++n) _Pragma("unroll") for (int k = 0; k < 2; ++k) \
;         acc[ai][bj][m][n] = __builtin_amdgcn_mfma_f32_16x16x32_bf16(Bt[n][k], At[m][k], acc[ai][bj][m][n], 0, 0, 0); __builtin_amdgcn_s_setprio(0); } while (0)
; #define PG8_WAIT_V(n) asm volatile("s_waitcnt vmcnt(" #n ")" ::: "memory")
; #define PG8_WAIT_L(n) asm volatile("s_waitcnt lgkmcnt(" #n ")" ::: "memory")
; #define PG8_BAR __builtin_amdgcn_s_barrier()
; #define PG8_SCHED __builtin_amdgcn_sched_barrier(0)
; template <class Epi>
; DI void gemm_phase(int wv, LAS unsigned char* lds, const GemmD g, const Epi& E) {
;     ...
;             PG8_STAGE(PG8_SB(0, 1), b2 + hstepB, voffB);
;             PG8_WAIT_V(6); PG8_BAR; PG8_MMA(1, 1, At, B1); PG8_BAR;
;             PG8_LDB(B0, 1, 0); PG8_SCHED; PG8_LDA(At, 1, 0); PG8_STAGE(PG8_SA(0, 1), a2 + hstepA, voffA);
;             PG8_WAIT_L(8); PG8_BAR; PG8_WAIT_L(0); PG8_MMA(0, 0, At, B0); PG8_BAR; PG8_SCHED;
;             PG8_LDB(B1, 1, 1); PG8_STAGE(PG8_SB(1, 0), b3, voffB);
;             PG8_BAR; PG8_WAIT_L(0); PG8_MMA(0, 1, At, B1); PG8_BAR;
;             PG8_LDA(At, 1, 1); PG8_STAGE(PG8_SA(1, 0), a3, voffA);
	s_add_u32 s34, s34, s56
	s_addc_u32 s35, s35, 0
	s_add_i32 s2, s2, s84
	v_lshl_add_u64 v[224:225], s[34:35], 0, v[0:1]
	s_mov_b32 m0, s2
	v_lshl_add_u64 v[226:227], s[34:35], 0, v[134:135]
	global_load_lds_dwordx4 v[224:225], off
	s_add_i32 m0, s2, 0x2000
	s_nop 0
	global_load_lds_dwordx4 v[226:227], off
	s_waitcnt vmcnt(6)
	s_barrier
	v_mfma_f32_16x16x32_bf16 v[46:49], v[200:203], v[162:165], 0
	v_mfma_f32_16x16x32_bf16 v[42:45], v[208:211], v[162:165], 0
	v_mfma_f32_16x16x32_bf16 v[30:33], v[200:203], v[176:179], 0
	v_mfma_f32_16x16x32_bf16 v[26:29], v[208:211], v[176:179], 0
	v_mfma_f32_16x16x32_bf16 v[14:17], v[200:203], v[184:187], 0
	v_mfma_f32_16x16x32_bf16 v[10:13], v[208:211], v[184:187], 0
	v_mfma_f32_16x16x32_bf16 v[6:9], v[200:203], v[192:195], 0
	v_mfma_f32_16x16x32_bf16 v[2:5], v[208:211], v[192:195], 0
	v_mfma_f32_16x16x32_bf16 v[46:49], v[204:207], v[168:171], v[46:49]
	v_mfma_f32_16x16x32_bf16 v[42:45], v[212:215], v[168:171], v[42:45]
	v_mfma_f32_16x16x32_bf16 v[30:33], v[204:207], v[180:183], v[30:33]
	v_mfma_f32_16x16x32_bf16 v[26:29], v[212:215], v[180:183], v[26:29]
	v_mfma_f32_16x16x32_bf16 v[14:17], v[204:207], v[188:191], v[14:17]
	v_mfma_f32_16x16x32_bf16 v[10:13], v[212:215], v[188:191], v[10:13]
	v_mfma_f32_16x16x32_bf16 v[6:9], v[204:207], v[196:199], v[6:9]
	v_mfma_f32_16x16x32_bf16 v[2:5], v[212:215], v[196:199], v[2:5]
	s_add_i32 s2, 0, 0x18000
	v_add_u32_e32 v145, s2, v141
	s_barrier
	ds_read_b128 v[146:149], v145
	ds_read_b128 v[150:153], v145 offset:1024
	ds_read_b128 v[154:157], v145 offset:2048
	ds_read_b128 v[158:161], v145 offset:3072
	s_add_u32 s30, s30, s56
	s_addc_u32 s31, s31, 0
	s_mov_b32 m0, s74
	v_lshl_add_u64 v[200:201], s[30:31], 0, v[130:131]
	ds_read_b128 v[162:165], v144 offset:32768
	ds_read_b128 v[168:171], v144 offset:33792
	ds_read_b128 v[176:179], v144 offset:34816
	ds_read_b128 v[180:183], v144 offset:35840
	ds_read_b128 v[184:187], v144 offset:36864
	ds_read_b128 v[188:191], v144 offset:37888
	ds_read_b128 v[192:195], v144 offset:38912
	ds_read_b128 v[196:199], v144 offset:39936
	global_load_lds_dwordx4 v[200:201], off
	v_lshl_add_u64 v[200:201], s[30:31], 0, v[132:133]
	s_mov_b32 m0, s41
	s_nop 0
	global_load_lds_dwordx4 v[200:201], off
	s_waitcnt lgkmcnt(8)
	s_barrier
	s_waitcnt lgkmcnt(0)
	s_waitcnt lgkmcnt(0)
	s_nop 0
	v_mfma_f32_16x16x32_bf16 v[126:129], v[146:149], v[162:165], v[126:129]
	v_mfma_f32_16x16x32_bf16 v[122:125], v[154:157], v[162:165], v[122:125]
	v_mfma_f32_16x16x32_bf16 v[118:121], v[146:149], v[176:179], v[118:121]
	v_mfma_f32_16x16x32_bf16 v[114:117], v[154:157], v[176:179], v[114:117]
	v_mfma_f32_16x16x32_bf16 v[102:105], v[146:149], v[184:187], v[102:105]
	v_mfma_f32_16x16x32_bf16 v[98:101], v[154:157], v[184:187], v[98:101]
	v_mfma_f32_16x16x32_bf16 v[86:89], v[146:149], v[192:195], v[86:89]
	v_mfma_f32_16x16x32_bf16 v[82:85], v[154:157], v[192:195], v[82:85]
	v_mfma_f32_16x16x32_bf16 v[126:129], v[150:153], v[168:171], v[126:129]
	v_mfma_f32_16x16x32_bf16 v[122:125], v[158:161], v[168:171], v[122:125]
	v_mfma_f32_16x16x32_bf16 v[118:121], v[150:153], v[180:183], v[118:121]
	v_mfma_f32_16x16x32_bf16 v[114:117], v[158:161], v[180:183], v[114:117]
	v_mfma_f32_16x16x32_bf16 v[102:105], v[150:153], v[188:191], v[102:105]
	v_mfma_f32_16x16x32_bf16 v[98:101], v[158:161], v[188:191], v[98:101]
	v_mfma_f32_16x16x32_bf16 v[86:89], v[150:153], v[196:199], v[86:89]
	v_mfma_f32_16x16x32_bf16 v[82:85], v[158:161], v[196:199], v[82:85]
	s_barrier
	s_add_i32 s3, 0, 0x1c000
	s_add_i32 s2, s2, s84
	v_add_u32_e32 v145, s3, v141
	v_lshl_add_u64 v[216:217], v[216:217], 0, s[58:59]
	s_mov_b32 m0, s2
	ds_read_b128 v[200:203], v145
	ds_read_b128 v[204:207], v145 offset:1024
	ds_read_b128 v[208:211], v145 offset:2048
	ds_read_b128 v[212:215], v145 offset:3072
	global_load_lds_dwordx4 v[216:217], off
	v_lshl_add_u64 v[216:217], v[218:219], 0, s[58:59]
	s_add_i32 m0, s2, 0x2000
	s_nop 0
	global_load_lds_dwordx4 v[216:217], off
	s_barrier
	s_waitcnt lgkmcnt(0)
	s_waitcnt lgkmcnt(0)
	v_mfma_f32_16x16x32_bf16 v[110:113], v[200:203], v[162:165], v[110:113]
	v_mfma_f32_16x16x32_bf16 v[106:109], v[208:211], v[162:165], v[106:109]
	v_mfma_f32_16x16x32_bf16 v[94:97], v[200:203], v[176:179], v[94:97]
	v_mfma_f32_16x16x32_bf16 v[90:93], v[208:211], v[176:179], v[90:93]
	v_mfma_f32_16x16x32_bf16 v[78:81], v[200:203], v[184:187], v[78:81]
	v_mfma_f32_16x16x32_bf16 v[74:77], v[208:211], v[184:187], v[74:77]
	v_mfma_f32_16x16x32_bf16 v[70:73], v[200:203], v[192:195], v[70:73]
	v_mfma_f32_16x16x32_bf16 v[66:69], v[208:211], v[192:195], v[66:69]
	v_mfma_f32_16x16x32_bf16 v[110:113], v[204:207], v[168:171], v[110:113]
	v_mfma_f32_16x16x32_bf16 v[106:109], v[212:215], v[168:171], v[106:109]
	v_mfma_f32_16x16x32_bf16 v[94:97], v[204:207], v[180:183], v[94:97]
	v_mfma_f32_16x16x32_bf16 v[90:93], v[212:215], v[180:183], v[90:93]
	v_mfma_f32_16x16x32_bf16 v[78:81], v[204:207], v[188:191], v[78:81]
	v_mfma_f32_16x16x32_bf16 v[74:77], v[212:215], v[188:191], v[74:77]
	v_mfma_f32_16x16x32_bf16 v[70:73], v[204:207], v[196:199], v[70:73]
	v_mfma_f32_16x16x32_bf16 v[66:69], v[212:215], v[196:199], v[66:69]
	s_mov_b32 m0, s13
	v_lshl_add_u64 v[216:217], v[220:221], 0, s[58:59]
	s_barrier
	ds_read_b128 v[162:165], v144 offset:49152
	ds_read_b128 v[168:171], v144 offset:50176
	ds_read_b128 v[176:179], v144 offset:51200
	ds_read_b128 v[180:183], v144 offset:52224
	ds_read_b128 v[184:187], v144 offset:53248
	ds_read_b128 v[188:191], v144 offset:54272
	ds_read_b128 v[192:195], v144 offset:55296
	ds_read_b128 v[196:199], v144 offset:56320
	global_load_lds_dwordx4 v[216:217], off
	v_lshl_add_u64 v[216:217], v[222:223], 0, s[58:59]
	s_mov_b32 m0, s16
	s_nop 0
	global_load_lds_dwordx4 v[216:217], off
	s_barrier
; #define PG8_STAGE(bufoff, gbase, voff) do { _Pragma("unroll") for (int _i = 0; _i < 2; ++_i) \
;         __builtin_amdgcn_global_load_lds((const unsigned*)((const char*)(gbase) + (voff)[_i]), (LAS unsigned*)(lds + (bufoff) + ldsw + _i * 8192), 16, 0, 0); } while (0)
; #define PG8_LDA(dst, b, h) do { _Pragma("unroll") for (int m = 0; m < 4; ++m) _Pragma("unroll") for (int k = 0; k < 2; ++k) dst[m][k] = *(const LAS bf16x8*)(lds + PG8_SA(b, h) + aoff + m * 2048 + k * 1024); } while (0)
; #define PG8_LDB(dst, b, h) do { _Pragma("unroll") for (int n = 0; n < 2; ++n) _Pragma("unroll") for (int k = 0; k < 2; ++k) dst[n][k] = *(const LAS bf16x8*)(lds + PG8_SB(b, h) + boff + n * 2048 + k * 1024); } while (0)
; #define PG8_MMA(ai, bj, At, Bt) do { __builtin_amdgcn_s_setprio(1); _Pragma("unroll") for (int m = 0; m < 4; ++m) _Pragma("unroll") for (int n = 0; n < 2; ++n) _Pragma("unroll") for (int k = 0; k < 2; ++k) \
;         acc[ai][bj][m][n] = __builtin_amdgcn_mfma_f32_16x16x32_bf16(Bt[n][k], At[m][k], acc[ai][bj][m][n], 0, 0, 0); __builtin_amdgcn_s_setprio(0); } while (0)
; #define PG8_WAIT_V(n) asm volatile("s_waitcnt vmcnt(" #n ")" ::: "memory")
; #define PG8_WAIT_L(n) asm volatile("s_waitcnt lgkmcnt(" #n ")" ::: "memory")
; #define PG8_BAR __builtin_amdgcn_s_barrier()
; #define PG8_SCHED __builtin_amdgcn_sched_barrier(0)
; template <class Epi>
; DI void gemm_phase(int wv, LAS unsigned char* lds, const GemmD g, const Epi& E) {
;     ...
;         for (int t = 0; t < nt; t += 2) {
;             const bool last = (t == nt - 2);
;             const char* a1 = cA + (size_t)(t + 1) * kstep;
;             const char* a2 = last ? nA : cA + (size_t)(t + 2) * kstep; const char* b2 = last ? nB : cB + (size_t)(t + 2) * kstep;
;             const char* a3 = a2 + kstep; const char* b3 = b2 + kstep;
;             PG8_LDB(B0, 0, 0); PG8_SCHED; PG8_LDA(At, 0, 0); PG8_STAGE(PG8_SA(1, 1), a1 + hstepA, voffA);
;             PG8_WAIT_L(8); PG8_BAR; PG8_WAIT_L(0); PG8_MMA(0, 0, At, B0); PG8_BAR; PG8_SCHED;
;             PG8_LDB(B1, 0, 1); PG8_STAGE(PG8_SB(0, 0), b2, voffB);
;     ...
;             PG8_BAR; PG8_WAIT_L(0); PG8_MMA(1, 0, At, B0); PG8_BAR; PG8_SCHED;
;             PG8_STAGE(PG8_SB(1, 1), b3 + hstepB, voffB);
;             PG8_WAIT_V(6); PG8_BAR; PG8_MMA(1, 1, At, B1); PG8_BAR;
	s_waitcnt lgkmcnt(0)
	s_waitcnt lgkmcnt(0)
	s_nop 0
	v_mfma_f32_16x16x32_bf16 v[62:65], v[146:149], v[162:165], v[62:65]
	v_mfma_f32_16x16x32_bf16 v[58:61], v[154:157], v[162:165], v[58:61]
	v_mfma_f32_16x16x32_bf16 v[54:57], v[146:149], v[176:179], v[54:57]
	v_mfma_f32_16x16x32_bf16 v[50:53], v[154:157], v[176:179], v[50:53]
	v_mfma_f32_16x16x32_bf16 v[38:41], v[146:149], v[184:187], v[38:41]
	v_mfma_f32_16x16x32_bf16 v[34:37], v[154:157], v[184:187], v[34:37]
	v_mfma_f32_16x16x32_bf16 v[22:25], v[146:149], v[192:195], v[22:25]
	v_mfma_f32_16x16x32_bf16 v[18:21], v[154:157], v[192:195], v[18:21]
	v_mfma_f32_16x16x32_bf16 v[62:65], v[150:153], v[168:171], v[62:65]
	v_mfma_f32_16x16x32_bf16 v[58:61], v[158:161], v[168:171], v[58:61]
	v_mfma_f32_16x16x32_bf16 v[54:57], v[150:153], v[180:183], v[54:57]
	v_mfma_f32_16x16x32_bf16 v[50:53], v[158:161], v[180:183], v[50:53]
	v_mfma_f32_16x16x32_bf16 v[38:41], v[150:153], v[188:191], v[38:41]
	v_mfma_f32_16x16x32_bf16 v[34:37], v[158:161], v[188:191], v[34:37]
	v_mfma_f32_16x16x32_bf16 v[22:25], v[150:153], v[196:199], v[22:25]
	v_mfma_f32_16x16x32_bf16 v[18:21], v[158:161], v[196:199], v[18:21]
	s_barrier
	s_add_i32 s2, s3, s84
	v_lshl_add_u64 v[146:147], v[224:225], 0, s[58:59]
	s_mov_b32 m0, s2
	s_nop 0
	global_load_lds_dwordx4 v[146:147], off
	v_lshl_add_u64 v[146:147], v[226:227], 0, s[58:59]
	s_add_i32 m0, s2, 0x2000
	s_nop 0
	global_load_lds_dwordx4 v[146:147], off
	s_waitcnt vmcnt(6)
	s_barrier
	s_nop 0
	v_mfma_f32_16x16x32_bf16 v[46:49], v[200:203], v[162:165], v[46:49]
	v_mfma_f32_16x16x32_bf16 v[42:45], v[208:211], v[162:165], v[42:45]
	v_mfma_f32_16x16x32_bf16 v[30:33], v[200:203], v[176:179], v[30:33]
	v_mfma_f32_16x16x32_bf16 v[26:29], v[208:211], v[176:179], v[26:29]
	v_mfma_f32_16x16x32_bf16 v[14:17], v[200:203], v[184:187], v[14:17]
	v_mfma_f32_16x16x32_bf16 v[10:13], v[208:211], v[184:187], v[10:13]
	v_mfma_f32_16x16x32_bf16 v[6:9], v[200:203], v[192:195], v[6:9]
	v_mfma_f32_16x16x32_bf16 v[2:5], v[208:211], v[192:195], v[2:5]
	v_mfma_f32_16x16x32_bf16 v[46:49], v[204:207], v[168:171], v[46:49]
	v_mfma_f32_16x16x32_bf16 v[42:45], v[212:215], v[168:171], v[42:45]
	v_mfma_f32_16x16x32_bf16 v[30:33], v[204:207], v[180:183], v[30:33]
	v_mfma_f32_16x16x32_bf16 v[26:29], v[212:215], v[180:183], v[26:29]
	v_mfma_f32_16x16x32_bf16 v[14:17], v[204:207], v[188:191], v[14:17]
	v_mfma_f32_16x16x32_bf16 v[10:13], v[212:215], v[188:191], v[10:13]
	v_mfma_f32_16x16x32_bf16 v[6:9], v[204:207], v[196:199], v[6:9]
	v_mfma_f32_16x16x32_bf16 v[2:5], v[212:215], v[196:199], v[2:5]
	s_add_u32 s28, s28, 0x100
	s_addc_u32 s29, s29, 0
	s_add_u32 s37, s37, 0x100
	s_addc_u32 s18, s18, 0
	s_cmp_ge_u32 s95, s38
	s_mov_b32 s19, s95
	s_barrier
	s_cbranch_scc0 .LBB0_544
	s_branch .Lgemm_epi_c
	.p2align 6
.LBB0_544:
	s_add_i32 s95, s19, 2
	s_add_u32 s2, s28, 0x80
	s_addc_u32 s3, s29, 0
	s_add_i32 s94, 0, 0x10000
	v_add_u32_e32 v145, s94, v141
	ds_read_b128 v[146:149], v145
	ds_read_b128 v[150:153], v145 offset:1024
	ds_read_b128 v[154:157], v145 offset:2048
	ds_read_b128 v[158:161], v145 offset:3072
	s_cmp_eq_u32 s17, s19
	s_cselect_b32 s31, s23, s3
	s_cselect_b32 s30, s68, s2
	s_cselect_b32 s35, vcc_lo, s18
	s_cselect_b32 s34, vcc_hi, s37
	v_lshl_add_u64 v[200:201], s[28:29], 0, v[136:137]
	s_add_i32 m0, s86, 0xc000
	ds_read_b128 v[162:165], v144
	ds_read_b128 v[168:171], v144 offset:1024
	ds_read_b128 v[176:179], v144 offset:2048
	ds_read_b128 v[180:183], v144 offset:3072
	ds_read_b128 v[184:187], v144 offset:4096
	ds_read_b128 v[188:191], v144 offset:5120
	ds_read_b128 v[192:195], v144 offset:6144
	ds_read_b128 v[196:199], v144 offset:7168
	global_load_lds_dwordx4 v[200:201], off
	v_lshl_add_u64 v[200:201], s[28:29], 0, v[138:139]
	s_add_i32 m0, s86, 0xe000
	s_nop 0
	global_load_lds_dwordx4 v[200:201], off
	s_waitcnt lgkmcnt(8)
	s_barrier
	s_waitcnt lgkmcnt(0)
	s_waitcnt lgkmcnt(0)
	s_nop 0
	v_mfma_f32_16x16x32_bf16 v[126:129], v[146:149], v[162:165], v[126:129]
	v_mfma_f32_16x16x32_bf16 v[122:125], v[154:157], v[162:165], v[122:125]
	v_mfma_f32_16x16x32_bf16 v[118:121], v[146:149], v[176:179], v[118:121]
	v_mfma_f32_16x16x32_bf16 v[114:117], v[154:157], v[176:179], v[114:117]
	v_mfma_f32_16x16x32_bf16 v[102:105], v[146:149], v[184:187], v[102:105]
	v_mfma_f32_16x16x32_bf16 v[98:101], v[154:157], v[184:187], v[98:101]
	v_mfma_f32_16x16x32_bf16 v[86:89], v[146:149], v[192:195], v[86:89]
	v_mfma_f32_16x16x32_bf16 v[82:85], v[154:157], v[192:195], v[82:85]
	v_mfma_f32_16x16x32_bf16 v[126:129], v[150:153], v[168:171], v[126:129]
	v_mfma_f32_16x16x32_bf16 v[122:125], v[158:161], v[168:171], v[122:125]
	v_mfma_f32_16x16x32_bf16 v[118:121], v[150:153], v[180:183], v[118:121]
	v_mfma_f32_16x16x32_bf16 v[114:117], v[158:161], v[180:183], v[114:117]
	v_mfma_f32_16x16x32_bf16 v[102:105], v[150:153], v[188:191], v[102:105]
	v_mfma_f32_16x16x32_bf16 v[98:101], v[158:161], v[188:191], v[98:101]
	v_mfma_f32_16x16x32_bf16 v[86:89], v[150:153], v[196:199], v[86:89]
	v_mfma_f32_16x16x32_bf16 v[82:85], v[158:161], v[196:199], v[82:85]
	s_barrier
	s_add_i32 s2, 0, 0x14000
	s_add_i32 s3, s94, s84
	v_add_u32_e32 v145, s2, v141
	v_lshl_add_u64 v[216:217], s[34:35], 0, v[0:1]
	s_mov_b32 m0, s3
	ds_read_b128 v[200:203], v145
	ds_read_b128 v[204:207], v145 offset:1024
	ds_read_b128 v[208:211], v145 offset:2048
	ds_read_b128 v[212:215], v145 offset:3072
	global_load_lds_dwordx4 v[216:217], off
	v_lshl_add_u64 v[218:219], s[34:35], 0, v[134:135]
	s_add_i32 m0, s3, 0x2000
	s_nop 0
	global_load_lds_dwordx4 v[218:219], off
	s_barrier
; #define PG8_STAGE(bufoff, gbase, voff) do { _Pragma("unroll") for (int _i = 0; _i < 2; ++_i) \
;         __builtin_amdgcn_global_load_lds((const unsigned*)((const char*)(gbase) + (voff)[_i]), (LAS unsigned*)(lds + (bufoff) + ldsw + _i * 8192), 16, 0, 0); } while (0)
; #define PG8_LDA(dst, b, h) do { _Pragma("unroll") for (int m = 0; m < 4; ++m) _Pragma("unroll") for (int k = 0; k < 2; ++k) dst[m][k] = *(const LAS bf16x8*)(lds + PG8_SA(b, h) + aoff + m * 2048 + k * 1024); } while (0)
; #define PG8_LDB(dst, b, h) do { _Pragma("unroll") for (int n = 0; n < 2; ++n) _Pragma("unroll") for (int k = 0; k < 2; ++k) dst[n][k] = *(const LAS bf16x8*)(lds + PG8_SB(b, h) + boff + n * 2048 + k * 1024); } while (0)
; #define PG8_MMA(ai, bj, At, Bt) do { __builtin_amdgcn_s_setprio(1); _Pragma("unroll") for (int m = 0; m < 4; ++m) _Pragma("unroll") for (int n = 0; n < 2; ++n) _Pragma("unroll") for (int k = 0; k < 2; ++k) \
;         acc[ai][bj][m][n] = __builtin_amdgcn_mfma_f32_16x16x32_bf16(Bt[n][k], At[m][k], acc[ai][bj][m][n], 0, 0, 0); __builtin_amdgcn_s_setprio(0); } while (0)
; #define PG8_WAIT_V(n) asm volatile("s_waitcnt vmcnt(" #n ")" ::: "memory")
; #define PG8_WAIT_L(n) asm volatile("s_waitcnt lgkmcnt(" #n ")" ::: "memory")
; #define PG8_BAR __builtin_amdgcn_s_barrier()
; #define PG8_SCHED __builtin_amdgcn_sched_barrier(0)
; template <class Epi>
; DI void gemm_phase(int wv, LAS unsigned char* lds, const GemmD g, const Epi& E) {
;     ...
;             PG8_BAR; PG8_WAIT_L(0); PG8_MMA(0, 1, At, B1); PG8_BAR;
;             PG8_LDA(At, 0, 1); PG8_STAGE(PG8_SA(0, 0), a2, voffA);
;             PG8_BAR; PG8_WAIT_L(0); PG8_MMA(1, 0, At, B0); PG8_BAR; PG8_SCHED;
;             PG8_STAGE(PG8_SB(0, 1), b2 + hstepB, voffB);
;             PG8_WAIT_V(6); PG8_BAR; PG8_MMA(1, 1, At, B1); PG8_BAR;
;             PG8_LDB(B0, 1, 0); PG8_SCHED; PG8_LDA(At, 1, 0); PG8_STAGE(PG8_SA(0, 1), a2 + hstepA, voffA);
;             PG8_WAIT_L(8); PG8_BAR; PG8_WAIT_L(0); PG8_MMA(0, 0, At, B0); PG8_BAR; PG8_SCHED;
;             PG8_LDB(B1, 1, 1); PG8_STAGE(PG8_SB(1, 0), b3, voffB);
	s_waitcnt lgkmcnt(0)
	s_waitcnt lgkmcnt(0)
	v_mfma_f32_16x16x32_bf16 v[110:113], v[200:203], v[162:165], v[110:113]
	v_mfma_f32_16x16x32_bf16 v[106:109], v[208:211], v[162:165], v[106:109]
	v_mfma_f32_16x16x32_bf16 v[94:97], v[200:203], v[176:179], v[94:97]
	v_mfma_f32_16x16x32_bf16 v[90:93], v[208:211], v[176:179], v[90:93]
	v_mfma_f32_16x16x32_bf16 v[78:81], v[200:203], v[184:187], v[78:81]
	v_mfma_f32_16x16x32_bf16 v[74:77], v[208:211], v[184:187], v[74:77]
	v_mfma_f32_16x16x32_bf16 v[70:73], v[200:203], v[192:195], v[70:73]
	v_mfma_f32_16x16x32_bf16 v[66:69], v[208:211], v[192:195], v[66:69]
	v_mfma_f32_16x16x32_bf16 v[110:113], v[204:207], v[168:171], v[110:113]
	v_mfma_f32_16x16x32_bf16 v[106:109], v[212:215], v[168:171], v[106:109]
	v_mfma_f32_16x16x32_bf16 v[94:97], v[204:207], v[180:183], v[94:97]
	v_mfma_f32_16x16x32_bf16 v[90:93], v[212:215], v[180:183], v[90:93]
	v_mfma_f32_16x16x32_bf16 v[78:81], v[204:207], v[188:191], v[78:81]
	v_mfma_f32_16x16x32_bf16 v[74:77], v[212:215], v[188:191], v[74:77]
	v_mfma_f32_16x16x32_bf16 v[70:73], v[204:207], v[196:199], v[70:73]
	v_mfma_f32_16x16x32_bf16 v[66:69], v[212:215], v[196:199], v[66:69]
	s_mov_b32 m0, s86
	v_lshl_add_u64 v[220:221], s[30:31], 0, v[130:131]
	s_barrier
	ds_read_b128 v[162:165], v144 offset:16384
	ds_read_b128 v[168:171], v144 offset:17408
	ds_read_b128 v[176:179], v144 offset:18432
	ds_read_b128 v[180:183], v144 offset:19456
	ds_read_b128 v[184:187], v144 offset:20480
	ds_read_b128 v[188:191], v144 offset:21504
	ds_read_b128 v[192:195], v144 offset:22528
	ds_read_b128 v[196:199], v144 offset:23552
	global_load_lds_dwordx4 v[220:221], off
	v_lshl_add_u64 v[222:223], s[30:31], 0, v[132:133]
	s_mov_b32 m0, s87
	s_nop 0
	global_load_lds_dwordx4 v[222:223], off
	s_barrier
	s_waitcnt lgkmcnt(0)
	s_waitcnt lgkmcnt(0)
	s_nop 0
	v_mfma_f32_16x16x32_bf16 v[62:65], v[146:149], v[162:165], v[62:65]
	v_mfma_f32_16x16x32_bf16 v[58:61], v[154:157], v[162:165], v[58:61]
	v_mfma_f32_16x16x32_bf16 v[54:57], v[146:149], v[176:179], v[54:57]
	v_mfma_f32_16x16x32_bf16 v[50:53], v[154:157], v[176:179], v[50:53]
	v_mfma_f32_16x16x32_bf16 v[38:41], v[146:149], v[184:187], v[38:41]
	v_mfma_f32_16x16x32_bf16 v[34:37], v[154:157], v[184:187], v[34:37]
	v_mfma_f32_16x16x32_bf16 v[22:25], v[146:149], v[192:195], v[22:25]
	v_mfma_f32_16x16x32_bf16 v[18:21], v[154:157], v[192:195], v[18:21]
	v_mfma_f32_16x16x32_bf16 v[62:65], v[150:153], v[168:171], v[62:65]
	v_mfma_f32_16x16x32_bf16 v[58:61], v[158:161], v[168:171], v[58:61]
	v_mfma_f32_16x16x32_bf16 v[54:57], v[150:153], v[180:183], v[54:57]
	v_mfma_f32_16x16x32_bf16 v[50:53], v[158:161], v[180:183], v[50:53]
	v_mfma_f32_16x16x32_bf16 v[38:41], v[150:153], v[188:191], v[38:41]
	v_mfma_f32_16x16x32_bf16 v[34:37], v[158:161], v[188:191], v[34:37]
	v_mfma_f32_16x16x32_bf16 v[22:25], v[150:153], v[196:199], v[22:25]
	v_mfma_f32_16x16x32_bf16 v[18:21], v[158:161], v[196:199], v[18:21]
	s_barrier
	s_add_u32 s34, s34, s56
	s_addc_u32 s35, s35, 0
	s_add_i32 s2, s2, s84
	v_lshl_add_u64 v[224:225], s[34:35], 0, v[0:1]
	s_mov_b32 m0, s2
	v_lshl_add_u64 v[226:227], s[34:35], 0, v[134:135]
	global_load_lds_dwordx4 v[224:225], off
	s_add_i32 m0, s2, 0x2000
	s_nop 0
	global_load_lds_dwordx4 v[226:227], off
	s_waitcnt vmcnt(6)
	s_barrier
	v_mfma_f32_16x16x32_bf16 v[46:49], v[200:203], v[162:165], v[46:49]
	v_mfma_f32_16x16x32_bf16 v[42:45], v[208:211], v[162:165], v[42:45]
	v_mfma_f32_16x16x32_bf16 v[30:33], v[200:203], v[176:179], v[30:33]
	v_mfma_f32_16x16x32_bf16 v[26:29], v[208:211], v[176:179], v[26:29]
	v_mfma_f32_16x16x32_bf16 v[14:17], v[200:203], v[184:187], v[14:17]
	v_mfma_f32_16x16x32_bf16 v[10:13], v[208:211], v[184:187], v[10:13]
	v_mfma_f32_16x16x32_bf16 v[6:9], v[200:203], v[192:195], v[6:9]
	v_mfma_f32_16x16x32_bf16 v[2:5], v[208:211], v[192:195], v[2:5]
	v_mfma_f32_16x16x32_bf16 v[46:49], v[204:207], v[168:171], v[46:49]
	v_mfma_f32_16x16x32_bf16 v[42:45], v[212:215], v[168:171], v[42:45]
	v_mfma_f32_16x16x32_bf16 v[30:33], v[204:207], v[180:183], v[30:33]
	v_mfma_f32_16x16x32_bf16 v[26:29], v[212:215], v[180:183], v[26:29]
	v_mfma_f32_16x16x32_bf16 v[14:17], v[204:207], v[188:191], v[14:17]
	v_mfma_f32_16x16x32_bf16 v[10:13], v[212:215], v[188:191], v[10:13]
	v_mfma_f32_16x16x32_bf16 v[6:9], v[204:207], v[196:199], v[6:9]
	v_mfma_f32_16x16x32_bf16 v[2:5], v[212:215], v[196:199], v[2:5]
	s_add_i32 s2, 0, 0x18000
	v_add_u32_e32 v145, s2, v141
	s_barrier
	ds_read_b128 v[146:149], v145
	ds_read_b128 v[150:153], v145 offset:1024
	ds_read_b128 v[154:157], v145 offset:2048
	ds_read_b128 v[158:161], v145 offset:3072
	s_add_u32 s30, s30, s56
	s_addc_u32 s31, s31, 0
	s_mov_b32 m0, s74
	v_lshl_add_u64 v[200:201], s[30:31], 0, v[130:131]
	ds_read_b128 v[162:165], v144 offset:32768
	ds_read_b128 v[168:171], v144 offset:33792
	ds_read_b128 v[176:179], v144 offset:34816
	ds_read_b128 v[180:183], v144 offset:35840
	ds_read_b128 v[184:187], v144 offset:36864
	ds_read_b128 v[188:191], v144 offset:37888
	ds_read_b128 v[192:195], v144 offset:38912
	ds_read_b128 v[196:199], v144 offset:39936
	global_load_lds_dwordx4 v[200:201], off
	v_lshl_add_u64 v[200:201], s[30:31], 0, v[132:133]
	s_mov_b32 m0, s41
	s_nop 0
	global_load_lds_dwordx4 v[200:201], off
	s_waitcnt lgkmcnt(8)
	s_barrier
; #define PG8_STAGE(bufoff, gbase, voff) do { _Pragma("unroll") for (int _i = 0; _i < 2; ++_i) \
;         __builtin_amdgcn_global_load_lds((const unsigned*)((const char*)(gbase) + (voff)[_i]), (LAS unsigned*)(lds + (bufoff) + ldsw + _i * 8192), 16, 0, 0); } while (0)
; #define PG8_LDA(dst, b, h) do { _Pragma("unroll") for (int m = 0; m < 4; ++m) _Pragma("unroll") for (int k = 0; k < 2; ++k) dst[m][k] = *(const LAS bf16x8*)(lds + PG8_SA(b, h) + aoff + m * 2048 + k * 1024); } while (0)
; #define PG8_LDB(dst, b, h) do { _Pragma("unroll") for (int n = 0; n < 2; ++n) _Pragma("unroll") for (int k = 0; k < 2; ++k) dst[n][k] = *(const LAS bf16x8*)(lds + PG8_SB(b, h) + boff + n * 2048 + k * 1024); } while (0)
; #define PG8_MMA(ai, bj, At, Bt) do { __builtin_amdgcn_s_setprio(1); _Pragma("unroll") for (int m = 0; m < 4; ++m) _Pragma("unroll") for (int n = 0; n < 2; ++n) _Pragma("unroll") for (int k = 0; k < 2; ++k) \
;         acc[ai][bj][m][n] = __builtin_amdgcn_mfma_f32_16x16x32_bf16(Bt[n][k], At[m][k], acc[ai][bj][m][n], 0, 0, 0); __builtin_amdgcn_s_setprio(0); } while (0)
; #define PG8_WAIT_V(n) asm volatile("s_waitcnt vmcnt(" #n ")" ::: "memory")
; #define PG8_WAIT_L(n) asm volatile("s_waitcnt lgkmcnt(" #n ")" ::: "memory")
; #define PG8_BAR __builtin_amdgcn_s_barrier()
; #define PG8_SCHED __builtin_amdgcn_sched_barrier(0)
; template <class Epi>
; DI void gemm_phase(int wv, LAS unsigned char* lds, const GemmD g, const Epi& E) {
;     ...
;             PG8_WAIT_L(8); PG8_BAR; PG8_WAIT_L(0); PG8_MMA(0, 0, At, B0); PG8_BAR; PG8_SCHED;
;             PG8_LDB(B1, 1, 1); PG8_STAGE(PG8_SB(1, 0), b3, voffB);
;             PG8_BAR; PG8_WAIT_L(0); PG8_MMA(0, 1, At, B1); PG8_BAR;
;             PG8_LDA(At, 1, 1); PG8_STAGE(PG8_SA(1, 0), a3, voffA);
;             PG8_BAR; PG8_WAIT_L(0); PG8_MMA(1, 0, At, B0); PG8_BAR; PG8_SCHED;
;             PG8_STAGE(PG8_SB(1, 1), b3 + hstepB, voffB);
;             PG8_WAIT_V(6); PG8_BAR; PG8_MMA(1, 1, At, B1); PG8_BAR;
;         }
	s_waitcnt lgkmcnt(0)
	s_waitcnt lgkmcnt(0)
	s_nop 0
	v_mfma_f32_16x16x32_bf16 v[126:129], v[146:149], v[162:165], v[126:129]
	v_mfma_f32_16x16x32_bf16 v[122:125], v[154:157], v[162:165], v[122:125]
	v_mfma_f32_16x16x32_bf16 v[118:121], v[146:149], v[176:179], v[118:121]
	v_mfma_f32_16x16x32_bf16 v[114:117], v[154:157], v[176:179], v[114:117]
	v_mfma_f32_16x16x32_bf16 v[102:105], v[146:149], v[184:187], v[102:105]
	v_mfma_f32_16x16x32_bf16 v[98:101], v[154:157], v[184:187], v[98:101]
	v_mfma_f32_16x16x32_bf16 v[86:89], v[146:149], v[192:195], v[86:89]
	v_mfma_f32_16x16x32_bf16 v[82:85], v[154:157], v[192:195], v[82:85]
	v_mfma_f32_16x16x32_bf16 v[126:129], v[150:153], v[168:171], v[126:129]
	v_mfma_f32_16x16x32_bf16 v[122:125], v[158:161], v[168:171], v[122:125]
	v_mfma_f32_16x16x32_bf16 v[118:121], v[150:153], v[180:183], v[118:121]
	v_mfma_f32_16x16x32_bf16 v[114:117], v[158:161], v[180:183], v[114:117]
	v_mfma_f32_16x16x32_bf16 v[102:105], v[150:153], v[188:191], v[102:105]
	v_mfma_f32_16x16x32_bf16 v[98:101], v[158:161], v[188:191], v[98:101]
	v_mfma_f32_16x16x32_bf16 v[86:89], v[150:153], v[196:199], v[86:89]
	v_mfma_f32_16x16x32_bf16 v[82:85], v[158:161], v[196:199], v[82:85]
	s_barrier
	s_add_i32 s3, 0, 0x1c000
	s_add_i32 s2, s2, s84
	v_add_u32_e32 v145, s3, v141
	v_lshl_add_u64 v[216:217], v[216:217], 0, s[58:59]
	s_mov_b32 m0, s2
	ds_read_b128 v[200:203], v145
	ds_read_b128 v[204:207], v145 offset:1024
	ds_read_b128 v[208:211], v145 offset:2048
	ds_read_b128 v[212:215], v145 offset:3072
	global_load_lds_dwordx4 v[216:217], off
	v_lshl_add_u64 v[216:217], v[218:219], 0, s[58:59]
	s_add_i32 m0, s2, 0x2000
	s_nop 0
	global_load_lds_dwordx4 v[216:217], off
	s_barrier
	s_waitcnt lgkmcnt(0)
	s_waitcnt lgkmcnt(0)
	v_mfma_f32_16x16x32_bf16 v[110:113], v[200:203], v[162:165], v[110:113]
	v_mfma_f32_16x16x32_bf16 v[106:109], v[208:211], v[162:165], v[106:109]
	v_mfma_f32_16x16x32_bf16 v[94:97], v[200:203], v[176:179], v[94:97]
	v_mfma_f32_16x16x32_bf16 v[90:93], v[208:211], v[176:179], v[90:93]
	v_mfma_f32_16x16x32_bf16 v[78:81], v[200:203], v[184:187], v[78:81]
	v_mfma_f32_16x16x32_bf16 v[74:77], v[208:211], v[184:187], v[74:77]
	v_mfma_f32_16x16x32_bf16 v[70:73], v[200:203], v[192:195], v[70:73]
	v_mfma_f32_16x16x32_bf16 v[66:69], v[208:211], v[192:195], v[66:69]
	v_mfma_f32_16x16x32_bf16 v[110:113], v[204:207], v[168:171], v[110:113]
	v_mfma_f32_16x16x32_bf16 v[106:109], v[212:215], v[168:171], v[106:109]
	v_mfma_f32_16x16x32_bf16 v[94:97], v[204:207], v[180:183], v[94:97]
	v_mfma_f32_16x16x32_bf16 v[90:93], v[212:215], v[180:183], v[90:93]
	v_mfma_f32_16x16x32_bf16 v[78:81], v[204:207], v[188:191], v[78:81]
	v_mfma_f32_16x16x32_bf16 v[74:77], v[212:215], v[188:191], v[74:77]
	v_mfma_f32_16x16x32_bf16 v[70:73], v[204:207], v[196:199], v[70:73]
	v_mfma_f32_16x16x32_bf16 v[66:69], v[212:215], v[196:199], v[66:69]
	s_mov_b32 m0, s13
	v_lshl_add_u64 v[216:217], v[220:221], 0, s[58:59]
	s_barrier
	ds_read_b128 v[162:165], v144 offset:49152
	ds_read_b128 v[168:171], v144 offset:50176
	ds_read_b128 v[176:179], v144 offset:51200
	ds_read_b128 v[180:183], v144 offset:52224
	ds_read_b128 v[184:187], v144 offset:53248
	ds_read_b128 v[188:191], v144 offset:54272
	ds_read_b128 v[192:195], v144 offset:55296
	ds_read_b128 v[196:199], v144 offset:56320
	global_load_lds_dwordx4 v[216:217], off
	v_lshl_add_u64 v[216:217], v[222:223], 0, s[58:59]
	s_mov_b32 m0, s16
	s_nop 0
	global_load_lds_dwordx4 v[216:217], off
	s_barrier
	s_waitcnt lgkmcnt(0)
	s_waitcnt lgkmcnt(0)
	s_nop 0
	v_mfma_f32_16x16x32_bf16 v[62:65], v[146:149], v[162:165], v[62:65]
	v_mfma_f32_16x16x32_bf16 v[58:61], v[154:157], v[162:165], v[58:61]
	v_mfma_f32_16x16x32_bf16 v[54:57], v[146:149], v[176:179], v[54:57]
	v_mfma_f32_16x16x32_bf16 v[50:53], v[154:157], v[176:179], v[50:53]
	v_mfma_f32_16x16x32_bf16 v[38:41], v[146:149], v[184:187], v[38:41]
	v_mfma_f32_16x16x32_bf16 v[34:37], v[154:157], v[184:187], v[34:37]
	v_mfma_f32_16x16x32_bf16 v[22:25], v[146:149], v[192:195], v[22:25]
	v_mfma_f32_16x16x32_bf16 v[18:21], v[154:157], v[192:195], v[18:21]
	v_mfma_f32_16x16x32_bf16 v[62:65], v[150:153], v[168:171], v[62:65]
	v_mfma_f32_16x16x32_bf16 v[58:61], v[158:161], v[168:171], v[58:61]
	v_mfma_f32_16x16x32_bf16 v[54:57], v[150:153], v[180:183], v[54:57]
	v_mfma_f32_16x16x32_bf16 v[50:53], v[158:161], v[180:183], v[50:53]
	v_mfma_f32_16x16x32_bf16 v[38:41], v[150:153], v[188:191], v[38:41]
	v_mfma_f32_16x16x32_bf16 v[34:37], v[158:161], v[188:191], v[34:37]
	v_mfma_f32_16x16x32_bf16 v[22:25], v[150:153], v[196:199], v[22:25]
	v_mfma_f32_16x16x32_bf16 v[18:21], v[158:161], v[196:199], v[18:21]
	s_barrier
	s_add_i32 s2, s3, s84
	v_lshl_add_u64 v[146:147], v[224:225], 0, s[58:59]
	s_mov_b32 m0, s2
	s_nop 0
	global_load_lds_dwordx4 v[146:147], off
	v_lshl_add_u64 v[146:147], v[226:227], 0, s[58:59]
	s_add_i32 m0, s2, 0x2000
	s_nop 0
	global_load_lds_dwordx4 v[146:147], off
	s_waitcnt vmcnt(6)
	s_barrier
	s_nop 0
	v_mfma_f32_16x16x32_bf16 v[46:49], v[200:203], v[162:165], v[46:49]
	v_mfma_f32_16x16x32_bf16 v[42:45], v[208:211], v[162:165], v[42:45]
	v_mfma_f32_16x16x32_bf16 v[30:33], v[200:203], v[176:179], v[30:33]
	v_mfma_f32_16x16x32_bf16 v[26:29], v[208:211], v[176:179], v[26:29]
	v_mfma_f32_16x16x32_bf16 v[14:17], v[200:203], v[184:187], v[14:17]
	v_mfma_f32_16x16x32_bf16 v[10:13], v[208:211], v[184:187], v[10:13]
	v_mfma_f32_16x16x32_bf16 v[6:9], v[200:203], v[192:195], v[6:9]
	v_mfma_f32_16x16x32_bf16 v[2:5], v[208:211], v[192:195], v[2:5]
	v_mfma_f32_16x16x32_bf16 v[46:49], v[204:207], v[168:171], v[46:49]
	v_mfma_f32_16x16x32_bf16 v[42:45], v[212:215], v[168:171], v[42:45]
	v_mfma_f32_16x16x32_bf16 v[30:33], v[204:207], v[180:183], v[30:33]
	v_mfma_f32_16x16x32_bf16 v[26:29], v[212:215], v[180:183], v[26:29]
	v_mfma_f32_16x16x32_bf16 v[14:17], v[204:207], v[188:191], v[14:17]
	v_mfma_f32_16x16x32_bf16 v[10:13], v[212:215], v[188:191], v[10:13]
	v_mfma_f32_16x16x32_bf16 v[6:9], v[204:207], v[196:199], v[6:9]
	v_mfma_f32_16x16x32_bf16 v[2:5], v[212:215], v[196:199], v[2:5]
	s_add_u32 s28, s28, 0x100
	s_addc_u32 s29, s29, 0
	s_add_u32 s37, s37, 0x100
	s_addc_u32 s18, s18, 0
	s_cmp_ge_u32 s95, s38
	s_mov_b32 s19, s95
	s_barrier
	s_cbranch_scc0 .LBB0_544
